# select-phase load ring + candidate sort network; PEER-q epilogue row-scale loads gathered up front through one ring
# speedup vs baseline: 1.1353x; 1.0039x over previous
; #define MFMA32(a, b, c) __builtin_amdgcn_mfma_f32_32x32x16_bf16((a), (b), (c), 0, 0, 0)
; DI int crow(int r, int hi) { return (r & 3) + 8 * (r >> 2) + 4 * hi; }
; DI unsigned ordf(float f) { const unsigned u = __builtin_bit_cast(unsigned, f); return (u & 0x80000000u) ? ~u : (u | 0x80000000u); }
; DI void peer_half_topk(const bf16_t* qrow  , const bf16_t* subk  , int hi, int lane, LAS unsigned* ltop) {
;     ...
;     for (int rt = 0; rt < 4; ++rt) {
;         f32x16 acc;
; #pragma unroll
;         for (int r = 0; r < 16; ++r) acc[r] = 0.f;
; #pragma unroll
;         for (int kk = 0; kk < 8; ++kk) {
;             const bf16x8 af = *(const bf16x8*)(subk + (size_t)(rt * 32) * 128 + kk * 16);
;             const bf16x8 bf = *(const bf16x8*)(qrow + kk * 16);
;             acc = MFMA32(af, bf, acc);
;         }
; #pragma unroll
;         for (int r = 0; r < 16; ++r) { const int n = rt * 32 + crow(r, hi); keys[rt * 16 + r] = (ordf(acc[r]) & ~0x7Fu) | (unsigned)(127 - n); }
;     }
.LBB0_40:
	v_ashrrev_i32_e32 v49, 31, v48
	v_lshlrev_b64 v[126:127], 2, v[48:49]
	v_or_b32_e32 v126, v126, v50
	v_mov_b64_e32 v[188:189], v[54:55]
	v_lshlrev_b64 v[0:1], 12, v[126:127]
	v_lshl_add_u64 v[140:141], v[52:53], 0, v[0:1]
	s_mov_b32 s8, 0
	global_load_dwordx4 v[220:223], v[188:189], off
	global_load_dwordx4 v[44:47], v[140:141], off
	global_load_dwordx4 v[236:239], v[188:189], off offset:32
	global_load_dwordx4 v[40:43], v[140:141], off offset:32
	global_load_dwordx4 v[248:251], v[188:189], off offset:64
	global_load_dwordx4 v[36:39], v[140:141], off offset:64
	global_load_dwordx4 v[180:183], v[188:189], off offset:96
	global_load_dwordx4 v[32:35], v[140:141], off offset:96
	s_waitcnt vmcnt(6)
	v_mfma_f32_32x32x16_bf16 v[0:15], v[220:223], v[44:47], 0
	global_load_dwordx4 v[220:223], v[188:189], off offset:128
	global_load_dwordx4 v[28:31], v[140:141], off offset:128
	s_waitcnt vmcnt(6)
	v_mfma_f32_32x32x16_bf16 v[0:15], v[236:239], v[40:43], v[0:15]
	global_load_dwordx4 v[236:239], v[188:189], off offset:160
	global_load_dwordx4 v[24:27], v[140:141], off offset:160
	s_waitcnt vmcnt(6)
	v_mfma_f32_32x32x16_bf16 v[0:15], v[248:251], v[36:39], v[0:15]
	global_load_dwordx4 v[248:251], v[188:189], off offset:192
	global_load_dwordx4 v[20:23], v[140:141], off offset:192
	s_waitcnt vmcnt(6)
	v_mfma_f32_32x32x16_bf16 v[0:15], v[180:183], v[32:35], v[0:15]
	global_load_dwordx4 v[180:183], v[188:189], off offset:224
	global_load_dwordx4 v[16:19], v[140:141], off offset:224
	s_waitcnt vmcnt(6)
	v_mfma_f32_32x32x16_bf16 v[0:15], v[220:223], v[28:31], v[0:15]
	s_waitcnt vmcnt(4)
	v_mfma_f32_32x32x16_bf16 v[0:15], v[236:239], v[24:27], v[0:15]
	s_waitcnt vmcnt(2)
	v_mfma_f32_32x32x16_bf16 v[0:15], v[248:251], v[20:23], v[0:15]
	s_waitcnt vmcnt(0)
	v_mfma_f32_32x32x16_bf16 v[0:15], v[180:183], v[16:19], v[0:15]
	s_nop 11
	v_and_b32_e32 v143, 0x7fffffff, v1
	v_and_b32_e32 v142, 0x7fffffff, v0
	v_xor_b32_e32 v49, -1, v1
	v_xor_b32_e32 v119, -1, v0
	v_pk_add_f32 v[142:143], v[142:143], 0 neg_lo:[1,1] neg_hi:[1,1]
	v_cmp_gt_i32_e32 vcc, 0, v0
	v_cmp_gt_i32_e64 s[0:1], 0, v1
	v_xor_b32_e32 v131, -1, v2
	v_cndmask_b32_e32 v1, v142, v119, vcc
	v_cndmask_b32_e64 v0, v143, v49, s[0:1]
	v_and_b32_e32 v0, 0xffffff80, v0
	v_and_b32_e32 v1, 0xffffff80, v1
	v_add_u32_e32 v49, v0, v51
	v_add_u32_e32 v128, v1, v56
	v_and_b32_e32 v1, 0x7fffffff, v3
	v_and_b32_e32 v0, 0x7fffffff, v2
	v_xor_b32_e32 v119, -1, v3
	v_pk_add_f32 v[0:1], v[0:1], 0 neg_lo:[1,1] neg_hi:[1,1]
	v_cmp_gt_i32_e32 vcc, 0, v2
	v_cmp_gt_i32_e64 s[0:1], 0, v3
	v_xor_b32_e32 v2, -1, v5
	v_cndmask_b32_e32 v0, v0, v131, vcc
	v_cndmask_b32_e64 v1, v1, v119, s[0:1]
	v_and_b32_e32 v1, 0xffffff80, v1
	v_and_b32_e32 v0, 0xffffff80, v0
	v_add_u32_e32 v119, v1, v57
	v_add_u32_e32 v142, v0, v58
	v_and_b32_e32 v1, 0x7fffffff, v5
	v_and_b32_e32 v0, 0x7fffffff, v4
	v_xor_b32_e32 v3, -1, v4
	v_pk_add_f32 v[0:1], v[0:1], 0 neg_lo:[1,1] neg_hi:[1,1]
	v_cmp_gt_i32_e32 vcc, 0, v4
	v_cmp_gt_i32_e64 s[0:1], 0, v5
	s_nop 0
	v_cndmask_b32_e32 v0, v0, v3, vcc
	v_cndmask_b32_e64 v1, v1, v2, s[0:1]
	v_and_b32_e32 v1, 0xffffff80, v1
	v_and_b32_e32 v0, 0xffffff80, v0
	v_add_u32_e32 v131, v1, v59
	v_add_u32_e32 v144, v0, v60
	v_and_b32_e32 v1, 0x7fffffff, v7
	v_and_b32_e32 v0, 0x7fffffff, v6
	v_xor_b32_e32 v2, -1, v7
	v_xor_b32_e32 v3, -1, v6
	v_pk_add_f32 v[0:1], v[0:1], 0 neg_lo:[1,1] neg_hi:[1,1]
	v_cmp_gt_i32_e32 vcc, 0, v6
	v_cmp_gt_i32_e64 s[0:1], 0, v7
	s_nop 0
	v_cndmask_b32_e32 v0, v0, v3, vcc
	v_cndmask_b32_e64 v1, v1, v2, s[0:1]
	v_and_b32_e32 v1, 0xffffff80, v1
	v_and_b32_e32 v0, 0xffffff80, v0
	v_add_u32_e32 v143, v1, v61
	v_add_u32_e32 v146, v0, v62
	v_and_b32_e32 v1, 0x7fffffff, v9
	v_and_b32_e32 v0, 0x7fffffff, v8
	v_xor_b32_e32 v2, -1, v9
	v_xor_b32_e32 v3, -1, v8
	v_pk_add_f32 v[0:1], v[0:1], 0 neg_lo:[1,1] neg_hi:[1,1]
	v_cmp_gt_i32_e32 vcc, 0, v8
	v_cmp_gt_i32_e64 s[0:1], 0, v9
	s_nop 0
	v_cndmask_b32_e32 v0, v0, v3, vcc
	v_cndmask_b32_e64 v1, v1, v2, s[0:1]
	v_and_b32_e32 v1, 0xffffff80, v1
	v_and_b32_e32 v0, 0xffffff80, v0
	v_add_u32_e32 v145, v1, v63
	v_add_u32_e32 v148, v0, v64
	v_and_b32_e32 v1, 0x7fffffff, v11
	v_and_b32_e32 v0, 0x7fffffff, v10
	v_xor_b32_e32 v2, -1, v11
	v_xor_b32_e32 v3, -1, v10
	v_pk_add_f32 v[0:1], v[0:1], 0 neg_lo:[1,1] neg_hi:[1,1]
	v_cmp_gt_i32_e32 vcc, 0, v10
	v_cmp_gt_i32_e64 s[0:1], 0, v11
	s_nop 0
	v_cndmask_b32_e32 v0, v0, v3, vcc
	v_cndmask_b32_e64 v1, v1, v2, s[0:1]
	v_and_b32_e32 v1, 0xffffff80, v1
	v_and_b32_e32 v0, 0xffffff80, v0
	v_add_u32_e32 v147, v1, v65
	v_add_u32_e32 v150, v0, v66
	v_and_b32_e32 v1, 0x7fffffff, v13
	v_and_b32_e32 v0, 0x7fffffff, v12
	v_xor_b32_e32 v2, -1, v13
	v_xor_b32_e32 v3, -1, v12
	v_pk_add_f32 v[0:1], v[0:1], 0 neg_lo:[1,1] neg_hi:[1,1]
	v_cmp_gt_i32_e32 vcc, 0, v12
	v_cmp_gt_i32_e64 s[0:1], 0, v13
	s_nop 0
	v_cndmask_b32_e32 v0, v0, v3, vcc
	v_cndmask_b32_e64 v1, v1, v2, s[0:1]
	v_and_b32_e32 v1, 0xffffff80, v1
	v_and_b32_e32 v0, 0xffffff80, v0
	v_add_u32_e32 v149, v1, v67
	v_add_u32_e32 v152, v0, v68
	v_and_b32_e32 v1, 0x7fffffff, v15
	v_and_b32_e32 v0, 0x7fffffff, v14
	v_xor_b32_e32 v2, -1, v15
	v_pk_add_f32 v[0:1], v[0:1], 0 neg_lo:[1,1] neg_hi:[1,1]
	v_cmp_gt_i32_e64 s[0:1], 0, v15
	v_xor_b32_e32 v3, -1, v14
	v_cmp_gt_i32_e32 vcc, 0, v14
	v_cndmask_b32_e64 v1, v1, v2, s[0:1]
	s_movk_i32 s0, 0x2000
	v_cndmask_b32_e32 v0, v0, v3, vcc
	v_add_co_u32_e32 v160, vcc, s0, v188
	v_and_b32_e32 v1, 0xffffff80, v1
	v_and_b32_e32 v0, 0xffffff80, v0
	v_addc_co_u32_e32 v161, vcc, 0, v189, vcc
	v_add_u32_e32 v151, v1, v69
	v_add_u32_e32 v154, v0, v70
	global_load_dwordx4 v[220:223], v[160:161], off
	global_load_dwordx4 v[236:239], v[160:161], off offset:32
	global_load_dwordx4 v[248:251], v[160:161], off offset:64
	global_load_dwordx4 v[180:183], v[160:161], off offset:96
	s_waitcnt vmcnt(3)
; #define MFMA32(a, b, c) __builtin_amdgcn_mfma_f32_32x32x16_bf16((a), (b), (c), 0, 0, 0)
; DI int crow(int r, int hi) { return (r & 3) + 8 * (r >> 2) + 4 * hi; }
; DI unsigned ordf(float f) { const unsigned u = __builtin_bit_cast(unsigned, f); return (u & 0x80000000u) ? ~u : (u | 0x80000000u); }
; DI void peer_half_topk(const bf16_t* qrow  , const bf16_t* subk  , int hi, int lane, LAS unsigned* ltop) {
;     ...
;     for (int rt = 0; rt < 4; ++rt) {
;         f32x16 acc;
; #pragma unroll
;         for (int r = 0; r < 16; ++r) acc[r] = 0.f;
; #pragma unroll
;         for (int kk = 0; kk < 8; ++kk) {
;             const bf16x8 af = *(const bf16x8*)(subk + (size_t)(rt * 32) * 128 + kk * 16);
;             const bf16x8 bf = *(const bf16x8*)(qrow + kk * 16);
;             acc = MFMA32(af, bf, acc);
;         }
; #pragma unroll
;         for (int r = 0; r < 16; ++r) { const int n = rt * 32 + crow(r, hi); keys[rt * 16 + r] = (ordf(acc[r]) & ~0x7Fu) | (unsigned)(127 - n); }
;     }
	v_mfma_f32_32x32x16_bf16 v[0:15], v[220:223], v[44:47], 0
	global_load_dwordx4 v[220:223], v[160:161], off offset:128
	s_waitcnt vmcnt(3)
	v_mfma_f32_32x32x16_bf16 v[0:15], v[236:239], v[40:43], v[0:15]
	global_load_dwordx4 v[236:239], v[160:161], off offset:160
	s_waitcnt vmcnt(3)
	v_mfma_f32_32x32x16_bf16 v[0:15], v[248:251], v[36:39], v[0:15]
	global_load_dwordx4 v[248:251], v[160:161], off offset:192
	s_waitcnt vmcnt(3)
	v_mfma_f32_32x32x16_bf16 v[0:15], v[180:183], v[32:35], v[0:15]
	global_load_dwordx4 v[180:183], v[160:161], off offset:224
	s_waitcnt vmcnt(3)
	v_mfma_f32_32x32x16_bf16 v[0:15], v[220:223], v[28:31], v[0:15]
	s_waitcnt vmcnt(2)
	v_mfma_f32_32x32x16_bf16 v[0:15], v[236:239], v[24:27], v[0:15]
	s_waitcnt vmcnt(1)
	v_mfma_f32_32x32x16_bf16 v[0:15], v[248:251], v[20:23], v[0:15]
	s_waitcnt vmcnt(0)
	v_mfma_f32_32x32x16_bf16 v[0:15], v[180:183], v[16:19], v[0:15]
	s_nop 11
	v_and_b32_e32 v157, 0x7fffffff, v1
	v_and_b32_e32 v156, 0x7fffffff, v0
	v_xor_b32_e32 v153, -1, v1
	v_xor_b32_e32 v155, -1, v0
	v_pk_add_f32 v[156:157], v[156:157], 0 neg_lo:[1,1] neg_hi:[1,1]
	v_cmp_gt_i32_e32 vcc, 0, v0
	v_cmp_gt_i32_e64 s[0:1], 0, v1
	s_nop 0
	v_cndmask_b32_e32 v1, v156, v155, vcc
	v_cndmask_b32_e64 v0, v157, v153, s[0:1]
	v_and_b32_e32 v0, 0xffffff80, v0
	v_and_b32_e32 v1, 0xffffff80, v1
	v_add_u32_e32 v153, v0, v71
	v_add_u32_e32 v156, v1, v72
	v_and_b32_e32 v1, 0x7fffffff, v3
	v_and_b32_e32 v0, 0x7fffffff, v2
	v_xor_b32_e32 v155, -1, v3
	v_xor_b32_e32 v157, -1, v2
	v_pk_add_f32 v[0:1], v[0:1], 0 neg_lo:[1,1] neg_hi:[1,1]
	v_cmp_gt_i32_e32 vcc, 0, v2
	v_cmp_gt_i32_e64 s[0:1], 0, v3
	v_xor_b32_e32 v2, -1, v5
	v_cndmask_b32_e32 v0, v0, v157, vcc
	v_cndmask_b32_e64 v1, v1, v155, s[0:1]
	v_and_b32_e32 v1, 0xffffff80, v1
	v_and_b32_e32 v0, 0xffffff80, v0
	v_add_u32_e32 v155, v1, v73
	v_add_u32_e32 v158, v0, v74
	v_and_b32_e32 v1, 0x7fffffff, v5
	v_and_b32_e32 v0, 0x7fffffff, v4
	v_xor_b32_e32 v3, -1, v4
	v_pk_add_f32 v[0:1], v[0:1], 0 neg_lo:[1,1] neg_hi:[1,1]
	v_cmp_gt_i32_e32 vcc, 0, v4
	v_cmp_gt_i32_e64 s[0:1], 0, v5
	s_nop 0
	v_cndmask_b32_e32 v0, v0, v3, vcc
	v_cndmask_b32_e64 v1, v1, v2, s[0:1]
	v_and_b32_e32 v1, 0xffffff80, v1
	v_and_b32_e32 v0, 0xffffff80, v0
	v_add_u32_e32 v157, v1, v75
	v_add_u32_e32 v160, v0, v76
	v_and_b32_e32 v1, 0x7fffffff, v7
	v_and_b32_e32 v0, 0x7fffffff, v6
	v_xor_b32_e32 v2, -1, v7
	v_xor_b32_e32 v3, -1, v6
	v_pk_add_f32 v[0:1], v[0:1], 0 neg_lo:[1,1] neg_hi:[1,1]
	v_cmp_gt_i32_e32 vcc, 0, v6
	v_cmp_gt_i32_e64 s[0:1], 0, v7
	s_nop 0
	v_cndmask_b32_e32 v0, v0, v3, vcc
	v_cndmask_b32_e64 v1, v1, v2, s[0:1]
	v_and_b32_e32 v1, 0xffffff80, v1
	v_and_b32_e32 v0, 0xffffff80, v0
	v_add_u32_e32 v159, v1, v77
	v_add_u32_e32 v162, v0, v78
	v_and_b32_e32 v1, 0x7fffffff, v9
	v_and_b32_e32 v0, 0x7fffffff, v8
	v_xor_b32_e32 v2, -1, v9
	v_xor_b32_e32 v3, -1, v8
	v_pk_add_f32 v[0:1], v[0:1], 0 neg_lo:[1,1] neg_hi:[1,1]
	v_cmp_gt_i32_e32 vcc, 0, v8
	v_cmp_gt_i32_e64 s[0:1], 0, v9
	s_nop 0
	v_cndmask_b32_e32 v0, v0, v3, vcc
	v_cndmask_b32_e64 v1, v1, v2, s[0:1]
	v_and_b32_e32 v1, 0xffffff80, v1
	v_and_b32_e32 v0, 0xffffff80, v0
	v_add_u32_e32 v161, v1, v79
	v_add_u32_e32 v164, v0, v80
	v_and_b32_e32 v1, 0x7fffffff, v11
	v_and_b32_e32 v0, 0x7fffffff, v10
	v_xor_b32_e32 v2, -1, v11
	v_xor_b32_e32 v3, -1, v10
	v_pk_add_f32 v[0:1], v[0:1], 0 neg_lo:[1,1] neg_hi:[1,1]
	v_cmp_gt_i32_e32 vcc, 0, v10
	v_cmp_gt_i32_e64 s[0:1], 0, v11
	s_nop 0
	v_cndmask_b32_e32 v0, v0, v3, vcc
	v_cndmask_b32_e64 v1, v1, v2, s[0:1]
	v_and_b32_e32 v1, 0xffffff80, v1
	v_and_b32_e32 v0, 0xffffff80, v0
	v_add_u32_e32 v163, v1, v81
	v_add_u32_e32 v166, v0, v82
	v_and_b32_e32 v1, 0x7fffffff, v13
	v_and_b32_e32 v0, 0x7fffffff, v12
	v_xor_b32_e32 v2, -1, v13
	v_xor_b32_e32 v3, -1, v12
	v_pk_add_f32 v[0:1], v[0:1], 0 neg_lo:[1,1] neg_hi:[1,1]
	v_cmp_gt_i32_e32 vcc, 0, v12
	v_cmp_gt_i32_e64 s[0:1], 0, v13
	s_nop 0
	v_cndmask_b32_e32 v0, v0, v3, vcc
	v_cndmask_b32_e64 v1, v1, v2, s[0:1]
	v_and_b32_e32 v1, 0xffffff80, v1
	v_and_b32_e32 v0, 0xffffff80, v0
	v_add_u32_e32 v165, v1, v83
	v_add_u32_e32 v168, v0, v84
	v_and_b32_e32 v1, 0x7fffffff, v15
	v_and_b32_e32 v0, 0x7fffffff, v14
	v_xor_b32_e32 v2, -1, v15
	v_pk_add_f32 v[0:1], v[0:1], 0 neg_lo:[1,1] neg_hi:[1,1]
	v_cmp_gt_i32_e64 s[0:1], 0, v15
	v_xor_b32_e32 v3, -1, v14
	v_cmp_gt_i32_e32 vcc, 0, v14
	v_cndmask_b32_e64 v1, v1, v2, s[0:1]
	s_movk_i32 s0, 0x4000
	v_cndmask_b32_e32 v0, v0, v3, vcc
	v_add_co_u32_e32 v176, vcc, s0, v188
	v_and_b32_e32 v1, 0xffffff80, v1
	v_and_b32_e32 v0, 0xffffff80, v0
	v_addc_co_u32_e32 v177, vcc, 0, v189, vcc
	v_add_u32_e32 v167, v1, v85
	v_add_u32_e32 v170, v0, v86
	global_load_dwordx4 v[220:223], v[176:177], off
	global_load_dwordx4 v[236:239], v[176:177], off offset:32
	global_load_dwordx4 v[248:251], v[176:177], off offset:64
	global_load_dwordx4 v[180:183], v[176:177], off offset:96
	s_waitcnt vmcnt(3)
	v_mfma_f32_32x32x16_bf16 v[0:15], v[220:223], v[44:47], 0
	global_load_dwordx4 v[220:223], v[176:177], off offset:128
	s_waitcnt vmcnt(3)
	v_mfma_f32_32x32x16_bf16 v[0:15], v[236:239], v[40:43], v[0:15]
	global_load_dwordx4 v[236:239], v[176:177], off offset:160
	s_waitcnt vmcnt(3)
	v_mfma_f32_32x32x16_bf16 v[0:15], v[248:251], v[36:39], v[0:15]
	global_load_dwordx4 v[248:251], v[176:177], off offset:192
	s_waitcnt vmcnt(3)
	v_mfma_f32_32x32x16_bf16 v[0:15], v[180:183], v[32:35], v[0:15]
	global_load_dwordx4 v[180:183], v[176:177], off offset:224
	s_waitcnt vmcnt(3)
	v_mfma_f32_32x32x16_bf16 v[0:15], v[220:223], v[28:31], v[0:15]
	s_waitcnt vmcnt(2)
	v_mfma_f32_32x32x16_bf16 v[0:15], v[236:239], v[24:27], v[0:15]
	s_waitcnt vmcnt(1)
; #define MFMA32(a, b, c) __builtin_amdgcn_mfma_f32_32x32x16_bf16((a), (b), (c), 0, 0, 0)
; DI int crow(int r, int hi) { return (r & 3) + 8 * (r >> 2) + 4 * hi; }
; DI unsigned ordf(float f) { const unsigned u = __builtin_bit_cast(unsigned, f); return (u & 0x80000000u) ? ~u : (u | 0x80000000u); }
; DI void peer_half_topk(const bf16_t* qrow  , const bf16_t* subk  , int hi, int lane, LAS unsigned* ltop) {
;     ...
;         for (int kk = 0; kk < 8; ++kk) {
;             const bf16x8 af = *(const bf16x8*)(subk + (size_t)(rt * 32) * 128 + kk * 16);
;             const bf16x8 bf = *(const bf16x8*)(qrow + kk * 16);
;             acc = MFMA32(af, bf, acc);
;         }
; #pragma unroll
;         for (int r = 0; r < 16; ++r) { const int n = rt * 32 + crow(r, hi); keys[rt * 16 + r] = (ordf(acc[r]) & ~0x7Fu) | (unsigned)(127 - n); }
	v_mfma_f32_32x32x16_bf16 v[0:15], v[248:251], v[20:23], v[0:15]
	s_waitcnt vmcnt(0)
	v_mfma_f32_32x32x16_bf16 v[0:15], v[180:183], v[16:19], v[0:15]
	s_nop 11
	v_and_b32_e32 v173, 0x7fffffff, v1
	v_and_b32_e32 v172, 0x7fffffff, v0
	v_xor_b32_e32 v169, -1, v1
	v_xor_b32_e32 v171, -1, v0
	v_pk_add_f32 v[172:173], v[172:173], 0 neg_lo:[1,1] neg_hi:[1,1]
	v_cmp_gt_i32_e32 vcc, 0, v0
	v_cmp_gt_i32_e64 s[0:1], 0, v1
	s_nop 0
	v_cndmask_b32_e32 v1, v172, v171, vcc
	v_cndmask_b32_e64 v0, v173, v169, s[0:1]
	v_and_b32_e32 v0, 0xffffff80, v0
	v_and_b32_e32 v1, 0xffffff80, v1
	v_add_u32_e32 v169, v0, v87
	v_add_u32_e32 v172, v1, v88
	v_and_b32_e32 v1, 0x7fffffff, v3
	v_and_b32_e32 v0, 0x7fffffff, v2
	v_xor_b32_e32 v171, -1, v3
	v_xor_b32_e32 v173, -1, v2
	v_pk_add_f32 v[0:1], v[0:1], 0 neg_lo:[1,1] neg_hi:[1,1]
	v_cmp_gt_i32_e32 vcc, 0, v2
	v_cmp_gt_i32_e64 s[0:1], 0, v3
	v_xor_b32_e32 v2, -1, v5
	v_cndmask_b32_e32 v0, v0, v173, vcc
	v_cndmask_b32_e64 v1, v1, v171, s[0:1]
	v_and_b32_e32 v1, 0xffffff80, v1
	v_and_b32_e32 v0, 0xffffff80, v0
	v_add_u32_e32 v171, v1, v89
	v_add_u32_e32 v174, v0, v90
	v_and_b32_e32 v1, 0x7fffffff, v5
	v_and_b32_e32 v0, 0x7fffffff, v4
	v_xor_b32_e32 v3, -1, v4
	v_pk_add_f32 v[0:1], v[0:1], 0 neg_lo:[1,1] neg_hi:[1,1]
	v_cmp_gt_i32_e32 vcc, 0, v4
	v_cmp_gt_i32_e64 s[0:1], 0, v5
	s_nop 0
	v_cndmask_b32_e32 v0, v0, v3, vcc
	v_cndmask_b32_e64 v1, v1, v2, s[0:1]
	v_and_b32_e32 v1, 0xffffff80, v1
	v_and_b32_e32 v0, 0xffffff80, v0
	v_add_u32_e32 v173, v1, v91
	v_add_u32_e32 v176, v0, v92
	v_and_b32_e32 v1, 0x7fffffff, v7
	v_and_b32_e32 v0, 0x7fffffff, v6
	v_xor_b32_e32 v2, -1, v7
	v_xor_b32_e32 v3, -1, v6
	v_pk_add_f32 v[0:1], v[0:1], 0 neg_lo:[1,1] neg_hi:[1,1]
	v_cmp_gt_i32_e32 vcc, 0, v6
	v_cmp_gt_i32_e64 s[0:1], 0, v7
	s_nop 0
	v_cndmask_b32_e32 v0, v0, v3, vcc
	v_cndmask_b32_e64 v1, v1, v2, s[0:1]
	v_and_b32_e32 v1, 0xffffff80, v1
	v_and_b32_e32 v0, 0xffffff80, v0
	v_add_u32_e32 v175, v1, v93
	v_add_u32_e32 v178, v0, v94
	v_and_b32_e32 v1, 0x7fffffff, v9
	v_and_b32_e32 v0, 0x7fffffff, v8
	v_xor_b32_e32 v2, -1, v9
	v_xor_b32_e32 v3, -1, v8
	v_pk_add_f32 v[0:1], v[0:1], 0 neg_lo:[1,1] neg_hi:[1,1]
	v_cmp_gt_i32_e32 vcc, 0, v8
	v_cmp_gt_i32_e64 s[0:1], 0, v9
	s_nop 0
	v_cndmask_b32_e32 v0, v0, v3, vcc
	v_cndmask_b32_e64 v1, v1, v2, s[0:1]
	v_and_b32_e32 v1, 0xffffff80, v1
	v_and_b32_e32 v0, 0xffffff80, v0
	v_add_u32_e32 v177, v1, v95
	v_add_u32_e32 v180, v0, v96
	v_and_b32_e32 v1, 0x7fffffff, v11
	v_and_b32_e32 v0, 0x7fffffff, v10
	v_xor_b32_e32 v2, -1, v11
	v_xor_b32_e32 v3, -1, v10
	v_pk_add_f32 v[0:1], v[0:1], 0 neg_lo:[1,1] neg_hi:[1,1]
	v_cmp_gt_i32_e32 vcc, 0, v10
	v_cmp_gt_i32_e64 s[0:1], 0, v11
	s_nop 0
	v_cndmask_b32_e32 v0, v0, v3, vcc
	v_cndmask_b32_e64 v1, v1, v2, s[0:1]
	v_and_b32_e32 v1, 0xffffff80, v1
	v_and_b32_e32 v0, 0xffffff80, v0
	v_add_u32_e32 v179, v1, v97
	v_add_u32_e32 v182, v0, v98
	v_and_b32_e32 v1, 0x7fffffff, v13
	v_and_b32_e32 v0, 0x7fffffff, v12
	v_xor_b32_e32 v2, -1, v13
	v_xor_b32_e32 v3, -1, v12
	v_pk_add_f32 v[0:1], v[0:1], 0 neg_lo:[1,1] neg_hi:[1,1]
	v_cmp_gt_i32_e32 vcc, 0, v12
	v_cmp_gt_i32_e64 s[0:1], 0, v13
	s_nop 0
	v_cndmask_b32_e32 v0, v0, v3, vcc
	v_cndmask_b32_e64 v1, v1, v2, s[0:1]
	v_and_b32_e32 v1, 0xffffff80, v1
	v_and_b32_e32 v0, 0xffffff80, v0
	v_add_u32_e32 v181, v1, v99
	v_add_u32_e32 v184, v0, v100
	v_and_b32_e32 v1, 0x7fffffff, v15
	v_and_b32_e32 v0, 0x7fffffff, v14
	v_xor_b32_e32 v2, -1, v15
	v_pk_add_f32 v[0:1], v[0:1], 0 neg_lo:[1,1] neg_hi:[1,1]
	v_cmp_gt_i32_e64 s[0:1], 0, v15
	v_xor_b32_e32 v3, -1, v14
	v_cmp_gt_i32_e32 vcc, 0, v14
	v_cndmask_b32_e64 v1, v1, v2, s[0:1]
	s_movk_i32 s0, 0x6000
	v_cndmask_b32_e32 v0, v0, v3, vcc
	v_add_co_u32_e32 v188, vcc, s0, v188
	v_and_b32_e32 v1, 0xffffff80, v1
	v_and_b32_e32 v0, 0xffffff80, v0
	v_addc_co_u32_e32 v189, vcc, 0, v189, vcc
	v_add_u32_e32 v183, v1, v101
	v_add_u32_e32 v186, v0, v102
	global_load_dwordx4 v[220:223], v[188:189], off
	global_load_dwordx4 v[236:239], v[188:189], off offset:32
	global_load_dwordx4 v[248:251], v[188:189], off offset:64
	s_waitcnt vmcnt(2)
	v_mfma_f32_32x32x16_bf16 v[0:15], v[220:223], v[44:47], 0
	global_load_dwordx4 v[220:223], v[188:189], off offset:96
	s_waitcnt vmcnt(2)
	v_mfma_f32_32x32x16_bf16 v[0:15], v[236:239], v[40:43], v[0:15]
	global_load_dwordx4 v[236:239], v[188:189], off offset:128
	s_waitcnt vmcnt(2)
	v_mfma_f32_32x32x16_bf16 v[0:15], v[248:251], v[36:39], v[0:15]
	global_load_dwordx4 v[248:251], v[188:189], off offset:160
	s_waitcnt vmcnt(2)
	v_mfma_f32_32x32x16_bf16 v[0:15], v[220:223], v[32:35], v[0:15]
	global_load_dwordx4 v[220:223], v[188:189], off offset:192
	s_waitcnt vmcnt(2)
	v_mfma_f32_32x32x16_bf16 v[0:15], v[236:239], v[28:31], v[0:15]
	global_load_dwordx4 v[236:239], v[188:189], off offset:224
	s_waitcnt vmcnt(2)
	v_mfma_f32_32x32x16_bf16 v[0:15], v[248:251], v[24:27], v[0:15]
	s_waitcnt vmcnt(1)
	v_mfma_f32_32x32x16_bf16 v[0:15], v[220:223], v[20:23], v[0:15]
	s_waitcnt vmcnt(0)
; #define MFMA32(a, b, c) __builtin_amdgcn_mfma_f32_32x32x16_bf16((a), (b), (c), 0, 0, 0)
; DI int crow(int r, int hi) { return (r & 3) + 8 * (r >> 2) + 4 * hi; }
; DI unsigned ordf(float f) { const unsigned u = __builtin_bit_cast(unsigned, f); return (u & 0x80000000u) ? ~u : (u | 0x80000000u); }
; DI void peer_half_topk(const bf16_t* qrow  , const bf16_t* subk  , int hi, int lane, LAS unsigned* ltop) {
;     ...
;             acc = MFMA32(af, bf, acc);
;         }
; #pragma unroll
;         for (int r = 0; r < 16; ++r) { const int n = rt * 32 + crow(r, hi); keys[rt * 16 + r] = (ordf(acc[r]) & ~0x7Fu) | (unsigned)(127 - n); }
;     }
; #pragma unroll 1
;     for (int k = 0; k < 16; ++k) {
;         unsigned mx = keys[0];
; #pragma unroll
;         for (int i = 1; i < 64; ++i) mx = mx > keys[i] ? mx : keys[i];
;         const unsigned om = (unsigned)__shfl_xor((int)mx, 32);
;         mx = mx > om ? mx : om;
;         ltop[k * 64 + lane] = mx;
; #pragma unroll
;         for (int i = 0; i < 64; ++i) keys[i] = keys[i] == mx ? 0u : keys[i];
;     }
	v_mfma_f32_32x32x16_bf16 v[0:15], v[236:239], v[16:19], v[0:15]
	s_nop 11
	v_and_b32_e32 v17, 0x7fffffff, v1
	v_and_b32_e32 v16, 0x7fffffff, v0
	v_xor_b32_e32 v18, -1, v1
	v_xor_b32_e32 v19, -1, v0
	v_pk_add_f32 v[16:17], v[16:17], 0 neg_lo:[1,1] neg_hi:[1,1]
	v_cmp_gt_i32_e32 vcc, 0, v0
	v_cmp_gt_i32_e64 s[0:1], 0, v1
	v_cmp_gt_i32_e64 s[40:41], 0, v15
	v_cndmask_b32_e32 v1, v16, v19, vcc
	v_cndmask_b32_e64 v0, v17, v18, s[0:1]
	v_and_b32_e32 v0, 0xffffff80, v0
	v_and_b32_e32 v16, 0xffffff80, v1
	v_add_u32_e32 v1, v0, v103
	v_add_u32_e32 v0, v16, v104
	v_and_b32_e32 v17, 0x7fffffff, v3
	v_and_b32_e32 v16, 0x7fffffff, v2
	v_xor_b32_e32 v18, -1, v3
	v_xor_b32_e32 v19, -1, v2
	v_pk_add_f32 v[16:17], v[16:17], 0 neg_lo:[1,1] neg_hi:[1,1]
	v_cmp_gt_i32_e32 vcc, 0, v2
	v_cmp_gt_i32_e64 s[0:1], 0, v3
	s_nop 0
	v_cndmask_b32_e32 v3, v16, v19, vcc
	v_cndmask_b32_e64 v2, v17, v18, s[0:1]
	v_and_b32_e32 v2, 0xffffff80, v2
	v_and_b32_e32 v16, 0xffffff80, v3
	v_add_u32_e32 v3, v2, v105
	v_add_u32_e32 v2, v16, v106
	v_and_b32_e32 v17, 0x7fffffff, v5
	v_and_b32_e32 v16, 0x7fffffff, v4
	v_xor_b32_e32 v18, -1, v5
	v_xor_b32_e32 v19, -1, v4
	v_pk_add_f32 v[16:17], v[16:17], 0 neg_lo:[1,1] neg_hi:[1,1]
	v_cmp_gt_i32_e32 vcc, 0, v4
	v_cmp_gt_i32_e64 s[0:1], 0, v5
	s_nop 0
	v_cndmask_b32_e32 v5, v16, v19, vcc
	v_cndmask_b32_e64 v4, v17, v18, s[0:1]
	v_and_b32_e32 v4, 0xffffff80, v4
	v_and_b32_e32 v16, 0xffffff80, v5
	v_add_u32_e32 v5, v4, v107
	v_add_u32_e32 v4, v16, v108
	v_and_b32_e32 v17, 0x7fffffff, v7
	v_and_b32_e32 v16, 0x7fffffff, v6
	v_xor_b32_e32 v18, -1, v7
	v_xor_b32_e32 v19, -1, v6
	v_pk_add_f32 v[16:17], v[16:17], 0 neg_lo:[1,1] neg_hi:[1,1]
	v_cmp_gt_i32_e32 vcc, 0, v6
	v_cmp_gt_i32_e64 s[0:1], 0, v7
	s_nop 0
	v_cndmask_b32_e32 v7, v16, v19, vcc
	v_cndmask_b32_e64 v6, v17, v18, s[0:1]
	v_and_b32_e32 v6, 0xffffff80, v6
	v_and_b32_e32 v16, 0xffffff80, v7
	v_add_u32_e32 v7, v6, v109
	v_add_u32_e32 v6, v16, v110
	v_and_b32_e32 v17, 0x7fffffff, v9
	v_and_b32_e32 v16, 0x7fffffff, v8
	v_xor_b32_e32 v18, -1, v9
	v_xor_b32_e32 v19, -1, v8
	v_pk_add_f32 v[16:17], v[16:17], 0 neg_lo:[1,1] neg_hi:[1,1]
	v_cmp_gt_i32_e32 vcc, 0, v8
	v_cmp_gt_i32_e64 s[0:1], 0, v9
	s_nop 0
	v_cndmask_b32_e32 v9, v16, v19, vcc
	v_cndmask_b32_e64 v8, v17, v18, s[0:1]
	v_and_b32_e32 v8, 0xffffff80, v8
	v_and_b32_e32 v16, 0xffffff80, v9
	v_add_u32_e32 v9, v8, v111
	v_add_u32_e32 v8, v16, v112
	v_and_b32_e32 v17, 0x7fffffff, v11
	v_and_b32_e32 v16, 0x7fffffff, v10
	v_xor_b32_e32 v18, -1, v11
	v_xor_b32_e32 v19, -1, v10
	v_pk_add_f32 v[16:17], v[16:17], 0 neg_lo:[1,1] neg_hi:[1,1]
	v_cmp_gt_i32_e32 vcc, 0, v10
	v_cmp_gt_i32_e64 s[0:1], 0, v11
	s_nop 0
	v_cndmask_b32_e32 v11, v16, v19, vcc
	v_cndmask_b32_e64 v10, v17, v18, s[0:1]
	v_and_b32_e32 v10, 0xffffff80, v10
	v_and_b32_e32 v16, 0xffffff80, v11
	v_add_u32_e32 v11, v10, v113
	v_add_u32_e32 v10, v16, v114
	v_and_b32_e32 v17, 0x7fffffff, v13
	v_and_b32_e32 v16, 0x7fffffff, v12
	v_xor_b32_e32 v18, -1, v13
	v_xor_b32_e32 v19, -1, v12
	v_pk_add_f32 v[16:17], v[16:17], 0 neg_lo:[1,1] neg_hi:[1,1]
	v_cmp_gt_i32_e32 vcc, 0, v12
	v_cmp_gt_i32_e64 s[0:1], 0, v13
	s_nop 0
	v_cndmask_b32_e32 v13, v16, v19, vcc
	v_cndmask_b32_e64 v12, v17, v18, s[0:1]
	v_and_b32_e32 v12, 0xffffff80, v12
	v_and_b32_e32 v16, 0xffffff80, v13
	v_add_u32_e32 v13, v12, v115
	v_add_u32_e32 v12, v16, v116
	v_and_b32_e32 v17, 0x7fffffff, v15
	v_and_b32_e32 v16, 0x7fffffff, v14
	v_xor_b32_e32 v18, -1, v15
	v_xor_b32_e32 v19, -1, v14
	v_pk_add_f32 v[16:17], v[16:17], 0 neg_lo:[1,1] neg_hi:[1,1]
	v_cmp_gt_i32_e32 vcc, 0, v14
	v_cndmask_b32_e64 v14, v17, v18, s[40:41]
	v_and_b32_e32 v14, 0xffffff80, v14
	v_cndmask_b32_e32 v15, v16, v19, vcc
	v_and_b32_e32 v16, 0xffffff80, v15
	v_and_b32_e32 v17, 64, v197
	v_add_u32_e32 v15, v14, v117
	v_add_u32_e32 v14, v16, v118
	v_xor_b32_e32 v16, 32, v197
	v_add_u32_e32 v17, 64, v17
	v_cmp_lt_i32_e32 vcc, v16, v17
	s_nop 1
	v_cndmask_b32_e32 v16, v197, v16, vcc
	v_lshlrev_b32_e32 v188, 2, v16
.LBB0_41:
	v_max_u32_e32 v16, v128, v49
	v_min_u32_e32 v128, v128, v49
	v_max_u32_e32 v17, v156, v153
	v_min_u32_e32 v156, v156, v153
	v_max_u32_e32 v18, v172, v169
	v_min_u32_e32 v172, v172, v169
	v_max_u32_e32 v19, v0, v1
	v_min_u32_e32 v0, v0, v1
	v_max_u32_e32 v49, v142, v119
	v_min_u32_e32 v142, v142, v119
	v_max_u32_e32 v153, v158, v155
	v_min_u32_e32 v158, v158, v155
	v_max_u32_e32 v169, v174, v171
	v_min_u32_e32 v174, v174, v171
	v_max_u32_e32 v1, v2, v3
	v_min_u32_e32 v2, v2, v3
	v_max_u32_e32 v119, v16, v49
	v_min_u32_e32 v16, v16, v49
	v_max_u32_e32 v155, v17, v153
	v_min_u32_e32 v17, v17, v153
	v_max_u32_e32 v171, v18, v169
	v_min_u32_e32 v18, v18, v169
	v_max_u32_e32 v3, v19, v1
	v_min_u32_e32 v19, v19, v1
	v_max_u32_e32 v49, v128, v142
	v_min_u32_e32 v128, v128, v142
	v_max_u32_e32 v153, v156, v158
	v_min_u32_e32 v156, v156, v158
	v_max_u32_e32 v169, v172, v174
	v_min_u32_e32 v172, v172, v174
	v_max_u32_e32 v1, v0, v2
	v_min_u32_e32 v0, v0, v2
	v_max_u32_e32 v142, v49, v16
	v_min_u32_e32 v49, v49, v16
	v_max_u32_e32 v158, v153, v17
	v_min_u32_e32 v153, v153, v17
	v_max_u32_e32 v174, v169, v18
	v_min_u32_e32 v169, v169, v18
	v_max_u32_e32 v2, v1, v19
	v_min_u32_e32 v1, v1, v19
	v_max_u32_e32 v16, v144, v131
	v_min_u32_e32 v144, v144, v131
	v_max_u32_e32 v17, v160, v157
	v_min_u32_e32 v160, v160, v157
	v_max_u32_e32 v18, v176, v173
	v_min_u32_e32 v176, v176, v173
	v_max_u32_e32 v19, v4, v5
	v_min_u32_e32 v4, v4, v5
	v_max_u32_e32 v131, v146, v143
	v_min_u32_e32 v146, v146, v143
	v_max_u32_e32 v157, v162, v159
	v_min_u32_e32 v162, v162, v159
	v_max_u32_e32 v173, v178, v175
	v_min_u32_e32 v178, v178, v175
	v_max_u32_e32 v5, v6, v7
; DI void peer_half_topk(const bf16_t* qrow  , const bf16_t* subk  , int hi, int lane, LAS unsigned* ltop) {
;     ...
; #pragma unroll 1
;     for (int k = 0; k < 16; ++k) {
;         unsigned mx = keys[0];
; #pragma unroll
;         for (int i = 1; i < 64; ++i) mx = mx > keys[i] ? mx : keys[i];
;         const unsigned om = (unsigned)__shfl_xor((int)mx, 32);
;         mx = mx > om ? mx : om;
;         ltop[k * 64 + lane] = mx;
; #pragma unroll
;         for (int i = 0; i < 64; ++i) keys[i] = keys[i] == mx ? 0u : keys[i];
;     }
	v_min_u32_e32 v6, v6, v7
	v_max_u32_e32 v143, v16, v131
	v_min_u32_e32 v16, v16, v131
	v_max_u32_e32 v159, v17, v157
	v_min_u32_e32 v17, v17, v157
	v_max_u32_e32 v175, v18, v173
	v_min_u32_e32 v18, v18, v173
	v_max_u32_e32 v7, v19, v5
	v_min_u32_e32 v19, v19, v5
	v_max_u32_e32 v131, v144, v146
	v_min_u32_e32 v144, v144, v146
	v_max_u32_e32 v157, v160, v162
	v_min_u32_e32 v160, v160, v162
	v_max_u32_e32 v173, v176, v178
	v_min_u32_e32 v176, v176, v178
	v_max_u32_e32 v5, v4, v6
	v_min_u32_e32 v4, v4, v6
	v_max_u32_e32 v146, v131, v16
	v_min_u32_e32 v131, v131, v16
	v_max_u32_e32 v162, v157, v17
	v_min_u32_e32 v157, v157, v17
	v_max_u32_e32 v178, v173, v18
	v_min_u32_e32 v173, v173, v18
	v_max_u32_e32 v6, v5, v19
	v_min_u32_e32 v5, v5, v19
	v_max_u32_e32 v16, v119, v143
	v_min_u32_e32 v119, v119, v143
	v_max_u32_e32 v17, v155, v159
	v_min_u32_e32 v155, v155, v159
	v_max_u32_e32 v18, v171, v175
	v_min_u32_e32 v171, v171, v175
	v_max_u32_e32 v19, v3, v7
	v_min_u32_e32 v3, v3, v7
	v_max_u32_e32 v143, v49, v131
	v_min_u32_e32 v49, v49, v131
	v_max_u32_e32 v159, v153, v157
	v_min_u32_e32 v153, v153, v157
	v_max_u32_e32 v175, v169, v173
	v_min_u32_e32 v169, v169, v173
	v_max_u32_e32 v7, v1, v5
	v_min_u32_e32 v1, v1, v5
	v_max_u32_e32 v131, v143, v119
	v_min_u32_e32 v143, v143, v119
	v_max_u32_e32 v157, v159, v155
	v_min_u32_e32 v159, v159, v155
	v_max_u32_e32 v173, v175, v171
	v_min_u32_e32 v175, v175, v171
	v_max_u32_e32 v5, v7, v3
	v_min_u32_e32 v7, v7, v3
	v_max_u32_e32 v119, v142, v146
	v_min_u32_e32 v142, v142, v146
	v_max_u32_e32 v155, v158, v162
	v_min_u32_e32 v158, v158, v162
	v_max_u32_e32 v171, v174, v178
	v_min_u32_e32 v174, v174, v178
	v_max_u32_e32 v3, v2, v6
	v_min_u32_e32 v2, v2, v6
	v_max_u32_e32 v146, v128, v144
	v_min_u32_e32 v128, v128, v144
	v_max_u32_e32 v162, v156, v160
	v_min_u32_e32 v156, v156, v160
	v_max_u32_e32 v178, v172, v176
	v_min_u32_e32 v172, v172, v176
	v_max_u32_e32 v6, v0, v4
	v_min_u32_e32 v0, v0, v4
	v_max_u32_e32 v144, v146, v142
	v_min_u32_e32 v146, v146, v142
	v_max_u32_e32 v160, v162, v158
	v_min_u32_e32 v162, v162, v158
	v_max_u32_e32 v176, v178, v174
	v_min_u32_e32 v178, v178, v174
	v_max_u32_e32 v4, v6, v2
	v_min_u32_e32 v6, v6, v2
	v_max_u32_e32 v142, v119, v131
	v_min_u32_e32 v119, v119, v131
	v_max_u32_e32 v158, v155, v157
	v_min_u32_e32 v155, v155, v157
	v_max_u32_e32 v174, v171, v173
	v_min_u32_e32 v171, v171, v173
	v_max_u32_e32 v2, v3, v5
	v_min_u32_e32 v3, v3, v5
	v_max_u32_e32 v131, v144, v143
	v_min_u32_e32 v144, v144, v143
	v_max_u32_e32 v157, v160, v159
	v_min_u32_e32 v160, v160, v159
	v_max_u32_e32 v173, v176, v175
	v_min_u32_e32 v176, v176, v175
	v_max_u32_e32 v5, v4, v7
	v_min_u32_e32 v4, v4, v7
	v_max_u32_e32 v143, v146, v49
	v_min_u32_e32 v146, v146, v49
	v_max_u32_e32 v159, v162, v153
	v_min_u32_e32 v162, v162, v153
	v_max_u32_e32 v175, v178, v169
	v_min_u32_e32 v178, v178, v169
	v_max_u32_e32 v7, v6, v1
	v_min_u32_e32 v6, v6, v1
	v_max_u32_e32 v49, v148, v145
	v_min_u32_e32 v148, v148, v145
	v_max_u32_e32 v153, v164, v161
	v_min_u32_e32 v164, v164, v161
	v_max_u32_e32 v169, v180, v177
	v_min_u32_e32 v180, v180, v177
	v_max_u32_e32 v1, v8, v9
	v_min_u32_e32 v8, v8, v9
	v_max_u32_e32 v145, v150, v147
	v_min_u32_e32 v150, v150, v147
	v_max_u32_e32 v161, v166, v163
	v_min_u32_e32 v166, v166, v163
	v_max_u32_e32 v177, v182, v179
	v_min_u32_e32 v182, v182, v179
	v_max_u32_e32 v9, v10, v11
	v_min_u32_e32 v10, v10, v11
	v_max_u32_e32 v147, v49, v145
	v_min_u32_e32 v49, v49, v145
	v_max_u32_e32 v163, v153, v161
	v_min_u32_e32 v153, v153, v161
	v_max_u32_e32 v179, v169, v177
	v_min_u32_e32 v169, v169, v177
	v_max_u32_e32 v11, v1, v9
	v_min_u32_e32 v1, v1, v9
	v_max_u32_e32 v145, v148, v150
	v_min_u32_e32 v148, v148, v150
	v_max_u32_e32 v161, v164, v166
	v_min_u32_e32 v164, v164, v166
	v_max_u32_e32 v177, v180, v182
	v_min_u32_e32 v180, v180, v182
	v_max_u32_e32 v9, v8, v10
	v_min_u32_e32 v8, v8, v10
	v_max_u32_e32 v150, v145, v49
	v_min_u32_e32 v145, v145, v49
	v_max_u32_e32 v166, v161, v153
	v_min_u32_e32 v161, v161, v153
	v_max_u32_e32 v182, v177, v169
	v_min_u32_e32 v177, v177, v169
	v_max_u32_e32 v10, v9, v1
	v_min_u32_e32 v9, v9, v1
	v_max_u32_e32 v49, v152, v149
	v_min_u32_e32 v152, v152, v149
	v_max_u32_e32 v153, v168, v165
	v_min_u32_e32 v168, v168, v165
	v_max_u32_e32 v169, v184, v181
	v_min_u32_e32 v184, v184, v181
	v_max_u32_e32 v1, v12, v13
	v_min_u32_e32 v12, v12, v13
	v_max_u32_e32 v149, v154, v151
	v_min_u32_e32 v154, v154, v151
	v_max_u32_e32 v165, v170, v167
	v_min_u32_e32 v170, v170, v167
	v_max_u32_e32 v181, v186, v183
	v_min_u32_e32 v186, v186, v183
	v_max_u32_e32 v13, v14, v15
	v_min_u32_e32 v14, v14, v15
	v_max_u32_e32 v151, v49, v149
	v_min_u32_e32 v49, v49, v149
	v_max_u32_e32 v167, v153, v165
	v_min_u32_e32 v153, v153, v165
	v_max_u32_e32 v183, v169, v181
	v_min_u32_e32 v169, v169, v181
	v_max_u32_e32 v15, v1, v13
	v_min_u32_e32 v1, v1, v13
	v_max_u32_e32 v149, v152, v154
	v_min_u32_e32 v152, v152, v154
	v_max_u32_e32 v165, v168, v170
	v_min_u32_e32 v168, v168, v170
	v_max_u32_e32 v181, v184, v186
	v_min_u32_e32 v184, v184, v186
	v_max_u32_e32 v13, v12, v14
	v_min_u32_e32 v12, v12, v14
	v_max_u32_e32 v154, v149, v49
	v_min_u32_e32 v149, v149, v49
	v_max_u32_e32 v170, v165, v153
	v_min_u32_e32 v165, v165, v153
	v_max_u32_e32 v186, v181, v169
	v_min_u32_e32 v181, v181, v169
	v_max_u32_e32 v14, v13, v1
	v_min_u32_e32 v13, v13, v1
	v_max_u32_e32 v49, v147, v151
	v_min_u32_e32 v147, v147, v151
	v_max_u32_e32 v153, v163, v167
	v_min_u32_e32 v163, v163, v167
	v_max_u32_e32 v169, v179, v183
	v_min_u32_e32 v179, v179, v183
	v_max_u32_e32 v1, v11, v15
	v_min_u32_e32 v11, v11, v15
; DI void peer_half_topk(const bf16_t* qrow  , const bf16_t* subk  , int hi, int lane, LAS unsigned* ltop) {
;     ...
; #pragma unroll 1
;     for (int k = 0; k < 16; ++k) {
;         unsigned mx = keys[0];
; #pragma unroll
;         for (int i = 1; i < 64; ++i) mx = mx > keys[i] ? mx : keys[i];
;         const unsigned om = (unsigned)__shfl_xor((int)mx, 32);
;         mx = mx > om ? mx : om;
;         ltop[k * 64 + lane] = mx;
; #pragma unroll
;         for (int i = 0; i < 64; ++i) keys[i] = keys[i] == mx ? 0u : keys[i];
;     }
	v_max_u32_e32 v151, v145, v149
	v_min_u32_e32 v145, v145, v149
	v_max_u32_e32 v167, v161, v165
	v_min_u32_e32 v161, v161, v165
	v_max_u32_e32 v183, v177, v181
	v_min_u32_e32 v177, v177, v181
	v_max_u32_e32 v15, v9, v13
	v_min_u32_e32 v9, v9, v13
	v_max_u32_e32 v149, v151, v147
	v_min_u32_e32 v151, v151, v147
	v_max_u32_e32 v165, v167, v163
	v_min_u32_e32 v167, v167, v163
	v_max_u32_e32 v181, v183, v179
	v_min_u32_e32 v183, v183, v179
	v_max_u32_e32 v13, v15, v11
	v_min_u32_e32 v15, v15, v11
	v_max_u32_e32 v147, v150, v154
	v_min_u32_e32 v150, v150, v154
	v_max_u32_e32 v163, v166, v170
	v_min_u32_e32 v166, v166, v170
	v_max_u32_e32 v179, v182, v186
	v_min_u32_e32 v182, v182, v186
	v_max_u32_e32 v11, v10, v14
	v_min_u32_e32 v10, v10, v14
	v_max_u32_e32 v154, v148, v152
	v_min_u32_e32 v148, v148, v152
	v_max_u32_e32 v170, v164, v168
	v_min_u32_e32 v164, v164, v168
	v_max_u32_e32 v186, v180, v184
	v_min_u32_e32 v180, v180, v184
	v_max_u32_e32 v14, v8, v12
	v_min_u32_e32 v8, v8, v12
	v_max_u32_e32 v152, v154, v150
	v_min_u32_e32 v154, v154, v150
	v_max_u32_e32 v168, v170, v166
	v_min_u32_e32 v170, v170, v166
	v_max_u32_e32 v184, v186, v182
	v_min_u32_e32 v186, v186, v182
	v_max_u32_e32 v12, v14, v10
	v_min_u32_e32 v14, v14, v10
	v_max_u32_e32 v150, v147, v149
	v_min_u32_e32 v147, v147, v149
	v_max_u32_e32 v166, v163, v165
	v_min_u32_e32 v163, v163, v165
	v_max_u32_e32 v182, v179, v181
	v_min_u32_e32 v179, v179, v181
	v_max_u32_e32 v10, v11, v13
	v_min_u32_e32 v11, v11, v13
	v_max_u32_e32 v149, v152, v151
	v_min_u32_e32 v152, v152, v151
	v_max_u32_e32 v165, v168, v167
	v_min_u32_e32 v168, v168, v167
	v_max_u32_e32 v181, v184, v183
	v_min_u32_e32 v184, v184, v183
	v_max_u32_e32 v13, v12, v15
	v_min_u32_e32 v12, v12, v15
	v_max_u32_e32 v151, v154, v145
	v_min_u32_e32 v154, v154, v145
	v_max_u32_e32 v167, v170, v161
	v_min_u32_e32 v170, v170, v161
	v_max_u32_e32 v183, v186, v177
	v_min_u32_e32 v186, v186, v177
	v_max_u32_e32 v15, v14, v9
	v_min_u32_e32 v14, v14, v9
	v_max_u32_e32 v145, v16, v49
	v_min_u32_e32 v16, v16, v49
	v_max_u32_e32 v161, v17, v153
	v_min_u32_e32 v17, v17, v153
	v_max_u32_e32 v177, v18, v169
	v_min_u32_e32 v18, v18, v169
	v_max_u32_e32 v9, v19, v1
	v_min_u32_e32 v19, v19, v1
	v_max_u32_e32 v49, v144, v152
	v_min_u32_e32 v144, v144, v152
	v_max_u32_e32 v153, v160, v168
	v_min_u32_e32 v160, v160, v168
	v_max_u32_e32 v169, v176, v184
	v_min_u32_e32 v176, v176, v184
	v_max_u32_e32 v1, v4, v12
	v_min_u32_e32 v4, v4, v12
	v_max_u32_e32 v152, v49, v16
	v_min_u32_e32 v49, v49, v16
	v_max_u32_e32 v168, v153, v17
	v_min_u32_e32 v153, v153, v17
	v_max_u32_e32 v184, v169, v18
	v_min_u32_e32 v169, v169, v18
	v_max_u32_e32 v12, v1, v19
	v_min_u32_e32 v1, v1, v19
	v_max_u32_e32 v16, v119, v147
	v_min_u32_e32 v119, v119, v147
	v_max_u32_e32 v17, v155, v163
	v_min_u32_e32 v155, v155, v163
	v_max_u32_e32 v18, v171, v179
	v_min_u32_e32 v171, v171, v179
	v_max_u32_e32 v19, v3, v11
	v_min_u32_e32 v3, v3, v11
	v_max_u32_e32 v147, v146, v154
	v_min_u32_e32 v146, v146, v154
	v_max_u32_e32 v163, v162, v170
	v_min_u32_e32 v162, v162, v170
	v_max_u32_e32 v179, v178, v186
	v_min_u32_e32 v178, v178, v186
	v_max_u32_e32 v11, v6, v14
	v_min_u32_e32 v6, v6, v14
	v_max_u32_e32 v154, v147, v119
	v_min_u32_e32 v147, v147, v119
	v_max_u32_e32 v170, v163, v155
	v_min_u32_e32 v163, v163, v155
	v_max_u32_e32 v186, v179, v171
	v_min_u32_e32 v179, v179, v171
	v_max_u32_e32 v14, v11, v3
	v_min_u32_e32 v11, v11, v3
	v_max_u32_e32 v119, v16, v152
	v_min_u32_e32 v16, v16, v152
	v_max_u32_e32 v155, v17, v168
	v_min_u32_e32 v17, v17, v168
	v_max_u32_e32 v171, v18, v184
	v_min_u32_e32 v18, v18, v184
	v_max_u32_e32 v3, v19, v12
	v_min_u32_e32 v19, v19, v12
	v_max_u32_e32 v152, v154, v49
	v_min_u32_e32 v154, v154, v49
	v_max_u32_e32 v168, v170, v153
	v_min_u32_e32 v170, v170, v153
	v_max_u32_e32 v184, v186, v169
	v_min_u32_e32 v186, v186, v169
	v_max_u32_e32 v12, v14, v1
	v_min_u32_e32 v14, v14, v1
	v_max_u32_e32 v49, v147, v144
	v_min_u32_e32 v147, v147, v144
	v_max_u32_e32 v153, v163, v160
	v_min_u32_e32 v163, v163, v160
	v_max_u32_e32 v169, v179, v176
	v_min_u32_e32 v179, v179, v176
	v_max_u32_e32 v1, v11, v4
	v_min_u32_e32 v11, v11, v4
	v_max_u32_e32 v144, v142, v150
	v_min_u32_e32 v142, v142, v150
	v_max_u32_e32 v160, v158, v166
	v_min_u32_e32 v158, v158, v166
	v_max_u32_e32 v176, v174, v182
	v_min_u32_e32 v174, v174, v182
	v_max_u32_e32 v4, v2, v10
	v_min_u32_e32 v2, v2, v10
	v_max_u32_e32 v150, v143, v151
	v_min_u32_e32 v143, v143, v151
	v_max_u32_e32 v166, v159, v167
	v_min_u32_e32 v159, v159, v167
	v_max_u32_e32 v182, v175, v183
	v_min_u32_e32 v175, v175, v183
	v_max_u32_e32 v10, v7, v15
	v_min_u32_e32 v7, v7, v15
	v_max_u32_e32 v151, v150, v142
	v_min_u32_e32 v150, v150, v142
	v_max_u32_e32 v167, v166, v158
	v_min_u32_e32 v166, v166, v158
	v_max_u32_e32 v183, v182, v174
	v_min_u32_e32 v182, v182, v174
	v_max_u32_e32 v15, v10, v2
	v_min_u32_e32 v10, v10, v2
	v_max_u32_e32 v142, v131, v149
	v_min_u32_e32 v131, v131, v149
	v_max_u32_e32 v158, v157, v165
	v_min_u32_e32 v157, v157, v165
	v_max_u32_e32 v174, v173, v181
	v_min_u32_e32 v173, v173, v181
	v_max_u32_e32 v2, v5, v13
	v_min_u32_e32 v5, v5, v13
	v_max_u32_e32 v149, v128, v148
	v_min_u32_e32 v128, v128, v148
	v_max_u32_e32 v165, v156, v164
	v_min_u32_e32 v156, v156, v164
	v_max_u32_e32 v181, v172, v180
	v_min_u32_e32 v172, v172, v180
	v_max_u32_e32 v13, v0, v8
	v_min_u32_e32 v0, v0, v8
	v_max_u32_e32 v148, v149, v131
	v_min_u32_e32 v149, v149, v131
	v_max_u32_e32 v164, v165, v157
	v_min_u32_e32 v165, v165, v157
	v_max_u32_e32 v180, v181, v173
	v_min_u32_e32 v181, v181, v173
	v_max_u32_e32 v8, v13, v5
; DI void peer_half_topk(const bf16_t* qrow  , const bf16_t* subk  , int hi, int lane, LAS unsigned* ltop) {
;     ...
; #pragma unroll 1
;     for (int k = 0; k < 16; ++k) {
;         unsigned mx = keys[0];
; #pragma unroll
;         for (int i = 1; i < 64; ++i) mx = mx > keys[i] ? mx : keys[i];
;         const unsigned om = (unsigned)__shfl_xor((int)mx, 32);
;         mx = mx > om ? mx : om;
;         ltop[k * 64 + lane] = mx;
; #pragma unroll
;         for (int i = 0; i < 64; ++i) keys[i] = keys[i] == mx ? 0u : keys[i];
;     }
	v_min_u32_e32 v13, v13, v5
	v_max_u32_e32 v131, v142, v151
	v_min_u32_e32 v142, v142, v151
	v_max_u32_e32 v157, v158, v167
	v_min_u32_e32 v158, v158, v167
	v_max_u32_e32 v173, v174, v183
	v_min_u32_e32 v174, v174, v183
	v_max_u32_e32 v5, v2, v15
	v_min_u32_e32 v2, v2, v15
	v_max_u32_e32 v151, v148, v150
	v_min_u32_e32 v148, v148, v150
	v_max_u32_e32 v167, v164, v166
	v_min_u32_e32 v164, v164, v166
	v_max_u32_e32 v183, v180, v182
	v_min_u32_e32 v180, v180, v182
	v_max_u32_e32 v15, v8, v10
	v_min_u32_e32 v8, v8, v10
	v_max_u32_e32 v150, v149, v143
	v_min_u32_e32 v149, v149, v143
	v_max_u32_e32 v166, v165, v159
	v_min_u32_e32 v165, v165, v159
	v_max_u32_e32 v182, v181, v175
	v_min_u32_e32 v181, v181, v175
	v_max_u32_e32 v10, v13, v7
	v_min_u32_e32 v13, v13, v7
	v_max_u32_e32 v143, v144, v119
	v_min_u32_e32 v144, v144, v119
	v_max_u32_e32 v159, v160, v155
	v_min_u32_e32 v160, v160, v155
	v_max_u32_e32 v175, v176, v171
	v_min_u32_e32 v176, v176, v171
	v_max_u32_e32 v7, v4, v3
	v_min_u32_e32 v4, v4, v3
	v_max_u32_e32 v119, v131, v16
	v_min_u32_e32 v131, v131, v16
	v_max_u32_e32 v155, v157, v17
	v_min_u32_e32 v157, v157, v17
	v_max_u32_e32 v171, v173, v18
	v_min_u32_e32 v173, v173, v18
	v_max_u32_e32 v3, v5, v19
	v_min_u32_e32 v5, v5, v19
	v_max_u32_e32 v16, v142, v152
	v_min_u32_e32 v142, v142, v152
	v_max_u32_e32 v17, v158, v168
	v_min_u32_e32 v158, v158, v168
	v_max_u32_e32 v18, v174, v184
	v_min_u32_e32 v174, v174, v184
	v_max_u32_e32 v19, v2, v12
	v_min_u32_e32 v2, v2, v12
	v_max_u32_e32 v152, v151, v154
	v_min_u32_e32 v151, v151, v154
	v_max_u32_e32 v168, v167, v170
	v_min_u32_e32 v167, v167, v170
	v_max_u32_e32 v184, v183, v186
	v_min_u32_e32 v183, v183, v186
	v_max_u32_e32 v12, v15, v14
	v_min_u32_e32 v15, v15, v14
	v_max_u32_e32 v154, v148, v49
	v_min_u32_e32 v148, v148, v49
	v_max_u32_e32 v170, v164, v153
	v_min_u32_e32 v164, v164, v153
	v_max_u32_e32 v186, v180, v169
	v_min_u32_e32 v180, v180, v169
	v_max_u32_e32 v14, v8, v1
	v_min_u32_e32 v8, v8, v1
	v_max_u32_e32 v49, v150, v147
	v_min_u32_e32 v150, v150, v147
	v_max_u32_e32 v153, v166, v163
	v_min_u32_e32 v166, v166, v163
	v_max_u32_e32 v169, v182, v179
	v_min_u32_e32 v182, v182, v179
	v_max_u32_e32 v1, v10, v11
	v_min_u32_e32 v10, v10, v11
	v_max_u32_e32 v147, v149, v146
	v_min_u32_e32 v149, v149, v146
	v_max_u32_e32 v163, v165, v162
	v_min_u32_e32 v165, v165, v162
	v_max_u32_e32 v179, v181, v178
	v_min_u32_e32 v181, v181, v178
	v_max_u32_e32 v11, v13, v6
	v_min_u32_e32 v13, v13, v6
	v_max_u32_e32 v145, v145, v156
	v_max_u32_e32 v177, v177, v0
	v_max_u32_e32 v143, v143, v165
	v_max_u32_e32 v175, v175, v13
	v_max_u32_e32 v144, v144, v163
	v_max_u32_e32 v176, v176, v11
	v_max_u32_e32 v119, v119, v166
	v_max_u32_e32 v171, v171, v10
	v_max_u32_e32 v131, v131, v153
	v_max_u32_e32 v173, v173, v1
	v_max_u32_e32 v16, v16, v164
	v_max_u32_e32 v18, v18, v8
	v_max_u32_e32 v142, v142, v170
	v_max_u32_e32 v174, v174, v14
	v_max_u32_e32 v152, v152, v167
	v_max_u32_e32 v184, v184, v15
	v_max_u32_e32 v151, v151, v168
	v_max_u32_e32 v183, v183, v12
	v_max_u32_e32 v154, v154, v158
	v_max_u32_e32 v186, v186, v2
	v_max_u32_e32 v148, v148, v17
	v_max_u32_e32 v180, v180, v19
	v_max_u32_e32 v49, v49, v157
	v_max_u32_e32 v169, v169, v5
	v_max_u32_e32 v150, v150, v155
	v_max_u32_e32 v182, v182, v3
	v_max_u32_e32 v147, v147, v160
	v_max_u32_e32 v179, v179, v4
	v_max_u32_e32 v149, v149, v159
	v_max_u32_e32 v181, v181, v7
	v_max_u32_e32 v128, v128, v161
	v_max_u32_e32 v172, v172, v9
	v_max_u32_e32 v146, v145, v151
	v_min_u32_e32 v145, v145, v151
	v_max_u32_e32 v178, v177, v183
	v_min_u32_e32 v177, v177, v183
	v_max_u32_e32 v151, v143, v154
	v_min_u32_e32 v143, v143, v154
	v_max_u32_e32 v183, v175, v186
	v_min_u32_e32 v175, v175, v186
	v_max_u32_e32 v154, v144, v148
	v_min_u32_e32 v144, v144, v148
	v_max_u32_e32 v186, v176, v180
	v_min_u32_e32 v176, v176, v180
	v_max_u32_e32 v148, v119, v49
	v_min_u32_e32 v119, v119, v49
	v_max_u32_e32 v180, v171, v169
	v_min_u32_e32 v171, v171, v169
	v_max_u32_e32 v49, v131, v150
	v_min_u32_e32 v131, v131, v150
	v_max_u32_e32 v169, v173, v182
	v_min_u32_e32 v173, v173, v182
	v_max_u32_e32 v150, v16, v147
	v_min_u32_e32 v16, v16, v147
	v_max_u32_e32 v182, v18, v179
	v_min_u32_e32 v18, v18, v179
	v_max_u32_e32 v147, v142, v149
	v_min_u32_e32 v142, v142, v149
	v_max_u32_e32 v179, v174, v181
	v_min_u32_e32 v174, v174, v181
	v_max_u32_e32 v149, v152, v128
	v_min_u32_e32 v152, v152, v128
	v_max_u32_e32 v181, v184, v172
	v_min_u32_e32 v184, v184, v172
	v_max_u32_e32 v128, v146, v49
	v_min_u32_e32 v146, v146, v49
	v_max_u32_e32 v172, v178, v169
	v_min_u32_e32 v178, v178, v169
	v_max_u32_e32 v49, v151, v150
	v_min_u32_e32 v151, v151, v150
	v_max_u32_e32 v169, v183, v182
	v_min_u32_e32 v183, v183, v182
	v_max_u32_e32 v150, v154, v147
	v_min_u32_e32 v154, v154, v147
	v_max_u32_e32 v182, v186, v179
	v_min_u32_e32 v186, v186, v179
	v_max_u32_e32 v147, v148, v149
	v_min_u32_e32 v148, v148, v149
	v_max_u32_e32 v179, v180, v181
	v_min_u32_e32 v180, v180, v181
	v_max_u32_e32 v149, v145, v131
	v_min_u32_e32 v145, v145, v131
	v_max_u32_e32 v181, v177, v173
	v_min_u32_e32 v177, v177, v173
	v_max_u32_e32 v131, v143, v16
	v_min_u32_e32 v143, v143, v16
	v_max_u32_e32 v173, v175, v18
	v_min_u32_e32 v175, v175, v18
	v_max_u32_e32 v16, v144, v142
	v_min_u32_e32 v144, v144, v142
	v_max_u32_e32 v18, v176, v174
	v_min_u32_e32 v176, v176, v174
	v_max_u32_e32 v142, v119, v152
	v_min_u32_e32 v119, v119, v152
	v_max_u32_e32 v174, v171, v184
	v_min_u32_e32 v171, v171, v184
	v_max_u32_e32 v152, v128, v150
	v_min_u32_e32 v128, v128, v150
	v_max_u32_e32 v184, v172, v182
	v_min_u32_e32 v172, v172, v182
; DI void peer_half_topk(const bf16_t* qrow  , const bf16_t* subk  , int hi, int lane, LAS unsigned* ltop) {
;     ...
; #pragma unroll 1
;     for (int k = 0; k < 16; ++k) {
;         unsigned mx = keys[0];
; #pragma unroll
;         for (int i = 1; i < 64; ++i) mx = mx > keys[i] ? mx : keys[i];
;         const unsigned om = (unsigned)__shfl_xor((int)mx, 32);
;         mx = mx > om ? mx : om;
;         ltop[k * 64 + lane] = mx;
; #pragma unroll
;         for (int i = 0; i < 64; ++i) keys[i] = keys[i] == mx ? 0u : keys[i];
;     }
	v_max_u32_e32 v150, v49, v147
	v_min_u32_e32 v49, v49, v147
	v_max_u32_e32 v182, v169, v179
	v_min_u32_e32 v169, v169, v179
	v_max_u32_e32 v147, v146, v154
	v_min_u32_e32 v146, v146, v154
	v_max_u32_e32 v179, v178, v186
	v_min_u32_e32 v178, v178, v186
	v_max_u32_e32 v154, v151, v148
	v_min_u32_e32 v151, v151, v148
	v_max_u32_e32 v186, v183, v180
	v_min_u32_e32 v183, v183, v180
	v_max_u32_e32 v148, v149, v16
	v_min_u32_e32 v149, v149, v16
	v_max_u32_e32 v180, v181, v18
	v_min_u32_e32 v181, v181, v18
	v_max_u32_e32 v16, v131, v142
	v_min_u32_e32 v131, v131, v142
	v_max_u32_e32 v18, v173, v174
	v_min_u32_e32 v173, v173, v174
	v_max_u32_e32 v142, v145, v144
	v_min_u32_e32 v145, v145, v144
	v_max_u32_e32 v174, v177, v176
	v_min_u32_e32 v177, v177, v176
	v_max_u32_e32 v144, v143, v119
	v_min_u32_e32 v143, v143, v119
	v_max_u32_e32 v176, v175, v171
	v_min_u32_e32 v175, v175, v171
	v_max_u32_e32 v119, v152, v150
	v_min_u32_e32 v152, v152, v150
	v_max_u32_e32 v171, v184, v182
	v_min_u32_e32 v184, v184, v182
	v_max_u32_e32 v150, v128, v49
	v_min_u32_e32 v128, v128, v49
	v_max_u32_e32 v182, v172, v169
	v_min_u32_e32 v172, v172, v169
	v_max_u32_e32 v49, v147, v154
	v_min_u32_e32 v147, v147, v154
	v_max_u32_e32 v169, v179, v186
	v_min_u32_e32 v179, v179, v186
	v_max_u32_e32 v154, v146, v151
	v_min_u32_e32 v146, v146, v151
	v_max_u32_e32 v186, v178, v183
	v_min_u32_e32 v178, v178, v183
	v_max_u32_e32 v151, v148, v16
	v_min_u32_e32 v148, v148, v16
	v_max_u32_e32 v183, v180, v18
	v_min_u32_e32 v180, v180, v18
	v_max_u32_e32 v16, v149, v131
	v_min_u32_e32 v149, v149, v131
	v_max_u32_e32 v18, v181, v173
	v_min_u32_e32 v181, v181, v173
	v_max_u32_e32 v131, v142, v144
	v_min_u32_e32 v142, v142, v144
	v_max_u32_e32 v173, v174, v176
	v_min_u32_e32 v174, v174, v176
	v_max_u32_e32 v144, v145, v143
	v_min_u32_e32 v145, v145, v143
	v_max_u32_e32 v176, v177, v175
	v_min_u32_e32 v177, v177, v175
	v_max_u32_e32 v119, v119, v177
	v_max_u32_e32 v152, v152, v176
	v_max_u32_e32 v150, v150, v174
	v_max_u32_e32 v128, v128, v173
	v_max_u32_e32 v49, v49, v181
	v_max_u32_e32 v147, v147, v18
	v_max_u32_e32 v154, v154, v180
	v_max_u32_e32 v146, v146, v183
	v_max_u32_e32 v151, v151, v178
	v_max_u32_e32 v148, v148, v186
	v_max_u32_e32 v16, v16, v179
	v_max_u32_e32 v149, v149, v169
	v_max_u32_e32 v131, v131, v172
	v_max_u32_e32 v142, v142, v182
	v_max_u32_e32 v144, v144, v184
	v_max_u32_e32 v145, v145, v171
	v_max_u32_e32 v143, v119, v151
	v_min_u32_e32 v119, v119, v151
	v_max_u32_e32 v151, v152, v148
	v_min_u32_e32 v152, v152, v148
	v_max_u32_e32 v148, v150, v16
	v_min_u32_e32 v150, v150, v16
	v_max_u32_e32 v16, v128, v149
	v_min_u32_e32 v128, v128, v149
	v_max_u32_e32 v149, v49, v131
	v_min_u32_e32 v49, v49, v131
	v_max_u32_e32 v131, v147, v142
	v_min_u32_e32 v147, v147, v142
	v_max_u32_e32 v142, v154, v144
	v_min_u32_e32 v154, v154, v144
	v_max_u32_e32 v144, v146, v145
	v_min_u32_e32 v146, v146, v145
	v_max_u32_e32 v145, v143, v149
	v_min_u32_e32 v143, v143, v149
	v_max_u32_e32 v149, v151, v131
	v_min_u32_e32 v151, v151, v131
	v_max_u32_e32 v131, v148, v142
	v_min_u32_e32 v148, v148, v142
	v_max_u32_e32 v142, v16, v144
	v_min_u32_e32 v16, v16, v144
	v_max_u32_e32 v144, v119, v49
	v_min_u32_e32 v119, v119, v49
	v_max_u32_e32 v49, v152, v147
	v_min_u32_e32 v152, v152, v147
	v_max_u32_e32 v147, v150, v154
	v_min_u32_e32 v150, v150, v154
	v_max_u32_e32 v154, v128, v146
	v_min_u32_e32 v128, v128, v146
	v_max_u32_e32 v146, v145, v131
	v_min_u32_e32 v145, v145, v131
	v_max_u32_e32 v131, v149, v142
	v_min_u32_e32 v149, v149, v142
	v_max_u32_e32 v142, v143, v148
	v_min_u32_e32 v143, v143, v148
	v_max_u32_e32 v148, v151, v16
	v_min_u32_e32 v151, v151, v16
	v_max_u32_e32 v16, v144, v147
	v_min_u32_e32 v144, v144, v147
	v_max_u32_e32 v147, v49, v154
	v_min_u32_e32 v49, v49, v154
	v_max_u32_e32 v154, v119, v150
	v_min_u32_e32 v119, v119, v150
	v_max_u32_e32 v150, v152, v128
	v_min_u32_e32 v152, v152, v128
	v_max_u32_e32 v128, v146, v131
	v_min_u32_e32 v146, v146, v131
	v_max_u32_e32 v131, v145, v149
	v_min_u32_e32 v145, v145, v149
	v_max_u32_e32 v149, v142, v148
	v_min_u32_e32 v142, v142, v148
	v_max_u32_e32 v148, v143, v151
	v_min_u32_e32 v143, v143, v151
	v_max_u32_e32 v151, v16, v147
	v_min_u32_e32 v16, v16, v147
	v_max_u32_e32 v147, v144, v49
	v_min_u32_e32 v144, v144, v49
	v_max_u32_e32 v49, v154, v150
	v_min_u32_e32 v154, v154, v150
	v_max_u32_e32 v150, v119, v152
	v_min_u32_e32 v119, v119, v152
	ds_bpermute_b32 v156, v188, v128
	ds_bpermute_b32 v153, v188, v146
	ds_bpermute_b32 v158, v188, v131
	ds_bpermute_b32 v155, v188, v145
	ds_bpermute_b32 v160, v188, v149
	ds_bpermute_b32 v157, v188, v142
	ds_bpermute_b32 v162, v188, v148
	ds_bpermute_b32 v159, v188, v143
	ds_bpermute_b32 v164, v188, v151
	ds_bpermute_b32 v161, v188, v16
	ds_bpermute_b32 v166, v188, v147
	ds_bpermute_b32 v163, v188, v144
	ds_bpermute_b32 v168, v188, v49
	ds_bpermute_b32 v165, v188, v154
	ds_bpermute_b32 v170, v188, v150
	ds_bpermute_b32 v167, v188, v119
	s_waitcnt lgkmcnt(0)
; #define MFMA32(a, b, c) __builtin_amdgcn_mfma_f32_32x32x16_bf16((a), (b), (c), 0, 0, 0)
; DI void peer_half_topk(const bf16_t* qrow  , const bf16_t* subk  , int hi, int lane, LAS unsigned* ltop) {
;     ...
;         for (int kk = 0; kk < 8; ++kk) {
;             const bf16x8 af = *(const bf16x8*)(subk + (size_t)(rt * 32) * 128 + kk * 16);
;             const bf16x8 bf = *(const bf16x8*)(qrow + kk * 16);
;             acc = MFMA32(af, bf, acc);
;     ...
;         ltop[k * 64 + lane] = mx;
	v_max_u32_e32 v128, v128, v167
	v_max_u32_e32 v146, v146, v170
	v_max_u32_e32 v131, v131, v165
	v_max_u32_e32 v145, v145, v168
	v_max_u32_e32 v149, v149, v163
	v_max_u32_e32 v142, v142, v166
	v_max_u32_e32 v148, v148, v161
	v_max_u32_e32 v143, v143, v164
	v_max_u32_e32 v151, v151, v159
	v_max_u32_e32 v16, v16, v162
	v_max_u32_e32 v147, v147, v157
	v_max_u32_e32 v144, v144, v160
	v_max_u32_e32 v49, v49, v155
	v_max_u32_e32 v154, v154, v158
	v_max_u32_e32 v150, v150, v153
	v_max_u32_e32 v119, v119, v156
	v_max_u32_e32 v152, v128, v151
	v_min_u32_e32 v128, v128, v151
	v_max_u32_e32 v151, v146, v16
	v_min_u32_e32 v146, v146, v16
	v_max_u32_e32 v16, v131, v147
	v_min_u32_e32 v131, v131, v147
	v_max_u32_e32 v147, v145, v144
	v_min_u32_e32 v145, v145, v144
	v_max_u32_e32 v144, v149, v49
	v_min_u32_e32 v149, v149, v49
	v_max_u32_e32 v49, v142, v154
	v_min_u32_e32 v142, v142, v154
	v_max_u32_e32 v154, v148, v150
	v_min_u32_e32 v148, v148, v150
	v_max_u32_e32 v150, v143, v119
	v_min_u32_e32 v143, v143, v119
	v_max_u32_e32 v119, v152, v144
	v_min_u32_e32 v152, v152, v144
	v_max_u32_e32 v144, v151, v49
	v_min_u32_e32 v151, v151, v49
	v_max_u32_e32 v49, v16, v154
	v_min_u32_e32 v16, v16, v154
	v_max_u32_e32 v154, v147, v150
	v_min_u32_e32 v147, v147, v150
	v_max_u32_e32 v150, v128, v149
	v_min_u32_e32 v128, v128, v149
	v_max_u32_e32 v149, v146, v142
	v_min_u32_e32 v146, v146, v142
	v_max_u32_e32 v142, v131, v148
	v_min_u32_e32 v131, v131, v148
	v_max_u32_e32 v148, v145, v143
	v_min_u32_e32 v145, v145, v143
	v_max_u32_e32 v143, v119, v49
	v_min_u32_e32 v119, v119, v49
	v_max_u32_e32 v49, v144, v154
	v_min_u32_e32 v144, v144, v154
	v_max_u32_e32 v154, v152, v16
	v_min_u32_e32 v152, v152, v16
	v_max_u32_e32 v16, v151, v147
	v_min_u32_e32 v151, v151, v147
	v_max_u32_e32 v147, v150, v142
	v_min_u32_e32 v150, v150, v142
	v_max_u32_e32 v142, v149, v148
	v_min_u32_e32 v149, v149, v148
	v_max_u32_e32 v148, v128, v131
	v_min_u32_e32 v128, v128, v131
	v_max_u32_e32 v131, v146, v145
	v_min_u32_e32 v146, v146, v145
	v_max_u32_e32 v145, v143, v49
	v_min_u32_e32 v143, v143, v49
	v_max_u32_e32 v49, v119, v144
	v_min_u32_e32 v119, v119, v144
	v_max_u32_e32 v144, v154, v16
	v_min_u32_e32 v154, v154, v16
	v_max_u32_e32 v16, v152, v151
	v_min_u32_e32 v152, v152, v151
	v_max_u32_e32 v151, v147, v142
	v_min_u32_e32 v147, v147, v142
	v_max_u32_e32 v142, v150, v149
	v_min_u32_e32 v150, v150, v149
	v_max_u32_e32 v149, v148, v131
	v_min_u32_e32 v148, v148, v131
	v_max_u32_e32 v131, v128, v146
	v_min_u32_e32 v128, v128, v146
	ds_write_b32 v216, v145
	ds_write_b32 v216, v143 offset:256
	ds_write_b32 v216, v49 offset:512
	ds_write_b32 v216, v119 offset:768
	ds_write_b32 v216, v144 offset:1024
	ds_write_b32 v216, v154 offset:1280
	ds_write_b32 v216, v16 offset:1536
	ds_write_b32 v216, v152 offset:1792
	ds_write_b32 v216, v151 offset:2048
	ds_write_b32 v216, v147 offset:2304
	ds_write_b32 v216, v142 offset:2560
	ds_write_b32 v216, v150 offset:2816
	ds_write_b32 v216, v149 offset:3072
	ds_write_b32 v216, v148 offset:3328
	ds_write_b32 v216, v131 offset:3584
	ds_write_b32 v216, v128 offset:3840
	v_mov_b64_e32 v[186:187], v[120:121]
	s_mov_b32 s8, 0
	global_load_dwordx4 v[220:223], v[186:187], off
	global_load_dwordx4 v[44:47], v[140:141], off offset:256
	global_load_dwordx4 v[236:239], v[186:187], off offset:32
	global_load_dwordx4 v[40:43], v[140:141], off offset:288
	global_load_dwordx4 v[248:251], v[186:187], off offset:64
	global_load_dwordx4 v[36:39], v[140:141], off offset:320
	global_load_dwordx4 v[180:183], v[186:187], off offset:96
	global_load_dwordx4 v[32:35], v[140:141], off offset:352
	s_waitcnt vmcnt(6)
	v_mfma_f32_32x32x16_bf16 v[0:15], v[220:223], v[44:47], 0
	global_load_dwordx4 v[220:223], v[186:187], off offset:128
	global_load_dwordx4 v[28:31], v[140:141], off offset:384
	s_waitcnt vmcnt(6)
	v_mfma_f32_32x32x16_bf16 v[0:15], v[236:239], v[40:43], v[0:15]
	global_load_dwordx4 v[236:239], v[186:187], off offset:160
	global_load_dwordx4 v[20:23], v[140:141], off offset:416
	s_waitcnt vmcnt(6)
	v_mfma_f32_32x32x16_bf16 v[0:15], v[248:251], v[36:39], v[0:15]
	global_load_dwordx4 v[248:251], v[186:187], off offset:192
	global_load_dwordx4 v[24:27], v[140:141], off offset:448
	s_waitcnt vmcnt(6)
	v_mfma_f32_32x32x16_bf16 v[0:15], v[180:183], v[32:35], v[0:15]
	global_load_dwordx4 v[180:183], v[186:187], off offset:224
	global_load_dwordx4 v[16:19], v[140:141], off offset:480
	s_waitcnt vmcnt(6)
	v_mfma_f32_32x32x16_bf16 v[0:15], v[220:223], v[28:31], v[0:15]
	s_waitcnt vmcnt(4)
	v_mfma_f32_32x32x16_bf16 v[0:15], v[236:239], v[20:23], v[0:15]
	s_waitcnt vmcnt(2)
	v_mfma_f32_32x32x16_bf16 v[0:15], v[248:251], v[24:27], v[0:15]
	s_waitcnt vmcnt(0)
; #define MFMA32(a, b, c) __builtin_amdgcn_mfma_f32_32x32x16_bf16((a), (b), (c), 0, 0, 0)
; DI int crow(int r, int hi) { return (r & 3) + 8 * (r >> 2) + 4 * hi; }
; DI unsigned ordf(float f) { const unsigned u = __builtin_bit_cast(unsigned, f); return (u & 0x80000000u) ? ~u : (u | 0x80000000u); }
; DI void peer_half_topk(const bf16_t* qrow  , const bf16_t* subk  , int hi, int lane, LAS unsigned* ltop) {
;     ...
;         for (int kk = 0; kk < 8; ++kk) {
;             const bf16x8 af = *(const bf16x8*)(subk + (size_t)(rt * 32) * 128 + kk * 16);
;             const bf16x8 bf = *(const bf16x8*)(qrow + kk * 16);
;             acc = MFMA32(af, bf, acc);
;         }
; #pragma unroll
;         for (int r = 0; r < 16; ++r) { const int n = rt * 32 + crow(r, hi); keys[rt * 16 + r] = (ordf(acc[r]) & ~0x7Fu) | (unsigned)(127 - n); }
	v_mfma_f32_32x32x16_bf16 v[0:15], v[180:183], v[16:19], v[0:15]
	s_nop 11
	v_and_b32_e32 v141, 0x7fffffff, v1
	v_and_b32_e32 v140, 0x7fffffff, v0
	v_xor_b32_e32 v49, -1, v1
	v_xor_b32_e32 v119, -1, v0
	v_pk_add_f32 v[140:141], v[140:141], 0 neg_lo:[1,1] neg_hi:[1,1]
	v_cmp_gt_i32_e32 vcc, 0, v0
	v_cmp_gt_i32_e64 s[0:1], 0, v1
	v_xor_b32_e32 v131, -1, v2
	v_cndmask_b32_e32 v1, v140, v119, vcc
	v_cndmask_b32_e64 v0, v141, v49, s[0:1]
	v_and_b32_e32 v0, 0xffffff80, v0
	v_and_b32_e32 v1, 0xffffff80, v1
	v_add_u32_e32 v49, v0, v51
	v_add_u32_e32 v128, v1, v56
	v_and_b32_e32 v1, 0x7fffffff, v3
	v_and_b32_e32 v0, 0x7fffffff, v2
	v_xor_b32_e32 v119, -1, v3
	v_pk_add_f32 v[0:1], v[0:1], 0 neg_lo:[1,1] neg_hi:[1,1]
	v_cmp_gt_i32_e32 vcc, 0, v2
	v_cmp_gt_i32_e64 s[0:1], 0, v3
	v_xor_b32_e32 v2, -1, v5
	v_cndmask_b32_e32 v0, v0, v131, vcc
	v_cndmask_b32_e64 v1, v1, v119, s[0:1]
	v_and_b32_e32 v1, 0xffffff80, v1
	v_and_b32_e32 v0, 0xffffff80, v0
	v_add_u32_e32 v119, v1, v57
	v_add_u32_e32 v140, v0, v58
	v_and_b32_e32 v1, 0x7fffffff, v5
	v_and_b32_e32 v0, 0x7fffffff, v4
	v_xor_b32_e32 v3, -1, v4
	v_pk_add_f32 v[0:1], v[0:1], 0 neg_lo:[1,1] neg_hi:[1,1]
	v_cmp_gt_i32_e32 vcc, 0, v4
	v_cmp_gt_i32_e64 s[0:1], 0, v5
	s_nop 0
	v_cndmask_b32_e32 v0, v0, v3, vcc
	v_cndmask_b32_e64 v1, v1, v2, s[0:1]
	v_and_b32_e32 v1, 0xffffff80, v1
	v_and_b32_e32 v0, 0xffffff80, v0
	v_add_u32_e32 v131, v1, v59
	v_add_u32_e32 v142, v0, v60
	v_and_b32_e32 v1, 0x7fffffff, v7
	v_and_b32_e32 v0, 0x7fffffff, v6
	v_xor_b32_e32 v2, -1, v7
	v_xor_b32_e32 v3, -1, v6
	v_pk_add_f32 v[0:1], v[0:1], 0 neg_lo:[1,1] neg_hi:[1,1]
	v_cmp_gt_i32_e32 vcc, 0, v6
	v_cmp_gt_i32_e64 s[0:1], 0, v7
	s_nop 0
	v_cndmask_b32_e32 v0, v0, v3, vcc
	v_cndmask_b32_e64 v1, v1, v2, s[0:1]
	v_and_b32_e32 v1, 0xffffff80, v1
	v_and_b32_e32 v0, 0xffffff80, v0
	v_add_u32_e32 v141, v1, v61
	v_add_u32_e32 v144, v0, v62
	v_and_b32_e32 v1, 0x7fffffff, v9
	v_and_b32_e32 v0, 0x7fffffff, v8
	v_xor_b32_e32 v2, -1, v9
	v_xor_b32_e32 v3, -1, v8
	v_pk_add_f32 v[0:1], v[0:1], 0 neg_lo:[1,1] neg_hi:[1,1]
	v_cmp_gt_i32_e32 vcc, 0, v8
	v_cmp_gt_i32_e64 s[0:1], 0, v9
	s_nop 0
	v_cndmask_b32_e32 v0, v0, v3, vcc
	v_cndmask_b32_e64 v1, v1, v2, s[0:1]
	v_and_b32_e32 v1, 0xffffff80, v1
	v_and_b32_e32 v0, 0xffffff80, v0
	v_add_u32_e32 v143, v1, v63
	v_add_u32_e32 v146, v0, v64
	v_and_b32_e32 v1, 0x7fffffff, v11
	v_and_b32_e32 v0, 0x7fffffff, v10
	v_xor_b32_e32 v2, -1, v11
	v_xor_b32_e32 v3, -1, v10
	v_pk_add_f32 v[0:1], v[0:1], 0 neg_lo:[1,1] neg_hi:[1,1]
	v_cmp_gt_i32_e32 vcc, 0, v10
	v_cmp_gt_i32_e64 s[0:1], 0, v11
	s_nop 0
	v_cndmask_b32_e32 v0, v0, v3, vcc
	v_cndmask_b32_e64 v1, v1, v2, s[0:1]
	v_and_b32_e32 v1, 0xffffff80, v1
	v_and_b32_e32 v0, 0xffffff80, v0
	v_add_u32_e32 v145, v1, v65
	v_add_u32_e32 v148, v0, v66
	v_and_b32_e32 v1, 0x7fffffff, v13
	v_and_b32_e32 v0, 0x7fffffff, v12
	v_xor_b32_e32 v2, -1, v13
	v_xor_b32_e32 v3, -1, v12
	v_pk_add_f32 v[0:1], v[0:1], 0 neg_lo:[1,1] neg_hi:[1,1]
	v_cmp_gt_i32_e32 vcc, 0, v12
	v_cmp_gt_i32_e64 s[0:1], 0, v13
	s_nop 0
	v_cndmask_b32_e32 v0, v0, v3, vcc
	v_cndmask_b32_e64 v1, v1, v2, s[0:1]
	v_and_b32_e32 v1, 0xffffff80, v1
	v_and_b32_e32 v0, 0xffffff80, v0
	v_add_u32_e32 v147, v1, v67
	v_add_u32_e32 v150, v0, v68
	v_and_b32_e32 v1, 0x7fffffff, v15
	v_and_b32_e32 v0, 0x7fffffff, v14
	v_xor_b32_e32 v2, -1, v15
	v_pk_add_f32 v[0:1], v[0:1], 0 neg_lo:[1,1] neg_hi:[1,1]
	v_cmp_gt_i32_e64 s[0:1], 0, v15
	v_xor_b32_e32 v3, -1, v14
	v_cmp_gt_i32_e32 vcc, 0, v14
	v_cndmask_b32_e64 v1, v1, v2, s[0:1]
	s_movk_i32 s0, 0x2000
	v_cndmask_b32_e32 v0, v0, v3, vcc
	v_add_co_u32_e32 v158, vcc, s0, v186
	v_and_b32_e32 v1, 0xffffff80, v1
	v_and_b32_e32 v0, 0xffffff80, v0
	v_addc_co_u32_e32 v159, vcc, 0, v187, vcc
	v_add_u32_e32 v149, v1, v69
	v_add_u32_e32 v152, v0, v70
	global_load_dwordx4 v[220:223], v[158:159], off
	global_load_dwordx4 v[236:239], v[158:159], off offset:32
	global_load_dwordx4 v[248:251], v[158:159], off offset:64
	global_load_dwordx4 v[180:183], v[158:159], off offset:96
	s_waitcnt vmcnt(3)
	v_mfma_f32_32x32x16_bf16 v[0:15], v[220:223], v[44:47], 0
	global_load_dwordx4 v[220:223], v[158:159], off offset:128
	s_waitcnt vmcnt(3)
	v_mfma_f32_32x32x16_bf16 v[0:15], v[236:239], v[40:43], v[0:15]
	global_load_dwordx4 v[236:239], v[158:159], off offset:160
	s_waitcnt vmcnt(3)
	v_mfma_f32_32x32x16_bf16 v[0:15], v[248:251], v[36:39], v[0:15]
	global_load_dwordx4 v[248:251], v[158:159], off offset:192
	s_waitcnt vmcnt(3)
	v_mfma_f32_32x32x16_bf16 v[0:15], v[180:183], v[32:35], v[0:15]
	global_load_dwordx4 v[180:183], v[158:159], off offset:224
	s_waitcnt vmcnt(3)
	v_mfma_f32_32x32x16_bf16 v[0:15], v[220:223], v[28:31], v[0:15]
	s_waitcnt vmcnt(2)
	v_mfma_f32_32x32x16_bf16 v[0:15], v[236:239], v[20:23], v[0:15]
	s_waitcnt vmcnt(1)
	v_mfma_f32_32x32x16_bf16 v[0:15], v[248:251], v[24:27], v[0:15]
	s_waitcnt vmcnt(0)
; #define MFMA32(a, b, c) __builtin_amdgcn_mfma_f32_32x32x16_bf16((a), (b), (c), 0, 0, 0)
; DI int crow(int r, int hi) { return (r & 3) + 8 * (r >> 2) + 4 * hi; }
; DI unsigned ordf(float f) { const unsigned u = __builtin_bit_cast(unsigned, f); return (u & 0x80000000u) ? ~u : (u | 0x80000000u); }
; DI void peer_half_topk(const bf16_t* qrow  , const bf16_t* subk  , int hi, int lane, LAS unsigned* ltop) {
;     ...
;         for (int kk = 0; kk < 8; ++kk) {
;             const bf16x8 af = *(const bf16x8*)(subk + (size_t)(rt * 32) * 128 + kk * 16);
;             const bf16x8 bf = *(const bf16x8*)(qrow + kk * 16);
;             acc = MFMA32(af, bf, acc);
;         }
; #pragma unroll
;         for (int r = 0; r < 16; ++r) { const int n = rt * 32 + crow(r, hi); keys[rt * 16 + r] = (ordf(acc[r]) & ~0x7Fu) | (unsigned)(127 - n); }
	v_mfma_f32_32x32x16_bf16 v[0:15], v[180:183], v[16:19], v[0:15]
	s_nop 11
	v_and_b32_e32 v155, 0x7fffffff, v1
	v_and_b32_e32 v154, 0x7fffffff, v0
	v_xor_b32_e32 v151, -1, v1
	v_xor_b32_e32 v153, -1, v0
	v_pk_add_f32 v[154:155], v[154:155], 0 neg_lo:[1,1] neg_hi:[1,1]
	v_cmp_gt_i32_e32 vcc, 0, v0
	v_cmp_gt_i32_e64 s[0:1], 0, v1
	s_nop 0
	v_cndmask_b32_e32 v1, v154, v153, vcc
	v_cndmask_b32_e64 v0, v155, v151, s[0:1]
	v_and_b32_e32 v0, 0xffffff80, v0
	v_and_b32_e32 v1, 0xffffff80, v1
	v_add_u32_e32 v151, v0, v71
	v_add_u32_e32 v154, v1, v72
	v_and_b32_e32 v1, 0x7fffffff, v3
	v_and_b32_e32 v0, 0x7fffffff, v2
	v_xor_b32_e32 v153, -1, v3
	v_xor_b32_e32 v155, -1, v2
	v_pk_add_f32 v[0:1], v[0:1], 0 neg_lo:[1,1] neg_hi:[1,1]
	v_cmp_gt_i32_e32 vcc, 0, v2
	v_cmp_gt_i32_e64 s[0:1], 0, v3
	v_xor_b32_e32 v2, -1, v5
	v_cndmask_b32_e32 v0, v0, v155, vcc
	v_cndmask_b32_e64 v1, v1, v153, s[0:1]
	v_and_b32_e32 v1, 0xffffff80, v1
	v_and_b32_e32 v0, 0xffffff80, v0
	v_add_u32_e32 v153, v1, v73
	v_add_u32_e32 v156, v0, v74
	v_and_b32_e32 v1, 0x7fffffff, v5
	v_and_b32_e32 v0, 0x7fffffff, v4
	v_xor_b32_e32 v3, -1, v4
	v_pk_add_f32 v[0:1], v[0:1], 0 neg_lo:[1,1] neg_hi:[1,1]
	v_cmp_gt_i32_e32 vcc, 0, v4
	v_cmp_gt_i32_e64 s[0:1], 0, v5
	s_nop 0
	v_cndmask_b32_e32 v0, v0, v3, vcc
	v_cndmask_b32_e64 v1, v1, v2, s[0:1]
	v_and_b32_e32 v1, 0xffffff80, v1
	v_and_b32_e32 v0, 0xffffff80, v0
	v_add_u32_e32 v155, v1, v75
	v_add_u32_e32 v158, v0, v76
	v_and_b32_e32 v1, 0x7fffffff, v7
	v_and_b32_e32 v0, 0x7fffffff, v6
	v_xor_b32_e32 v2, -1, v7
	v_xor_b32_e32 v3, -1, v6
	v_pk_add_f32 v[0:1], v[0:1], 0 neg_lo:[1,1] neg_hi:[1,1]
	v_cmp_gt_i32_e32 vcc, 0, v6
	v_cmp_gt_i32_e64 s[0:1], 0, v7
	s_nop 0
	v_cndmask_b32_e32 v0, v0, v3, vcc
	v_cndmask_b32_e64 v1, v1, v2, s[0:1]
	v_and_b32_e32 v1, 0xffffff80, v1
	v_and_b32_e32 v0, 0xffffff80, v0
	v_add_u32_e32 v157, v1, v77
	v_add_u32_e32 v160, v0, v78
	v_and_b32_e32 v1, 0x7fffffff, v9
	v_and_b32_e32 v0, 0x7fffffff, v8
	v_xor_b32_e32 v2, -1, v9
	v_xor_b32_e32 v3, -1, v8
	v_pk_add_f32 v[0:1], v[0:1], 0 neg_lo:[1,1] neg_hi:[1,1]
	v_cmp_gt_i32_e32 vcc, 0, v8
	v_cmp_gt_i32_e64 s[0:1], 0, v9
	s_nop 0
	v_cndmask_b32_e32 v0, v0, v3, vcc
	v_cndmask_b32_e64 v1, v1, v2, s[0:1]
	v_and_b32_e32 v1, 0xffffff80, v1
	v_and_b32_e32 v0, 0xffffff80, v0
	v_add_u32_e32 v159, v1, v79
	v_add_u32_e32 v162, v0, v80
	v_and_b32_e32 v1, 0x7fffffff, v11
	v_and_b32_e32 v0, 0x7fffffff, v10
	v_xor_b32_e32 v2, -1, v11
	v_xor_b32_e32 v3, -1, v10
	v_pk_add_f32 v[0:1], v[0:1], 0 neg_lo:[1,1] neg_hi:[1,1]
	v_cmp_gt_i32_e32 vcc, 0, v10
	v_cmp_gt_i32_e64 s[0:1], 0, v11
	s_nop 0
	v_cndmask_b32_e32 v0, v0, v3, vcc
	v_cndmask_b32_e64 v1, v1, v2, s[0:1]
	v_and_b32_e32 v1, 0xffffff80, v1
	v_and_b32_e32 v0, 0xffffff80, v0
	v_add_u32_e32 v161, v1, v81
	v_add_u32_e32 v164, v0, v82
	v_and_b32_e32 v1, 0x7fffffff, v13
	v_and_b32_e32 v0, 0x7fffffff, v12
	v_xor_b32_e32 v2, -1, v13
	v_xor_b32_e32 v3, -1, v12
	v_pk_add_f32 v[0:1], v[0:1], 0 neg_lo:[1,1] neg_hi:[1,1]
	v_cmp_gt_i32_e32 vcc, 0, v12
	v_cmp_gt_i32_e64 s[0:1], 0, v13
	s_nop 0
	v_cndmask_b32_e32 v0, v0, v3, vcc
	v_cndmask_b32_e64 v1, v1, v2, s[0:1]
	v_and_b32_e32 v1, 0xffffff80, v1
	v_and_b32_e32 v0, 0xffffff80, v0
	v_add_u32_e32 v163, v1, v83
	v_add_u32_e32 v166, v0, v84
	v_and_b32_e32 v1, 0x7fffffff, v15
	v_and_b32_e32 v0, 0x7fffffff, v14
	v_xor_b32_e32 v2, -1, v15
	v_pk_add_f32 v[0:1], v[0:1], 0 neg_lo:[1,1] neg_hi:[1,1]
	v_cmp_gt_i32_e64 s[0:1], 0, v15
	v_xor_b32_e32 v3, -1, v14
	v_cmp_gt_i32_e32 vcc, 0, v14
	v_cndmask_b32_e64 v1, v1, v2, s[0:1]
	s_movk_i32 s0, 0x4000
	v_cndmask_b32_e32 v0, v0, v3, vcc
	v_add_co_u32_e32 v174, vcc, s0, v186
	v_and_b32_e32 v1, 0xffffff80, v1
	v_and_b32_e32 v0, 0xffffff80, v0
	v_addc_co_u32_e32 v175, vcc, 0, v187, vcc
	v_add_u32_e32 v165, v1, v85
	v_add_u32_e32 v168, v0, v86
	global_load_dwordx4 v[220:223], v[174:175], off
	global_load_dwordx4 v[236:239], v[174:175], off offset:32
	global_load_dwordx4 v[248:251], v[174:175], off offset:64
	global_load_dwordx4 v[180:183], v[174:175], off offset:96
	s_waitcnt vmcnt(3)
	v_mfma_f32_32x32x16_bf16 v[0:15], v[220:223], v[44:47], 0
	global_load_dwordx4 v[220:223], v[174:175], off offset:128
	s_waitcnt vmcnt(3)
	v_mfma_f32_32x32x16_bf16 v[0:15], v[236:239], v[40:43], v[0:15]
	global_load_dwordx4 v[236:239], v[174:175], off offset:160
	s_waitcnt vmcnt(3)
	v_mfma_f32_32x32x16_bf16 v[0:15], v[248:251], v[36:39], v[0:15]
	global_load_dwordx4 v[248:251], v[174:175], off offset:192
	s_waitcnt vmcnt(3)
	v_mfma_f32_32x32x16_bf16 v[0:15], v[180:183], v[32:35], v[0:15]
	global_load_dwordx4 v[180:183], v[174:175], off offset:224
	s_waitcnt vmcnt(3)
	v_mfma_f32_32x32x16_bf16 v[0:15], v[220:223], v[28:31], v[0:15]
	s_waitcnt vmcnt(2)
	v_mfma_f32_32x32x16_bf16 v[0:15], v[236:239], v[20:23], v[0:15]
	s_waitcnt vmcnt(1)
	v_mfma_f32_32x32x16_bf16 v[0:15], v[248:251], v[24:27], v[0:15]
	s_waitcnt vmcnt(0)
; #define MFMA32(a, b, c) __builtin_amdgcn_mfma_f32_32x32x16_bf16((a), (b), (c), 0, 0, 0)
; DI int crow(int r, int hi) { return (r & 3) + 8 * (r >> 2) + 4 * hi; }
; DI unsigned ordf(float f) { const unsigned u = __builtin_bit_cast(unsigned, f); return (u & 0x80000000u) ? ~u : (u | 0x80000000u); }
; DI void peer_half_topk(const bf16_t* qrow  , const bf16_t* subk  , int hi, int lane, LAS unsigned* ltop) {
;     ...
;         for (int kk = 0; kk < 8; ++kk) {
;             const bf16x8 af = *(const bf16x8*)(subk + (size_t)(rt * 32) * 128 + kk * 16);
;             const bf16x8 bf = *(const bf16x8*)(qrow + kk * 16);
;             acc = MFMA32(af, bf, acc);
;         }
; #pragma unroll
;         for (int r = 0; r < 16; ++r) { const int n = rt * 32 + crow(r, hi); keys[rt * 16 + r] = (ordf(acc[r]) & ~0x7Fu) | (unsigned)(127 - n); }
	v_mfma_f32_32x32x16_bf16 v[0:15], v[180:183], v[16:19], v[0:15]
	s_nop 11
	v_and_b32_e32 v171, 0x7fffffff, v1
	v_and_b32_e32 v170, 0x7fffffff, v0
	v_xor_b32_e32 v167, -1, v1
	v_xor_b32_e32 v169, -1, v0
	v_pk_add_f32 v[170:171], v[170:171], 0 neg_lo:[1,1] neg_hi:[1,1]
	v_cmp_gt_i32_e32 vcc, 0, v0
	v_cmp_gt_i32_e64 s[0:1], 0, v1
	s_nop 0
	v_cndmask_b32_e32 v1, v170, v169, vcc
	v_cndmask_b32_e64 v0, v171, v167, s[0:1]
	v_and_b32_e32 v0, 0xffffff80, v0
	v_and_b32_e32 v1, 0xffffff80, v1
	v_add_u32_e32 v167, v0, v87
	v_add_u32_e32 v170, v1, v88
	v_and_b32_e32 v1, 0x7fffffff, v3
	v_and_b32_e32 v0, 0x7fffffff, v2
	v_xor_b32_e32 v169, -1, v3
	v_xor_b32_e32 v171, -1, v2
	v_pk_add_f32 v[0:1], v[0:1], 0 neg_lo:[1,1] neg_hi:[1,1]
	v_cmp_gt_i32_e32 vcc, 0, v2
	v_cmp_gt_i32_e64 s[0:1], 0, v3
	v_xor_b32_e32 v2, -1, v5
	v_cndmask_b32_e32 v0, v0, v171, vcc
	v_cndmask_b32_e64 v1, v1, v169, s[0:1]
	v_and_b32_e32 v1, 0xffffff80, v1
	v_and_b32_e32 v0, 0xffffff80, v0
	v_add_u32_e32 v169, v1, v89
	v_add_u32_e32 v172, v0, v90
	v_and_b32_e32 v1, 0x7fffffff, v5
	v_and_b32_e32 v0, 0x7fffffff, v4
	v_xor_b32_e32 v3, -1, v4
	v_pk_add_f32 v[0:1], v[0:1], 0 neg_lo:[1,1] neg_hi:[1,1]
	v_cmp_gt_i32_e32 vcc, 0, v4
	v_cmp_gt_i32_e64 s[0:1], 0, v5
	s_nop 0
	v_cndmask_b32_e32 v0, v0, v3, vcc
	v_cndmask_b32_e64 v1, v1, v2, s[0:1]
	v_and_b32_e32 v1, 0xffffff80, v1
	v_and_b32_e32 v0, 0xffffff80, v0
	v_add_u32_e32 v171, v1, v91
	v_add_u32_e32 v174, v0, v92
	v_and_b32_e32 v1, 0x7fffffff, v7
	v_and_b32_e32 v0, 0x7fffffff, v6
	v_xor_b32_e32 v2, -1, v7
	v_xor_b32_e32 v3, -1, v6
	v_pk_add_f32 v[0:1], v[0:1], 0 neg_lo:[1,1] neg_hi:[1,1]
	v_cmp_gt_i32_e32 vcc, 0, v6
	v_cmp_gt_i32_e64 s[0:1], 0, v7
	s_nop 0
	v_cndmask_b32_e32 v0, v0, v3, vcc
	v_cndmask_b32_e64 v1, v1, v2, s[0:1]
	v_and_b32_e32 v1, 0xffffff80, v1
	v_and_b32_e32 v0, 0xffffff80, v0
	v_add_u32_e32 v173, v1, v93
	v_add_u32_e32 v176, v0, v94
	v_and_b32_e32 v1, 0x7fffffff, v9
	v_and_b32_e32 v0, 0x7fffffff, v8
	v_xor_b32_e32 v2, -1, v9
	v_xor_b32_e32 v3, -1, v8
	v_pk_add_f32 v[0:1], v[0:1], 0 neg_lo:[1,1] neg_hi:[1,1]
	v_cmp_gt_i32_e32 vcc, 0, v8
	v_cmp_gt_i32_e64 s[0:1], 0, v9
	s_nop 0
	v_cndmask_b32_e32 v0, v0, v3, vcc
	v_cndmask_b32_e64 v1, v1, v2, s[0:1]
	v_and_b32_e32 v1, 0xffffff80, v1
	v_and_b32_e32 v0, 0xffffff80, v0
	v_add_u32_e32 v175, v1, v95
	v_add_u32_e32 v178, v0, v96
	v_and_b32_e32 v1, 0x7fffffff, v11
	v_and_b32_e32 v0, 0x7fffffff, v10
	v_xor_b32_e32 v2, -1, v11
	v_xor_b32_e32 v3, -1, v10
	v_pk_add_f32 v[0:1], v[0:1], 0 neg_lo:[1,1] neg_hi:[1,1]
	v_cmp_gt_i32_e32 vcc, 0, v10
	v_cmp_gt_i32_e64 s[0:1], 0, v11
	s_nop 0
	v_cndmask_b32_e32 v0, v0, v3, vcc
	v_cndmask_b32_e64 v1, v1, v2, s[0:1]
	v_and_b32_e32 v1, 0xffffff80, v1
	v_and_b32_e32 v0, 0xffffff80, v0
	v_add_u32_e32 v177, v1, v97
	v_add_u32_e32 v180, v0, v98
	v_and_b32_e32 v1, 0x7fffffff, v13
	v_and_b32_e32 v0, 0x7fffffff, v12
	v_xor_b32_e32 v2, -1, v13
	v_xor_b32_e32 v3, -1, v12
	v_pk_add_f32 v[0:1], v[0:1], 0 neg_lo:[1,1] neg_hi:[1,1]
	v_cmp_gt_i32_e32 vcc, 0, v12
	v_cmp_gt_i32_e64 s[0:1], 0, v13
	s_nop 0
	v_cndmask_b32_e32 v0, v0, v3, vcc
	v_cndmask_b32_e64 v1, v1, v2, s[0:1]
	v_and_b32_e32 v1, 0xffffff80, v1
	v_and_b32_e32 v0, 0xffffff80, v0
	v_add_u32_e32 v179, v1, v99
	v_add_u32_e32 v182, v0, v100
	v_and_b32_e32 v1, 0x7fffffff, v15
	v_and_b32_e32 v0, 0x7fffffff, v14
	v_xor_b32_e32 v2, -1, v15
	v_pk_add_f32 v[0:1], v[0:1], 0 neg_lo:[1,1] neg_hi:[1,1]
	v_cmp_gt_i32_e64 s[0:1], 0, v15
	v_xor_b32_e32 v3, -1, v14
	v_cmp_gt_i32_e32 vcc, 0, v14
	v_cndmask_b32_e64 v1, v1, v2, s[0:1]
	s_movk_i32 s0, 0x6000
	v_cndmask_b32_e32 v0, v0, v3, vcc
	v_add_co_u32_e32 v186, vcc, s0, v186
	v_and_b32_e32 v1, 0xffffff80, v1
	v_and_b32_e32 v0, 0xffffff80, v0
	v_addc_co_u32_e32 v187, vcc, 0, v187, vcc
	v_add_u32_e32 v181, v1, v101
	v_add_u32_e32 v184, v0, v102
	global_load_dwordx4 v[220:223], v[186:187], off
	global_load_dwordx4 v[236:239], v[186:187], off offset:32
	global_load_dwordx4 v[248:251], v[186:187], off offset:64
	s_waitcnt vmcnt(2)
	v_mfma_f32_32x32x16_bf16 v[0:15], v[220:223], v[44:47], 0
	global_load_dwordx4 v[220:223], v[186:187], off offset:96
	s_waitcnt vmcnt(2)
	v_mfma_f32_32x32x16_bf16 v[0:15], v[236:239], v[40:43], v[0:15]
	global_load_dwordx4 v[236:239], v[186:187], off offset:128
	s_waitcnt vmcnt(2)
; #define MFMA32(a, b, c) __builtin_amdgcn_mfma_f32_32x32x16_bf16((a), (b), (c), 0, 0, 0)
; DI int crow(int r, int hi) { return (r & 3) + 8 * (r >> 2) + 4 * hi; }
; DI unsigned ordf(float f) { const unsigned u = __builtin_bit_cast(unsigned, f); return (u & 0x80000000u) ? ~u : (u | 0x80000000u); }
; DI void peer_half_topk(const bf16_t* qrow  , const bf16_t* subk  , int hi, int lane, LAS unsigned* ltop) {
;     ...
;         for (int kk = 0; kk < 8; ++kk) {
;             const bf16x8 af = *(const bf16x8*)(subk + (size_t)(rt * 32) * 128 + kk * 16);
;             const bf16x8 bf = *(const bf16x8*)(qrow + kk * 16);
;             acc = MFMA32(af, bf, acc);
;         }
; #pragma unroll
;         for (int r = 0; r < 16; ++r) { const int n = rt * 32 + crow(r, hi); keys[rt * 16 + r] = (ordf(acc[r]) & ~0x7Fu) | (unsigned)(127 - n); }
	v_mfma_f32_32x32x16_bf16 v[0:15], v[248:251], v[36:39], v[0:15]
	global_load_dwordx4 v[248:251], v[186:187], off offset:160
	s_waitcnt vmcnt(2)
	v_mfma_f32_32x32x16_bf16 v[0:15], v[220:223], v[32:35], v[0:15]
	global_load_dwordx4 v[220:223], v[186:187], off offset:192
	s_waitcnt vmcnt(2)
	v_mfma_f32_32x32x16_bf16 v[0:15], v[236:239], v[28:31], v[0:15]
	global_load_dwordx4 v[236:239], v[186:187], off offset:224
	s_waitcnt vmcnt(2)
	v_mfma_f32_32x32x16_bf16 v[0:15], v[248:251], v[20:23], v[0:15]
	s_waitcnt vmcnt(1)
	v_mfma_f32_32x32x16_bf16 v[0:15], v[220:223], v[24:27], v[0:15]
	s_waitcnt vmcnt(0)
	v_mfma_f32_32x32x16_bf16 v[0:15], v[236:239], v[16:19], v[0:15]
	s_nop 11
	v_and_b32_e32 v17, 0x7fffffff, v1
	v_and_b32_e32 v16, 0x7fffffff, v0
	v_xor_b32_e32 v18, -1, v1
	v_xor_b32_e32 v19, -1, v0
	v_pk_add_f32 v[16:17], v[16:17], 0 neg_lo:[1,1] neg_hi:[1,1]
	v_cmp_gt_i32_e32 vcc, 0, v0
	v_cmp_gt_i32_e64 s[0:1], 0, v1
	v_cmp_gt_i32_e64 s[40:41], 0, v15
	v_cndmask_b32_e32 v1, v16, v19, vcc
	v_cndmask_b32_e64 v0, v17, v18, s[0:1]
	v_and_b32_e32 v0, 0xffffff80, v0
	v_and_b32_e32 v16, 0xffffff80, v1
	v_add_u32_e32 v1, v0, v103
	v_add_u32_e32 v0, v16, v104
	v_and_b32_e32 v17, 0x7fffffff, v3
	v_and_b32_e32 v16, 0x7fffffff, v2
	v_xor_b32_e32 v18, -1, v3
	v_xor_b32_e32 v19, -1, v2
	v_pk_add_f32 v[16:17], v[16:17], 0 neg_lo:[1,1] neg_hi:[1,1]
	v_cmp_gt_i32_e32 vcc, 0, v2
	v_cmp_gt_i32_e64 s[0:1], 0, v3
	s_nop 0
	v_cndmask_b32_e32 v3, v16, v19, vcc
	v_cndmask_b32_e64 v2, v17, v18, s[0:1]
	v_and_b32_e32 v2, 0xffffff80, v2
	v_and_b32_e32 v16, 0xffffff80, v3
	v_add_u32_e32 v3, v2, v105
	v_add_u32_e32 v2, v16, v106
	v_and_b32_e32 v17, 0x7fffffff, v5
	v_and_b32_e32 v16, 0x7fffffff, v4
	v_xor_b32_e32 v18, -1, v5
	v_xor_b32_e32 v19, -1, v4
	v_pk_add_f32 v[16:17], v[16:17], 0 neg_lo:[1,1] neg_hi:[1,1]
	v_cmp_gt_i32_e32 vcc, 0, v4
	v_cmp_gt_i32_e64 s[0:1], 0, v5
	s_nop 0
	v_cndmask_b32_e32 v5, v16, v19, vcc
	v_cndmask_b32_e64 v4, v17, v18, s[0:1]
	v_and_b32_e32 v4, 0xffffff80, v4
	v_and_b32_e32 v16, 0xffffff80, v5
	v_add_u32_e32 v5, v4, v107
	v_add_u32_e32 v4, v16, v108
	v_and_b32_e32 v17, 0x7fffffff, v7
	v_and_b32_e32 v16, 0x7fffffff, v6
	v_xor_b32_e32 v18, -1, v7
	v_xor_b32_e32 v19, -1, v6
	v_pk_add_f32 v[16:17], v[16:17], 0 neg_lo:[1,1] neg_hi:[1,1]
	v_cmp_gt_i32_e32 vcc, 0, v6
	v_cmp_gt_i32_e64 s[0:1], 0, v7
	s_nop 0
	v_cndmask_b32_e32 v7, v16, v19, vcc
	v_cndmask_b32_e64 v6, v17, v18, s[0:1]
	v_and_b32_e32 v6, 0xffffff80, v6
	v_and_b32_e32 v16, 0xffffff80, v7
	v_add_u32_e32 v7, v6, v109
	v_add_u32_e32 v6, v16, v110
	v_and_b32_e32 v17, 0x7fffffff, v9
	v_and_b32_e32 v16, 0x7fffffff, v8
	v_xor_b32_e32 v18, -1, v9
	v_xor_b32_e32 v19, -1, v8
	v_pk_add_f32 v[16:17], v[16:17], 0 neg_lo:[1,1] neg_hi:[1,1]
	v_cmp_gt_i32_e32 vcc, 0, v8
	v_cmp_gt_i32_e64 s[0:1], 0, v9
	s_nop 0
	v_cndmask_b32_e32 v9, v16, v19, vcc
	v_cndmask_b32_e64 v8, v17, v18, s[0:1]
	v_and_b32_e32 v8, 0xffffff80, v8
	v_and_b32_e32 v16, 0xffffff80, v9
	v_add_u32_e32 v9, v8, v111
	v_add_u32_e32 v8, v16, v112
	v_and_b32_e32 v17, 0x7fffffff, v11
	v_and_b32_e32 v16, 0x7fffffff, v10
	v_xor_b32_e32 v18, -1, v11
	v_xor_b32_e32 v19, -1, v10
	v_pk_add_f32 v[16:17], v[16:17], 0 neg_lo:[1,1] neg_hi:[1,1]
	v_cmp_gt_i32_e32 vcc, 0, v10
	v_cmp_gt_i32_e64 s[0:1], 0, v11
	s_nop 0
	v_cndmask_b32_e32 v11, v16, v19, vcc
	v_cndmask_b32_e64 v10, v17, v18, s[0:1]
	v_and_b32_e32 v10, 0xffffff80, v10
	v_and_b32_e32 v16, 0xffffff80, v11
	v_add_u32_e32 v11, v10, v113
	v_add_u32_e32 v10, v16, v114
	v_and_b32_e32 v17, 0x7fffffff, v13
	v_and_b32_e32 v16, 0x7fffffff, v12
	v_xor_b32_e32 v18, -1, v13
	v_xor_b32_e32 v19, -1, v12
	v_pk_add_f32 v[16:17], v[16:17], 0 neg_lo:[1,1] neg_hi:[1,1]
	v_cmp_gt_i32_e32 vcc, 0, v12
	v_cmp_gt_i32_e64 s[0:1], 0, v13
	s_nop 0
	v_cndmask_b32_e32 v13, v16, v19, vcc
	v_cndmask_b32_e64 v12, v17, v18, s[0:1]
	v_and_b32_e32 v12, 0xffffff80, v12
	v_and_b32_e32 v16, 0xffffff80, v13
	v_add_u32_e32 v13, v12, v115
	v_add_u32_e32 v12, v16, v116
	v_and_b32_e32 v17, 0x7fffffff, v15
	v_and_b32_e32 v16, 0x7fffffff, v14
	v_xor_b32_e32 v18, -1, v15
	v_xor_b32_e32 v19, -1, v14
	v_pk_add_f32 v[16:17], v[16:17], 0 neg_lo:[1,1] neg_hi:[1,1]
	v_cmp_gt_i32_e32 vcc, 0, v14
	v_cndmask_b32_e64 v14, v17, v18, s[40:41]
	v_and_b32_e32 v14, 0xffffff80, v14
	v_cndmask_b32_e32 v15, v16, v19, vcc
	v_and_b32_e32 v16, 0xffffff80, v15
	v_add_u32_e32 v15, v14, v117
	v_add_u32_e32 v14, v16, v118

; DI void phase_peer_select(const Args& a, int layer, LAS unsigned char* lds) {
;     ...
; #pragma unroll 1
;         for (int k = 0; k < 16; ++k) {
;             unsigned mx = 0u;
; #pragma unroll
;             for (int x = 0; x < 16; ++x)
; #pragma unroll
;                 for (int y = 0; y < 16; ++y)
;                     if ((x + 1) * (y + 1) <= 16) mx = mx > ck[x][y] ? mx : ck[x][y];
; #pragma unroll
;             for (int x = 0; x < 16; ++x)
; #pragma unroll
;                 for (int y = 0; y < 16; ++y)
;                     if ((x + 1) * (y + 1) <= 16) ck[x][y] = ck[x][y] == mx ? 0u : ck[x][y];
.LBB0_46:
	v_mov_b32_e32 v150, 0
	v_mov_b32_e32 v151, 0
	v_mov_b32_e32 v154, 0
	v_mov_b32_e32 v155, 0
	v_mov_b32_e32 v158, 0
	v_mov_b32_e32 v159, 0
	v_mov_b32_e32 v160, 0
	v_mov_b32_e32 v161, 0
	v_mov_b32_e32 v166, 0
	v_mov_b32_e32 v167, 0
	v_mov_b32_e32 v171, 0
	v_mov_b32_e32 v173, 0
	v_mov_b32_e32 v177, 0
	v_mov_b32_e32 v178, 0
	v_max_u32_e32 v182, v49, v119
	v_min_u32_e32 v49, v49, v119
	v_max_u32_e32 v183, v13, v12
	v_min_u32_e32 v13, v13, v12
	v_max_u32_e32 v184, v39, v38
	v_min_u32_e32 v39, v39, v38
	v_max_u32_e32 v189, v19, v18
	v_min_u32_e32 v19, v19, v18
	v_max_u32_e32 v119, v31, v30
	v_min_u32_e32 v31, v31, v30
	v_max_u32_e32 v12, v35, v34
	v_min_u32_e32 v35, v35, v34
	v_max_u32_e32 v38, v41, v40
	v_min_u32_e32 v41, v41, v40
	v_max_u32_e32 v18, v150, v151
	v_min_u32_e32 v150, v150, v151
	v_max_u32_e32 v30, v182, v119
	v_min_u32_e32 v182, v182, v119
	v_max_u32_e32 v34, v183, v12
	v_min_u32_e32 v183, v183, v12
	v_max_u32_e32 v40, v184, v38
	v_min_u32_e32 v184, v184, v38
	v_max_u32_e32 v151, v189, v18
	v_min_u32_e32 v189, v189, v18
	v_max_u32_e32 v119, v49, v31
	v_min_u32_e32 v49, v49, v31
	v_max_u32_e32 v12, v13, v35
	v_min_u32_e32 v13, v13, v35
	v_max_u32_e32 v38, v39, v41
	v_min_u32_e32 v39, v39, v41
	v_max_u32_e32 v18, v19, v150
	v_min_u32_e32 v19, v19, v150
	v_max_u32_e32 v31, v119, v182
	v_min_u32_e32 v119, v119, v182
	v_max_u32_e32 v35, v12, v183
	v_min_u32_e32 v12, v12, v183
	v_max_u32_e32 v41, v38, v184
	v_min_u32_e32 v38, v38, v184
	v_max_u32_e32 v150, v18, v189
	v_min_u32_e32 v18, v18, v189
	v_max_u32_e32 v182, v17, v16
	v_min_u32_e32 v17, v17, v16
	v_max_u32_e32 v183, v21, v20
	v_min_u32_e32 v21, v21, v20
	v_max_u32_e32 v184, v43, v42
	v_min_u32_e32 v43, v43, v42
	v_max_u32_e32 v189, v154, v155
	v_min_u32_e32 v154, v154, v155
	v_max_u32_e32 v16, v9, v8
	v_min_u32_e32 v9, v9, v8
	v_max_u32_e32 v20, v11, v10
	v_min_u32_e32 v11, v11, v10
	v_max_u32_e32 v42, v45, v44
	v_min_u32_e32 v45, v45, v44
	v_max_u32_e32 v155, v158, v159
	v_min_u32_e32 v158, v158, v159
	v_max_u32_e32 v8, v182, v16
	v_min_u32_e32 v182, v182, v16
	v_max_u32_e32 v10, v183, v20
	v_min_u32_e32 v183, v183, v20
	v_max_u32_e32 v44, v184, v42
	v_min_u32_e32 v184, v184, v42
	v_max_u32_e32 v159, v189, v155
	v_min_u32_e32 v189, v189, v155
	v_max_u32_e32 v16, v17, v9
	v_min_u32_e32 v17, v17, v9
	v_max_u32_e32 v20, v21, v11
	v_min_u32_e32 v21, v21, v11
	v_max_u32_e32 v42, v43, v45
	v_min_u32_e32 v43, v43, v45
	v_max_u32_e32 v155, v154, v158
	v_min_u32_e32 v154, v154, v158
	v_max_u32_e32 v9, v16, v182
	v_min_u32_e32 v16, v16, v182
	v_max_u32_e32 v11, v20, v183
	v_min_u32_e32 v20, v20, v183
	v_max_u32_e32 v45, v42, v184
	v_min_u32_e32 v42, v42, v184
	v_max_u32_e32 v158, v155, v189
	v_min_u32_e32 v155, v155, v189
	v_max_u32_e32 v182, v30, v8
	v_min_u32_e32 v30, v30, v8
	v_max_u32_e32 v183, v34, v10
	v_min_u32_e32 v34, v34, v10
	v_max_u32_e32 v184, v40, v44
	v_min_u32_e32 v40, v40, v44
	v_max_u32_e32 v189, v151, v159
	v_min_u32_e32 v151, v151, v159
	v_max_u32_e32 v8, v119, v16
	v_min_u32_e32 v119, v119, v16
	v_max_u32_e32 v10, v12, v20
	v_min_u32_e32 v12, v12, v20
	v_max_u32_e32 v44, v38, v42
	v_min_u32_e32 v38, v38, v42
	v_max_u32_e32 v159, v18, v155
	v_min_u32_e32 v18, v18, v155
	v_max_u32_e32 v16, v8, v30
	v_min_u32_e32 v8, v8, v30
	v_max_u32_e32 v20, v10, v34
	v_min_u32_e32 v10, v10, v34
	v_max_u32_e32 v42, v44, v40
	v_min_u32_e32 v44, v44, v40
	v_max_u32_e32 v155, v159, v151
	v_min_u32_e32 v159, v159, v151
	v_max_u32_e32 v30, v31, v9
	v_min_u32_e32 v31, v31, v9
	v_max_u32_e32 v34, v35, v11
	v_min_u32_e32 v35, v35, v11
	v_max_u32_e32 v40, v41, v45
	v_min_u32_e32 v41, v41, v45
	v_max_u32_e32 v151, v150, v158
	v_min_u32_e32 v150, v150, v158
	v_max_u32_e32 v9, v49, v17
	v_min_u32_e32 v49, v49, v17
	v_max_u32_e32 v11, v13, v21
	v_min_u32_e32 v13, v13, v21
	v_max_u32_e32 v45, v39, v43
	v_min_u32_e32 v39, v39, v43
	v_max_u32_e32 v158, v19, v154
	v_min_u32_e32 v19, v19, v154
	v_max_u32_e32 v17, v9, v31
	v_min_u32_e32 v9, v9, v31
	v_max_u32_e32 v21, v11, v35
	v_min_u32_e32 v11, v11, v35
	v_max_u32_e32 v43, v45, v41
	v_min_u32_e32 v45, v45, v41
	v_max_u32_e32 v154, v158, v150
	v_min_u32_e32 v158, v158, v150
	v_max_u32_e32 v31, v30, v16
	v_min_u32_e32 v30, v30, v16
	v_max_u32_e32 v35, v34, v20
	v_min_u32_e32 v34, v34, v20
	v_max_u32_e32 v41, v40, v42
	v_min_u32_e32 v40, v40, v42
	v_max_u32_e32 v150, v151, v155
	v_min_u32_e32 v151, v151, v155
	v_max_u32_e32 v16, v17, v8
	v_min_u32_e32 v17, v17, v8
	v_max_u32_e32 v20, v21, v10
	v_min_u32_e32 v21, v21, v10
	v_max_u32_e32 v42, v43, v44
	v_min_u32_e32 v43, v43, v44
	v_max_u32_e32 v155, v154, v159
	v_min_u32_e32 v154, v154, v159
	v_max_u32_e32 v8, v9, v119
	v_min_u32_e32 v9, v9, v119
	v_max_u32_e32 v10, v11, v12
	v_min_u32_e32 v11, v11, v12
	v_max_u32_e32 v44, v45, v38
	v_min_u32_e32 v45, v45, v38
	v_max_u32_e32 v159, v158, v18
	v_min_u32_e32 v158, v158, v18
	v_max_u32_e32 v119, v1, v0
	v_min_u32_e32 v1, v1, v0
	v_max_u32_e32 v12, v15, v14
	v_min_u32_e32 v15, v15, v14
	v_max_u32_e32 v38, v47, v46
	v_min_u32_e32 v47, v47, v46
	v_max_u32_e32 v18, v160, v161
	v_min_u32_e32 v160, v160, v161
	v_max_u32_e32 v0, v3, v2
	v_min_u32_e32 v3, v3, v2
	v_max_u32_e32 v14, v37, v36
	v_min_u32_e32 v37, v37, v36
	v_max_u32_e32 v46, v33, v32
	v_min_u32_e32 v33, v33, v32
	v_max_u32_e32 v161, v166, v167
	v_min_u32_e32 v166, v166, v167
	v_max_u32_e32 v2, v119, v0
	v_min_u32_e32 v119, v119, v0
	v_max_u32_e32 v36, v12, v14
	v_min_u32_e32 v12, v12, v14
	v_max_u32_e32 v32, v38, v46
	v_min_u32_e32 v38, v38, v46
	v_max_u32_e32 v167, v18, v161
	v_min_u32_e32 v18, v18, v161
	v_max_u32_e32 v0, v1, v3
	v_min_u32_e32 v1, v1, v3
	v_max_u32_e32 v14, v15, v37
; DI void phase_peer_select(const Args& a, int layer, LAS unsigned char* lds) {
;     ...
; #pragma unroll 1
;         for (int k = 0; k < 16; ++k) {
;             unsigned mx = 0u;
; #pragma unroll
;             for (int x = 0; x < 16; ++x)
; #pragma unroll
;                 for (int y = 0; y < 16; ++y)
;                     if ((x + 1) * (y + 1) <= 16) mx = mx > ck[x][y] ? mx : ck[x][y];
; #pragma unroll
;             for (int x = 0; x < 16; ++x)
; #pragma unroll
;                 for (int y = 0; y < 16; ++y)
;                     if ((x + 1) * (y + 1) <= 16) ck[x][y] = ck[x][y] == mx ? 0u : ck[x][y];
	v_min_u32_e32 v15, v15, v37
	v_max_u32_e32 v46, v47, v33
	v_min_u32_e32 v47, v47, v33
	v_max_u32_e32 v161, v160, v166
	v_min_u32_e32 v160, v160, v166
	v_max_u32_e32 v3, v0, v119
	v_min_u32_e32 v0, v0, v119
	v_max_u32_e32 v37, v14, v12
	v_min_u32_e32 v14, v14, v12
	v_max_u32_e32 v33, v46, v38
	v_min_u32_e32 v46, v46, v38
	v_max_u32_e32 v166, v161, v18
	v_min_u32_e32 v161, v161, v18
	v_max_u32_e32 v119, v5, v4
	v_min_u32_e32 v5, v5, v4
	v_max_u32_e32 v12, v25, v24
	v_min_u32_e32 v25, v25, v24
	v_max_u32_e32 v38, v29, v28
	v_min_u32_e32 v29, v29, v28
	v_max_u32_e32 v18, v171, v173
	v_min_u32_e32 v171, v171, v173
	v_max_u32_e32 v4, v7, v6
	v_min_u32_e32 v7, v7, v6
	v_max_u32_e32 v24, v27, v26
	v_min_u32_e32 v27, v27, v26
	v_max_u32_e32 v28, v23, v22
	v_min_u32_e32 v23, v23, v22
	v_max_u32_e32 v173, v177, v178
	v_min_u32_e32 v177, v177, v178
	v_max_u32_e32 v6, v119, v4
	v_min_u32_e32 v119, v119, v4
	v_max_u32_e32 v26, v12, v24
	v_min_u32_e32 v12, v12, v24
	v_max_u32_e32 v22, v38, v28
	v_min_u32_e32 v38, v38, v28
	v_max_u32_e32 v178, v18, v173
	v_min_u32_e32 v18, v18, v173
	v_max_u32_e32 v4, v5, v7
	v_min_u32_e32 v5, v5, v7
	v_max_u32_e32 v24, v25, v27
	v_min_u32_e32 v25, v25, v27
	v_max_u32_e32 v28, v29, v23
	v_min_u32_e32 v29, v29, v23
	v_max_u32_e32 v173, v171, v177
	v_min_u32_e32 v171, v171, v177
	v_max_u32_e32 v7, v4, v119
	v_min_u32_e32 v4, v4, v119
	v_max_u32_e32 v27, v24, v12
	v_min_u32_e32 v24, v24, v12
	v_max_u32_e32 v23, v28, v38
	v_min_u32_e32 v28, v28, v38
	v_max_u32_e32 v177, v173, v18
	v_min_u32_e32 v173, v173, v18
	v_max_u32_e32 v119, v2, v6
	v_min_u32_e32 v2, v2, v6
	v_max_u32_e32 v12, v36, v26
	v_min_u32_e32 v36, v36, v26
	v_max_u32_e32 v38, v32, v22
	v_min_u32_e32 v32, v32, v22
	v_max_u32_e32 v18, v167, v178
	v_min_u32_e32 v167, v167, v178
	v_max_u32_e32 v6, v0, v4
	v_min_u32_e32 v0, v0, v4
	v_max_u32_e32 v26, v14, v24
	v_min_u32_e32 v14, v14, v24
	v_max_u32_e32 v22, v46, v28
	v_min_u32_e32 v46, v46, v28
	v_max_u32_e32 v178, v161, v173
	v_min_u32_e32 v161, v161, v173
	v_max_u32_e32 v4, v6, v2
	v_min_u32_e32 v6, v6, v2
	v_max_u32_e32 v24, v26, v36
	v_min_u32_e32 v26, v26, v36
	v_max_u32_e32 v28, v22, v32
	v_min_u32_e32 v22, v22, v32
	v_max_u32_e32 v173, v178, v167
	v_min_u32_e32 v178, v178, v167
	v_max_u32_e32 v2, v3, v7
	v_min_u32_e32 v3, v3, v7
	v_max_u32_e32 v36, v37, v27
	v_min_u32_e32 v37, v37, v27
	v_max_u32_e32 v32, v33, v23
	v_min_u32_e32 v33, v33, v23
	v_max_u32_e32 v167, v166, v177
	v_min_u32_e32 v166, v166, v177
	v_max_u32_e32 v7, v1, v5
	v_min_u32_e32 v1, v1, v5
	v_max_u32_e32 v27, v15, v25
	v_min_u32_e32 v15, v15, v25
	v_max_u32_e32 v23, v47, v29
	v_min_u32_e32 v47, v47, v29
	v_max_u32_e32 v177, v160, v171
	v_min_u32_e32 v160, v160, v171
	v_max_u32_e32 v5, v7, v3
	v_min_u32_e32 v7, v7, v3
	v_max_u32_e32 v25, v27, v37
	v_min_u32_e32 v27, v27, v37
	v_max_u32_e32 v29, v23, v33
	v_min_u32_e32 v23, v23, v33
	v_max_u32_e32 v171, v177, v166
	v_min_u32_e32 v177, v177, v166
	v_max_u32_e32 v3, v2, v4
	v_min_u32_e32 v2, v2, v4
	v_max_u32_e32 v37, v36, v24
	v_min_u32_e32 v36, v36, v24
	v_max_u32_e32 v33, v32, v28
	v_min_u32_e32 v32, v32, v28
	v_max_u32_e32 v166, v167, v173
	v_min_u32_e32 v167, v167, v173
	v_max_u32_e32 v4, v5, v6
	v_min_u32_e32 v5, v5, v6
	v_max_u32_e32 v24, v25, v26
	v_min_u32_e32 v25, v25, v26
	v_max_u32_e32 v28, v29, v22
	v_min_u32_e32 v29, v29, v22
	v_max_u32_e32 v173, v171, v178
	v_min_u32_e32 v171, v171, v178
	v_max_u32_e32 v6, v7, v0
	v_min_u32_e32 v7, v7, v0
	v_max_u32_e32 v26, v27, v14
	v_min_u32_e32 v27, v27, v14
	v_max_u32_e32 v22, v23, v46
	v_min_u32_e32 v23, v23, v46
	v_max_u32_e32 v178, v177, v161
	v_min_u32_e32 v177, v177, v161
	v_max_u32_e32 v0, v182, v119
	v_min_u32_e32 v182, v182, v119
	v_max_u32_e32 v14, v183, v12
	v_min_u32_e32 v183, v183, v12
	v_max_u32_e32 v46, v184, v38
	v_min_u32_e32 v184, v184, v38
	v_max_u32_e32 v161, v189, v18
	v_min_u32_e32 v189, v189, v18
	v_max_u32_e32 v119, v17, v5
	v_min_u32_e32 v17, v17, v5
	v_max_u32_e32 v12, v21, v25
	v_min_u32_e32 v21, v21, v25
	v_max_u32_e32 v38, v43, v29
	v_min_u32_e32 v43, v43, v29
	v_max_u32_e32 v18, v154, v171
	v_min_u32_e32 v154, v154, v171
	v_max_u32_e32 v5, v119, v182
	v_min_u32_e32 v119, v119, v182
	v_max_u32_e32 v25, v12, v183
	v_min_u32_e32 v12, v12, v183
	v_max_u32_e32 v29, v38, v184
	v_min_u32_e32 v38, v38, v184
	v_max_u32_e32 v171, v18, v189
	v_min_u32_e32 v18, v18, v189
	v_max_u32_e32 v182, v30, v2
	v_min_u32_e32 v30, v30, v2
	v_max_u32_e32 v183, v34, v36
	v_min_u32_e32 v34, v34, v36
	v_max_u32_e32 v184, v40, v32
	v_min_u32_e32 v40, v40, v32
	v_max_u32_e32 v189, v151, v167
	v_min_u32_e32 v151, v151, v167
	v_max_u32_e32 v2, v9, v7
	v_min_u32_e32 v9, v9, v7
	v_max_u32_e32 v36, v11, v27
	v_min_u32_e32 v11, v11, v27
	v_max_u32_e32 v32, v45, v23
	v_min_u32_e32 v45, v45, v23
	v_max_u32_e32 v167, v158, v177
	v_min_u32_e32 v158, v158, v177
	v_max_u32_e32 v7, v2, v30
	v_min_u32_e32 v2, v2, v30
	v_max_u32_e32 v27, v36, v34
	v_min_u32_e32 v36, v36, v34
	v_max_u32_e32 v23, v32, v40
	v_min_u32_e32 v32, v32, v40
	v_max_u32_e32 v177, v167, v151
	v_min_u32_e32 v167, v167, v151
	v_max_u32_e32 v30, v182, v5
	v_min_u32_e32 v182, v182, v5
	v_max_u32_e32 v34, v183, v25
	v_min_u32_e32 v183, v183, v25
	v_max_u32_e32 v40, v184, v29
	v_min_u32_e32 v184, v184, v29
	v_max_u32_e32 v151, v189, v171
	v_min_u32_e32 v189, v189, v171
	v_max_u32_e32 v5, v7, v119
	v_min_u32_e32 v7, v7, v119
	v_max_u32_e32 v25, v27, v12
	v_min_u32_e32 v27, v27, v12
	v_max_u32_e32 v29, v23, v38
	v_min_u32_e32 v23, v23, v38
	v_max_u32_e32 v171, v177, v18
	v_min_u32_e32 v177, v177, v18
	v_max_u32_e32 v119, v2, v17
	v_min_u32_e32 v2, v2, v17
	v_max_u32_e32 v12, v36, v21
; DI void phase_peer_select(const Args& a, int layer, LAS unsigned char* lds) {
;     ...
; #pragma unroll 1
;         for (int k = 0; k < 16; ++k) {
;             unsigned mx = 0u;
; #pragma unroll
;             for (int x = 0; x < 16; ++x)
; #pragma unroll
;                 for (int y = 0; y < 16; ++y)
;                     if ((x + 1) * (y + 1) <= 16) mx = mx > ck[x][y] ? mx : ck[x][y];
; #pragma unroll
;             for (int x = 0; x < 16; ++x)
; #pragma unroll
;                 for (int y = 0; y < 16; ++y)
;                     if ((x + 1) * (y + 1) <= 16) ck[x][y] = ck[x][y] == mx ? 0u : ck[x][y];
	v_min_u32_e32 v36, v36, v21
	v_max_u32_e32 v38, v32, v43
	v_min_u32_e32 v32, v32, v43
	v_max_u32_e32 v18, v167, v154
	v_min_u32_e32 v167, v167, v154
	v_max_u32_e32 v17, v31, v3
	v_min_u32_e32 v31, v31, v3
	v_max_u32_e32 v21, v35, v37
	v_min_u32_e32 v35, v35, v37
	v_max_u32_e32 v43, v41, v33
	v_min_u32_e32 v41, v41, v33
	v_max_u32_e32 v154, v150, v166
	v_min_u32_e32 v150, v150, v166
	v_max_u32_e32 v3, v8, v6
	v_min_u32_e32 v8, v8, v6
	v_max_u32_e32 v37, v10, v26
	v_min_u32_e32 v10, v10, v26
	v_max_u32_e32 v33, v44, v22
	v_min_u32_e32 v44, v44, v22
	v_max_u32_e32 v166, v159, v178
	v_min_u32_e32 v159, v159, v178
	v_max_u32_e32 v6, v3, v31
	v_min_u32_e32 v3, v3, v31
	v_max_u32_e32 v26, v37, v35
	v_min_u32_e32 v37, v37, v35
	v_max_u32_e32 v22, v33, v41
	v_min_u32_e32 v33, v33, v41
	v_max_u32_e32 v178, v166, v150
	v_min_u32_e32 v166, v166, v150
	v_max_u32_e32 v31, v16, v4
	v_min_u32_e32 v16, v16, v4
	v_max_u32_e32 v35, v20, v24
	v_min_u32_e32 v20, v20, v24
	v_max_u32_e32 v41, v42, v28
	v_min_u32_e32 v42, v42, v28
	v_max_u32_e32 v150, v155, v173
	v_min_u32_e32 v155, v155, v173
	v_max_u32_e32 v4, v49, v1
	v_min_u32_e32 v49, v49, v1
	v_max_u32_e32 v24, v13, v15
	v_min_u32_e32 v13, v13, v15
	v_max_u32_e32 v28, v39, v47
	v_min_u32_e32 v39, v39, v47
	v_max_u32_e32 v173, v19, v160
	v_min_u32_e32 v19, v19, v160
	v_max_u32_e32 v1, v4, v16
	v_min_u32_e32 v4, v4, v16
	v_max_u32_e32 v15, v24, v20
	v_min_u32_e32 v24, v24, v20
	v_max_u32_e32 v47, v28, v42
	v_min_u32_e32 v28, v28, v42
	v_max_u32_e32 v160, v173, v155
	v_min_u32_e32 v173, v173, v155
	v_max_u32_e32 v16, v31, v6
	v_min_u32_e32 v31, v31, v6
	v_max_u32_e32 v20, v35, v26
	v_min_u32_e32 v35, v35, v26
	v_max_u32_e32 v42, v41, v22
	v_min_u32_e32 v41, v41, v22
	v_max_u32_e32 v155, v150, v178
	v_min_u32_e32 v150, v150, v178
	v_max_u32_e32 v6, v1, v3
	v_min_u32_e32 v1, v1, v3
	v_max_u32_e32 v26, v15, v37
	v_min_u32_e32 v15, v15, v37
	v_max_u32_e32 v22, v47, v33
	v_min_u32_e32 v47, v47, v33
	v_max_u32_e32 v178, v160, v166
	v_min_u32_e32 v160, v160, v166
	v_max_u32_e32 v3, v4, v8
	v_min_u32_e32 v4, v4, v8
	v_max_u32_e32 v37, v24, v10
	v_min_u32_e32 v24, v24, v10
	v_max_u32_e32 v33, v28, v44
	v_min_u32_e32 v28, v28, v44
	v_max_u32_e32 v166, v173, v159
	v_min_u32_e32 v173, v173, v159
	v_max_u32_e32 v8, v17, v30
	v_min_u32_e32 v17, v17, v30
	v_max_u32_e32 v10, v21, v34
	v_min_u32_e32 v21, v21, v34
	v_max_u32_e32 v44, v43, v40
	v_min_u32_e32 v43, v43, v40
	v_max_u32_e32 v159, v154, v151
	v_min_u32_e32 v154, v154, v151
	v_max_u32_e32 v30, v16, v182
	v_min_u32_e32 v16, v16, v182
	v_max_u32_e32 v34, v20, v183
	v_min_u32_e32 v20, v20, v183
	v_max_u32_e32 v40, v42, v184
	v_min_u32_e32 v42, v42, v184
	v_max_u32_e32 v151, v155, v189
	v_min_u32_e32 v155, v155, v189
	v_max_u32_e32 v182, v31, v5
	v_min_u32_e32 v31, v31, v5
	v_max_u32_e32 v183, v35, v25
	v_min_u32_e32 v35, v35, v25
	v_max_u32_e32 v184, v41, v29
	v_min_u32_e32 v41, v41, v29
	v_max_u32_e32 v189, v150, v171
	v_min_u32_e32 v150, v150, v171
	v_max_u32_e32 v5, v6, v7
	v_min_u32_e32 v6, v6, v7
	v_max_u32_e32 v25, v26, v27
	v_min_u32_e32 v26, v26, v27
	v_max_u32_e32 v29, v22, v23
	v_min_u32_e32 v22, v22, v23
	v_max_u32_e32 v171, v178, v177
	v_min_u32_e32 v178, v178, v177
	v_max_u32_e32 v7, v1, v119
	v_min_u32_e32 v1, v1, v119
	v_max_u32_e32 v27, v15, v12
	v_min_u32_e32 v15, v15, v12
	v_max_u32_e32 v23, v47, v38
	v_min_u32_e32 v47, v47, v38
	v_max_u32_e32 v177, v160, v18
	v_min_u32_e32 v160, v160, v18
	v_max_u32_e32 v119, v3, v2
	v_min_u32_e32 v3, v3, v2
	v_max_u32_e32 v12, v37, v36
	v_min_u32_e32 v37, v37, v36
	v_max_u32_e32 v38, v33, v32
	v_min_u32_e32 v33, v33, v32
	v_max_u32_e32 v18, v166, v167
	v_min_u32_e32 v166, v166, v167
	v_max_u32_e32 v2, v4, v9
	v_min_u32_e32 v4, v4, v9
	v_max_u32_e32 v36, v24, v11
	v_min_u32_e32 v24, v24, v11
	v_max_u32_e32 v32, v28, v45
	v_min_u32_e32 v28, v28, v45
	v_max_u32_e32 v167, v173, v158
	v_min_u32_e32 v173, v173, v158
	v_max_u32_e32 v0, v0, v13
	v_max_u32_e32 v46, v46, v19
	v_max_u32_e32 v8, v8, v24
	v_max_u32_e32 v44, v44, v173
	v_max_u32_e32 v17, v17, v36
	v_max_u32_e32 v43, v43, v167
	v_max_u32_e32 v30, v30, v37
	v_max_u32_e32 v40, v40, v166
	v_max_u32_e32 v16, v16, v12
	v_max_u32_e32 v42, v42, v18
	v_max_u32_e32 v182, v182, v15
	v_max_u32_e32 v184, v184, v160
	v_max_u32_e32 v31, v31, v27
	v_max_u32_e32 v41, v41, v177
	v_max_u32_e32 v5, v5, v26
	v_max_u32_e32 v29, v29, v178
	v_max_u32_e32 v6, v6, v25
	v_max_u32_e32 v22, v22, v171
	v_max_u32_e32 v7, v7, v35
	v_max_u32_e32 v23, v23, v150
	v_max_u32_e32 v1, v1, v183
	v_max_u32_e32 v47, v47, v189
	v_max_u32_e32 v119, v119, v20
	v_max_u32_e32 v38, v38, v155
	v_max_u32_e32 v3, v3, v34
	v_max_u32_e32 v33, v33, v151
	v_max_u32_e32 v2, v2, v21
	v_max_u32_e32 v32, v32, v154
	v_max_u32_e32 v4, v4, v10
	v_max_u32_e32 v28, v28, v159
	v_max_u32_e32 v49, v49, v14
	v_max_u32_e32 v39, v39, v161
	v_max_u32_e32 v9, v0, v6
	v_min_u32_e32 v0, v0, v6
	v_max_u32_e32 v45, v46, v22
	v_min_u32_e32 v46, v46, v22
	v_max_u32_e32 v6, v8, v7
	v_min_u32_e32 v8, v8, v7
	v_max_u32_e32 v22, v44, v23
	v_min_u32_e32 v44, v44, v23
	v_max_u32_e32 v7, v17, v1
	v_min_u32_e32 v17, v17, v1
	v_max_u32_e32 v23, v43, v47
	v_min_u32_e32 v43, v43, v47
	v_max_u32_e32 v1, v30, v119
	v_min_u32_e32 v30, v30, v119
	v_max_u32_e32 v47, v40, v38
	v_min_u32_e32 v40, v40, v38
	v_max_u32_e32 v119, v16, v3
	v_min_u32_e32 v16, v16, v3
	v_max_u32_e32 v38, v42, v33
	v_min_u32_e32 v42, v42, v33
	v_max_u32_e32 v3, v182, v2
	v_min_u32_e32 v182, v182, v2
	v_max_u32_e32 v33, v184, v32
	v_min_u32_e32 v184, v184, v32
	v_max_u32_e32 v2, v31, v4
	v_min_u32_e32 v31, v31, v4
	v_max_u32_e32 v32, v41, v28
	v_min_u32_e32 v41, v41, v28
; DI void phase_peer_select(const Args& a, int layer, LAS unsigned char* lds) {
;     ...
; #pragma unroll 1
;         for (int k = 0; k < 16; ++k) {
;             unsigned mx = 0u;
; #pragma unroll
;             for (int x = 0; x < 16; ++x)
; #pragma unroll
;                 for (int y = 0; y < 16; ++y)
;                     if ((x + 1) * (y + 1) <= 16) mx = mx > ck[x][y] ? mx : ck[x][y];
; #pragma unroll
;             for (int x = 0; x < 16; ++x)
; #pragma unroll
;                 for (int y = 0; y < 16; ++y)
;                     if ((x + 1) * (y + 1) <= 16) ck[x][y] = ck[x][y] == mx ? 0u : ck[x][y];
;             const int ci = 255 - (int)(mx & 0xFFu);
;             const int e = (int)(127u - (lt1[(ci >> 4) * 64 + lane] & 0x7Fu)) * 128 + (int)(127u - (lt2[(ci & 15) * 64 + lane] & 0x7Fu));
;             const float ek = __expf(unordf(mx & ~0xFFu) - scmax);
;             sum += ek;
;             if (hi == 0) { ip[k] = e; gp[k] = ek; }
	v_max_u32_e32 v4, v5, v49
	v_min_u32_e32 v5, v5, v49
	v_max_u32_e32 v28, v29, v39
	v_min_u32_e32 v29, v29, v39
	v_max_u32_e32 v49, v9, v119
	v_min_u32_e32 v9, v9, v119
	v_max_u32_e32 v39, v45, v38
	v_min_u32_e32 v45, v45, v38
	v_max_u32_e32 v119, v6, v3
	v_min_u32_e32 v6, v6, v3
	v_max_u32_e32 v38, v22, v33
	v_min_u32_e32 v22, v22, v33
	v_max_u32_e32 v3, v7, v2
	v_min_u32_e32 v7, v7, v2
	v_max_u32_e32 v33, v23, v32
	v_min_u32_e32 v23, v23, v32
	v_max_u32_e32 v2, v1, v4
	v_min_u32_e32 v1, v1, v4
	v_max_u32_e32 v32, v47, v28
	v_min_u32_e32 v47, v47, v28
	v_max_u32_e32 v4, v0, v16
	v_min_u32_e32 v0, v0, v16
	v_max_u32_e32 v28, v46, v42
	v_min_u32_e32 v46, v46, v42
	v_max_u32_e32 v16, v8, v182
	v_min_u32_e32 v8, v8, v182
	v_max_u32_e32 v42, v44, v184
	v_min_u32_e32 v44, v44, v184
	v_max_u32_e32 v182, v17, v31
	v_min_u32_e32 v17, v17, v31
	v_max_u32_e32 v184, v43, v41
	v_min_u32_e32 v43, v43, v41
	v_max_u32_e32 v31, v30, v5
	v_min_u32_e32 v30, v30, v5
	v_max_u32_e32 v41, v40, v29
	v_min_u32_e32 v40, v40, v29
	v_max_u32_e32 v5, v49, v3
	v_min_u32_e32 v49, v49, v3
	v_max_u32_e32 v29, v39, v33
	v_min_u32_e32 v39, v39, v33
	v_max_u32_e32 v3, v119, v2
	v_min_u32_e32 v119, v119, v2
	v_max_u32_e32 v33, v38, v32
	v_min_u32_e32 v38, v38, v32
	v_max_u32_e32 v2, v9, v7
	v_min_u32_e32 v9, v9, v7
	v_max_u32_e32 v32, v45, v23
	v_min_u32_e32 v45, v45, v23
	v_max_u32_e32 v7, v6, v1
	v_min_u32_e32 v6, v6, v1
	v_max_u32_e32 v23, v22, v47
	v_min_u32_e32 v22, v22, v47
	v_max_u32_e32 v1, v4, v182
	v_min_u32_e32 v4, v4, v182
	v_max_u32_e32 v47, v28, v184
	v_min_u32_e32 v28, v28, v184
	v_max_u32_e32 v182, v16, v31
	v_min_u32_e32 v16, v16, v31
	v_max_u32_e32 v184, v42, v41
	v_min_u32_e32 v42, v42, v41
	v_max_u32_e32 v31, v0, v17
	v_min_u32_e32 v0, v0, v17
	v_max_u32_e32 v41, v46, v43
	v_min_u32_e32 v46, v46, v43
	v_max_u32_e32 v17, v8, v30
	v_min_u32_e32 v8, v8, v30
	v_max_u32_e32 v43, v44, v40
	v_min_u32_e32 v44, v44, v40
	v_max_u32_e32 v30, v5, v3
	v_min_u32_e32 v5, v5, v3
	v_max_u32_e32 v40, v29, v33
	v_min_u32_e32 v29, v29, v33
	v_max_u32_e32 v3, v49, v119
	v_min_u32_e32 v49, v49, v119
	v_max_u32_e32 v33, v39, v38
	v_min_u32_e32 v39, v39, v38
	v_max_u32_e32 v119, v2, v7
	v_min_u32_e32 v2, v2, v7
	v_max_u32_e32 v38, v32, v23
	v_min_u32_e32 v32, v32, v23
	v_max_u32_e32 v7, v9, v6
	v_min_u32_e32 v9, v9, v6
	v_max_u32_e32 v23, v45, v22
	v_min_u32_e32 v45, v45, v22
	v_max_u32_e32 v6, v1, v182
	v_min_u32_e32 v1, v1, v182
	v_max_u32_e32 v22, v47, v184
	v_min_u32_e32 v47, v47, v184
	v_max_u32_e32 v182, v4, v16
	v_min_u32_e32 v4, v4, v16
	v_max_u32_e32 v184, v28, v42
	v_min_u32_e32 v28, v28, v42
	v_max_u32_e32 v16, v31, v17
	v_min_u32_e32 v31, v31, v17
	v_max_u32_e32 v42, v41, v43
	v_min_u32_e32 v41, v41, v43
	v_max_u32_e32 v17, v0, v8
	v_min_u32_e32 v0, v0, v8
	v_max_u32_e32 v43, v46, v44
	v_min_u32_e32 v46, v46, v44
	v_max_u32_e32 v30, v30, v46
	v_max_u32_e32 v5, v5, v43
	v_max_u32_e32 v3, v3, v41
	v_max_u32_e32 v49, v49, v42
	v_max_u32_e32 v119, v119, v28
	v_max_u32_e32 v2, v2, v184
	v_max_u32_e32 v7, v7, v47
	v_max_u32_e32 v9, v9, v22
	v_max_u32_e32 v6, v6, v45
	v_max_u32_e32 v1, v1, v23
	v_max_u32_e32 v182, v182, v32
	v_max_u32_e32 v4, v4, v38
	v_max_u32_e32 v16, v16, v39
	v_max_u32_e32 v31, v31, v33
	v_max_u32_e32 v17, v17, v29
	v_max_u32_e32 v0, v0, v40
	v_max_u32_e32 v8, v30, v6
	v_min_u32_e32 v30, v30, v6
	v_max_u32_e32 v6, v5, v1
	v_min_u32_e32 v5, v5, v1
	v_max_u32_e32 v1, v3, v182
	v_min_u32_e32 v3, v3, v182
	v_max_u32_e32 v182, v49, v4
	v_min_u32_e32 v49, v49, v4
	v_max_u32_e32 v4, v119, v16
	v_min_u32_e32 v119, v119, v16
	v_max_u32_e32 v16, v2, v31
	v_min_u32_e32 v2, v2, v31
	v_max_u32_e32 v31, v7, v17
	v_min_u32_e32 v7, v7, v17
	v_max_u32_e32 v17, v9, v0
	v_min_u32_e32 v9, v9, v0
	v_max_u32_e32 v0, v8, v4
	v_min_u32_e32 v8, v8, v4
	v_max_u32_e32 v4, v6, v16
	v_min_u32_e32 v6, v6, v16
	v_max_u32_e32 v16, v1, v31
	v_min_u32_e32 v1, v1, v31
	v_max_u32_e32 v31, v182, v17
	v_min_u32_e32 v182, v182, v17
	v_max_u32_e32 v17, v30, v119
	v_min_u32_e32 v30, v30, v119
	v_max_u32_e32 v119, v5, v2
	v_min_u32_e32 v5, v5, v2
	v_max_u32_e32 v2, v3, v7
	v_min_u32_e32 v3, v3, v7
	v_max_u32_e32 v7, v49, v9
	v_min_u32_e32 v49, v49, v9
	v_max_u32_e32 v9, v0, v16
	v_min_u32_e32 v0, v0, v16
	v_max_u32_e32 v16, v4, v31
	v_min_u32_e32 v4, v4, v31
	v_max_u32_e32 v31, v8, v1
	v_min_u32_e32 v8, v8, v1
	v_max_u32_e32 v1, v6, v182
	v_min_u32_e32 v6, v6, v182
	v_max_u32_e32 v182, v17, v2
	v_min_u32_e32 v17, v17, v2
	v_max_u32_e32 v2, v119, v7
	v_min_u32_e32 v119, v119, v7
	v_max_u32_e32 v7, v30, v3
	v_min_u32_e32 v30, v30, v3
	v_max_u32_e32 v3, v5, v49
	v_min_u32_e32 v5, v5, v49
	v_max_u32_e32 v49, v9, v16
	v_min_u32_e32 v9, v9, v16
	v_max_u32_e32 v16, v0, v4
	v_min_u32_e32 v0, v0, v4
	v_max_u32_e32 v4, v31, v1
	v_min_u32_e32 v31, v31, v1
	v_max_u32_e32 v1, v8, v6
	v_min_u32_e32 v8, v8, v6
	v_max_u32_e32 v6, v182, v2
	v_min_u32_e32 v182, v182, v2
	v_max_u32_e32 v2, v17, v119
	v_min_u32_e32 v17, v17, v119
	v_max_u32_e32 v119, v7, v3
	v_min_u32_e32 v7, v7, v3
	v_max_u32_e32 v3, v30, v5
	v_min_u32_e32 v30, v30, v5
	s_movk_i32 s8, 0xff
	v_and_b32_e32 v141, 0x7fffff00, v49
	v_bitop3_b32 v143, v49, s8, v49 bitop3:0xcf
	v_cmp_gt_i32_e32 vcc, 0, v49
	s_nop 1
	v_cndmask_b32_e32 v141, v143, v141, vcc
	v_sub_f32_e32 v141, v141, v131
	v_mul_f32_e32 v141, 0x3fb8aa3b, v141
	v_exp_f32_e32 v141, v141
	s_and_saveexec_b64 s[8:9], s[38:39]
	s_cbranch_execz .Lp_cand_0
	v_not_b32_e32 v143, v49
	v_lshlrev_b32_e32 v144, 8, v143
	v_lshlrev_b32_e32 v143, 4, v143
	v_and_b32_e32 v144, 0xf00, v144
	v_and_b32_e32 v143, 0xf00, v143
	v_add_u32_e32 v144, v216, v144
	v_add_u32_e32 v143, v216, v143
	ds_read_b32 v146, v144 offset:4096
	ds_read_b32 v143, v143
	v_lshl_add_u64 v[144:145], v[124:125], 0, s[0:1]
	s_movk_i32 s16, 0x3fff
	s_waitcnt lgkmcnt(1)
	v_and_b32_e32 v146, 0x7f, v146
	s_waitcnt lgkmcnt(0)
	v_lshlrev_b32_e32 v143, 7, v143
	v_and_b32_e32 v143, 0x3f80, v143
	v_bitop3_b32 v143, v143, s16, v146 bitop3:0x36
	v_add_co_u32_e32 v146, vcc, 0x6000000, v144
	s_nop 1
	v_addc_co_u32_e32 v147, vcc, 0, v145, vcc
	v_add_co_u32_e32 v144, vcc, 0x7000000, v144
	global_store_dword v[146:147], v143, off
	s_nop 0
	v_addc_co_u32_e32 v145, vcc, 0, v145, vcc
	global_store_dword v[144:145], v141, off
; DI void phase_peer_select(const Args& a, int layer, LAS unsigned char* lds) {
;     ...
;             const int ci = 255 - (int)(mx & 0xFFu);
;             const int e = (int)(127u - (lt1[(ci >> 4) * 64 + lane] & 0x7Fu)) * 128 + (int)(127u - (lt2[(ci & 15) * 64 + lane] & 0x7Fu));
;             const float ek = __expf(unordf(mx & ~0xFFu) - scmax);
;             sum += ek;
;             if (hi == 0) { ip[k] = e; gp[k] = ek; }
;         }
.Lp_cand_0:
	s_or_b64 exec, exec, s[8:9]
	s_add_u32 s0, s0, 4
	s_addc_u32 s1, s1, 0
	v_add_f32_e32 v128, v128, v141
	s_movk_i32 s8, 0xff
	v_and_b32_e32 v141, 0x7fffff00, v9
	v_bitop3_b32 v143, v9, s8, v9 bitop3:0xcf
	v_cmp_gt_i32_e32 vcc, 0, v9
	s_nop 1
	v_cndmask_b32_e32 v141, v143, v141, vcc
	v_sub_f32_e32 v141, v141, v131
	v_mul_f32_e32 v141, 0x3fb8aa3b, v141
	v_exp_f32_e32 v141, v141
	s_and_saveexec_b64 s[8:9], s[38:39]
	s_cbranch_execz .Lp_cand_1
	v_not_b32_e32 v143, v9
	v_lshlrev_b32_e32 v144, 8, v143
	v_lshlrev_b32_e32 v143, 4, v143
	v_and_b32_e32 v144, 0xf00, v144
	v_and_b32_e32 v143, 0xf00, v143
	v_add_u32_e32 v144, v216, v144
	v_add_u32_e32 v143, v216, v143
	ds_read_b32 v146, v144 offset:4096
	ds_read_b32 v143, v143
	v_lshl_add_u64 v[144:145], v[124:125], 0, s[0:1]
	s_movk_i32 s16, 0x3fff
	s_waitcnt lgkmcnt(1)
	v_and_b32_e32 v146, 0x7f, v146
	s_waitcnt lgkmcnt(0)
	v_lshlrev_b32_e32 v143, 7, v143
	v_and_b32_e32 v143, 0x3f80, v143
	v_bitop3_b32 v143, v143, s16, v146 bitop3:0x36
	v_add_co_u32_e32 v146, vcc, 0x6000000, v144
	s_nop 1
	v_addc_co_u32_e32 v147, vcc, 0, v145, vcc
	v_add_co_u32_e32 v144, vcc, 0x7000000, v144
	global_store_dword v[146:147], v143, off
	s_nop 0
	v_addc_co_u32_e32 v145, vcc, 0, v145, vcc
	global_store_dword v[144:145], v141, off
.Lp_cand_1:
	s_or_b64 exec, exec, s[8:9]
	s_add_u32 s0, s0, 4
	s_addc_u32 s1, s1, 0
	v_add_f32_e32 v128, v128, v141
	s_movk_i32 s8, 0xff
	v_and_b32_e32 v141, 0x7fffff00, v16
	v_bitop3_b32 v143, v16, s8, v16 bitop3:0xcf
	v_cmp_gt_i32_e32 vcc, 0, v16
	s_nop 1
	v_cndmask_b32_e32 v141, v143, v141, vcc
	v_sub_f32_e32 v141, v141, v131
	v_mul_f32_e32 v141, 0x3fb8aa3b, v141
	v_exp_f32_e32 v141, v141
	s_and_saveexec_b64 s[8:9], s[38:39]
	s_cbranch_execz .Lp_cand_2
	v_not_b32_e32 v143, v16
	v_lshlrev_b32_e32 v144, 8, v143
	v_lshlrev_b32_e32 v143, 4, v143
	v_and_b32_e32 v144, 0xf00, v144
	v_and_b32_e32 v143, 0xf00, v143
	v_add_u32_e32 v144, v216, v144
	v_add_u32_e32 v143, v216, v143
	ds_read_b32 v146, v144 offset:4096
	ds_read_b32 v143, v143
	v_lshl_add_u64 v[144:145], v[124:125], 0, s[0:1]
	s_movk_i32 s16, 0x3fff
	s_waitcnt lgkmcnt(1)
	v_and_b32_e32 v146, 0x7f, v146
	s_waitcnt lgkmcnt(0)
	v_lshlrev_b32_e32 v143, 7, v143
	v_and_b32_e32 v143, 0x3f80, v143
	v_bitop3_b32 v143, v143, s16, v146 bitop3:0x36
	v_add_co_u32_e32 v146, vcc, 0x6000000, v144
	s_nop 1
	v_addc_co_u32_e32 v147, vcc, 0, v145, vcc
	v_add_co_u32_e32 v144, vcc, 0x7000000, v144
	global_store_dword v[146:147], v143, off
	s_nop 0
	v_addc_co_u32_e32 v145, vcc, 0, v145, vcc
	global_store_dword v[144:145], v141, off
.Lp_cand_2:
	s_or_b64 exec, exec, s[8:9]
	s_add_u32 s0, s0, 4
	s_addc_u32 s1, s1, 0
	v_add_f32_e32 v128, v128, v141
	s_movk_i32 s8, 0xff
	v_and_b32_e32 v141, 0x7fffff00, v0
	v_bitop3_b32 v143, v0, s8, v0 bitop3:0xcf
	v_cmp_gt_i32_e32 vcc, 0, v0
	s_nop 1
	v_cndmask_b32_e32 v141, v143, v141, vcc
	v_sub_f32_e32 v141, v141, v131
	v_mul_f32_e32 v141, 0x3fb8aa3b, v141
	v_exp_f32_e32 v141, v141
	s_and_saveexec_b64 s[8:9], s[38:39]
	s_cbranch_execz .Lp_cand_3
	v_not_b32_e32 v143, v0
	v_lshlrev_b32_e32 v144, 8, v143
	v_lshlrev_b32_e32 v143, 4, v143
	v_and_b32_e32 v144, 0xf00, v144
	v_and_b32_e32 v143, 0xf00, v143
	v_add_u32_e32 v144, v216, v144
	v_add_u32_e32 v143, v216, v143
	ds_read_b32 v146, v144 offset:4096
	ds_read_b32 v143, v143
	v_lshl_add_u64 v[144:145], v[124:125], 0, s[0:1]
	s_movk_i32 s16, 0x3fff
	s_waitcnt lgkmcnt(1)
	v_and_b32_e32 v146, 0x7f, v146
	s_waitcnt lgkmcnt(0)
	v_lshlrev_b32_e32 v143, 7, v143
	v_and_b32_e32 v143, 0x3f80, v143
	v_bitop3_b32 v143, v143, s16, v146 bitop3:0x36
	v_add_co_u32_e32 v146, vcc, 0x6000000, v144
	s_nop 1
	v_addc_co_u32_e32 v147, vcc, 0, v145, vcc
	v_add_co_u32_e32 v144, vcc, 0x7000000, v144
	global_store_dword v[146:147], v143, off
	s_nop 0
	v_addc_co_u32_e32 v145, vcc, 0, v145, vcc
	global_store_dword v[144:145], v141, off
.Lp_cand_3:
	s_or_b64 exec, exec, s[8:9]
	s_add_u32 s0, s0, 4
	s_addc_u32 s1, s1, 0
	v_add_f32_e32 v128, v128, v141
	s_movk_i32 s8, 0xff
	v_and_b32_e32 v141, 0x7fffff00, v4
	v_bitop3_b32 v143, v4, s8, v4 bitop3:0xcf
	v_cmp_gt_i32_e32 vcc, 0, v4
	s_nop 1
	v_cndmask_b32_e32 v141, v143, v141, vcc
	v_sub_f32_e32 v141, v141, v131
	v_mul_f32_e32 v141, 0x3fb8aa3b, v141
	v_exp_f32_e32 v141, v141
	s_and_saveexec_b64 s[8:9], s[38:39]
	s_cbranch_execz .Lp_cand_4
	v_not_b32_e32 v143, v4
	v_lshlrev_b32_e32 v144, 8, v143
	v_lshlrev_b32_e32 v143, 4, v143
	v_and_b32_e32 v144, 0xf00, v144
	v_and_b32_e32 v143, 0xf00, v143
	v_add_u32_e32 v144, v216, v144
	v_add_u32_e32 v143, v216, v143
	ds_read_b32 v146, v144 offset:4096
	ds_read_b32 v143, v143
	v_lshl_add_u64 v[144:145], v[124:125], 0, s[0:1]
	s_movk_i32 s16, 0x3fff
	s_waitcnt lgkmcnt(1)
	v_and_b32_e32 v146, 0x7f, v146
	s_waitcnt lgkmcnt(0)
	v_lshlrev_b32_e32 v143, 7, v143
	v_and_b32_e32 v143, 0x3f80, v143
	v_bitop3_b32 v143, v143, s16, v146 bitop3:0x36
	v_add_co_u32_e32 v146, vcc, 0x6000000, v144
	s_nop 1
	v_addc_co_u32_e32 v147, vcc, 0, v145, vcc
	v_add_co_u32_e32 v144, vcc, 0x7000000, v144
	global_store_dword v[146:147], v143, off
	s_nop 0
	v_addc_co_u32_e32 v145, vcc, 0, v145, vcc
	global_store_dword v[144:145], v141, off
; DI void phase_peer_select(const Args& a, int layer, LAS unsigned char* lds) {
;     ...
;             const int ci = 255 - (int)(mx & 0xFFu);
;             const int e = (int)(127u - (lt1[(ci >> 4) * 64 + lane] & 0x7Fu)) * 128 + (int)(127u - (lt2[(ci & 15) * 64 + lane] & 0x7Fu));
;             const float ek = __expf(unordf(mx & ~0xFFu) - scmax);
;             sum += ek;
;             if (hi == 0) { ip[k] = e; gp[k] = ek; }
;         }
.Lp_cand_4:
	s_or_b64 exec, exec, s[8:9]
	s_add_u32 s0, s0, 4
	s_addc_u32 s1, s1, 0
	v_add_f32_e32 v128, v128, v141
	s_movk_i32 s8, 0xff
	v_and_b32_e32 v141, 0x7fffff00, v31
	v_bitop3_b32 v143, v31, s8, v31 bitop3:0xcf
	v_cmp_gt_i32_e32 vcc, 0, v31
	s_nop 1
	v_cndmask_b32_e32 v141, v143, v141, vcc
	v_sub_f32_e32 v141, v141, v131
	v_mul_f32_e32 v141, 0x3fb8aa3b, v141
	v_exp_f32_e32 v141, v141
	s_and_saveexec_b64 s[8:9], s[38:39]
	s_cbranch_execz .Lp_cand_5
	v_not_b32_e32 v143, v31
	v_lshlrev_b32_e32 v144, 8, v143
	v_lshlrev_b32_e32 v143, 4, v143
	v_and_b32_e32 v144, 0xf00, v144
	v_and_b32_e32 v143, 0xf00, v143
	v_add_u32_e32 v144, v216, v144
	v_add_u32_e32 v143, v216, v143
	ds_read_b32 v146, v144 offset:4096
	ds_read_b32 v143, v143
	v_lshl_add_u64 v[144:145], v[124:125], 0, s[0:1]
	s_movk_i32 s16, 0x3fff
	s_waitcnt lgkmcnt(1)
	v_and_b32_e32 v146, 0x7f, v146
	s_waitcnt lgkmcnt(0)
	v_lshlrev_b32_e32 v143, 7, v143
	v_and_b32_e32 v143, 0x3f80, v143
	v_bitop3_b32 v143, v143, s16, v146 bitop3:0x36
	v_add_co_u32_e32 v146, vcc, 0x6000000, v144
	s_nop 1
	v_addc_co_u32_e32 v147, vcc, 0, v145, vcc
	v_add_co_u32_e32 v144, vcc, 0x7000000, v144
	global_store_dword v[146:147], v143, off
	s_nop 0
	v_addc_co_u32_e32 v145, vcc, 0, v145, vcc
	global_store_dword v[144:145], v141, off
.Lp_cand_5:
	s_or_b64 exec, exec, s[8:9]
	s_add_u32 s0, s0, 4
	s_addc_u32 s1, s1, 0
	v_add_f32_e32 v128, v128, v141
	s_movk_i32 s8, 0xff
	v_and_b32_e32 v141, 0x7fffff00, v1
	v_bitop3_b32 v143, v1, s8, v1 bitop3:0xcf
	v_cmp_gt_i32_e32 vcc, 0, v1
	s_nop 1
	v_cndmask_b32_e32 v141, v143, v141, vcc
	v_sub_f32_e32 v141, v141, v131
	v_mul_f32_e32 v141, 0x3fb8aa3b, v141
	v_exp_f32_e32 v141, v141
	s_and_saveexec_b64 s[8:9], s[38:39]
	s_cbranch_execz .Lp_cand_6
	v_not_b32_e32 v143, v1
	v_lshlrev_b32_e32 v144, 8, v143
	v_lshlrev_b32_e32 v143, 4, v143
	v_and_b32_e32 v144, 0xf00, v144
	v_and_b32_e32 v143, 0xf00, v143
	v_add_u32_e32 v144, v216, v144
	v_add_u32_e32 v143, v216, v143
	ds_read_b32 v146, v144 offset:4096
	ds_read_b32 v143, v143
	v_lshl_add_u64 v[144:145], v[124:125], 0, s[0:1]
	s_movk_i32 s16, 0x3fff
	s_waitcnt lgkmcnt(1)
	v_and_b32_e32 v146, 0x7f, v146
	s_waitcnt lgkmcnt(0)
	v_lshlrev_b32_e32 v143, 7, v143
	v_and_b32_e32 v143, 0x3f80, v143
	v_bitop3_b32 v143, v143, s16, v146 bitop3:0x36
	v_add_co_u32_e32 v146, vcc, 0x6000000, v144
	s_nop 1
	v_addc_co_u32_e32 v147, vcc, 0, v145, vcc
	v_add_co_u32_e32 v144, vcc, 0x7000000, v144
	global_store_dword v[146:147], v143, off
	s_nop 0
	v_addc_co_u32_e32 v145, vcc, 0, v145, vcc
	global_store_dword v[144:145], v141, off
.Lp_cand_6:
	s_or_b64 exec, exec, s[8:9]
	s_add_u32 s0, s0, 4
	s_addc_u32 s1, s1, 0
	v_add_f32_e32 v128, v128, v141
	s_movk_i32 s8, 0xff
	v_and_b32_e32 v141, 0x7fffff00, v8
	v_bitop3_b32 v143, v8, s8, v8 bitop3:0xcf
	v_cmp_gt_i32_e32 vcc, 0, v8
	s_nop 1
	v_cndmask_b32_e32 v141, v143, v141, vcc
	v_sub_f32_e32 v141, v141, v131
	v_mul_f32_e32 v141, 0x3fb8aa3b, v141
	v_exp_f32_e32 v141, v141
	s_and_saveexec_b64 s[8:9], s[38:39]
	s_cbranch_execz .Lp_cand_7
	v_not_b32_e32 v143, v8
	v_lshlrev_b32_e32 v144, 8, v143
	v_lshlrev_b32_e32 v143, 4, v143
	v_and_b32_e32 v144, 0xf00, v144
	v_and_b32_e32 v143, 0xf00, v143
	v_add_u32_e32 v144, v216, v144
	v_add_u32_e32 v143, v216, v143
	ds_read_b32 v146, v144 offset:4096
	ds_read_b32 v143, v143
	v_lshl_add_u64 v[144:145], v[124:125], 0, s[0:1]
	s_movk_i32 s16, 0x3fff
	s_waitcnt lgkmcnt(1)
	v_and_b32_e32 v146, 0x7f, v146
	s_waitcnt lgkmcnt(0)
	v_lshlrev_b32_e32 v143, 7, v143
	v_and_b32_e32 v143, 0x3f80, v143
	v_bitop3_b32 v143, v143, s16, v146 bitop3:0x36
	v_add_co_u32_e32 v146, vcc, 0x6000000, v144
	s_nop 1
	v_addc_co_u32_e32 v147, vcc, 0, v145, vcc
	v_add_co_u32_e32 v144, vcc, 0x7000000, v144
	global_store_dword v[146:147], v143, off
	s_nop 0
	v_addc_co_u32_e32 v145, vcc, 0, v145, vcc
	global_store_dword v[144:145], v141, off
.Lp_cand_7:
	s_or_b64 exec, exec, s[8:9]
	s_add_u32 s0, s0, 4
	s_addc_u32 s1, s1, 0
	v_add_f32_e32 v128, v128, v141
	s_movk_i32 s8, 0xff
	v_and_b32_e32 v141, 0x7fffff00, v6
	v_bitop3_b32 v143, v6, s8, v6 bitop3:0xcf
	v_cmp_gt_i32_e32 vcc, 0, v6
	s_nop 1
	v_cndmask_b32_e32 v141, v143, v141, vcc
	v_sub_f32_e32 v141, v141, v131
	v_mul_f32_e32 v141, 0x3fb8aa3b, v141
	v_exp_f32_e32 v141, v141
	s_and_saveexec_b64 s[8:9], s[38:39]
	s_cbranch_execz .Lp_cand_8
	v_not_b32_e32 v143, v6
	v_lshlrev_b32_e32 v144, 8, v143
	v_lshlrev_b32_e32 v143, 4, v143
	v_and_b32_e32 v144, 0xf00, v144
	v_and_b32_e32 v143, 0xf00, v143
	v_add_u32_e32 v144, v216, v144
	v_add_u32_e32 v143, v216, v143
	ds_read_b32 v146, v144 offset:4096
	ds_read_b32 v143, v143
	v_lshl_add_u64 v[144:145], v[124:125], 0, s[0:1]
	s_movk_i32 s16, 0x3fff
	s_waitcnt lgkmcnt(1)
	v_and_b32_e32 v146, 0x7f, v146
	s_waitcnt lgkmcnt(0)
	v_lshlrev_b32_e32 v143, 7, v143
	v_and_b32_e32 v143, 0x3f80, v143
	v_bitop3_b32 v143, v143, s16, v146 bitop3:0x36
	v_add_co_u32_e32 v146, vcc, 0x6000000, v144
	s_nop 1
	v_addc_co_u32_e32 v147, vcc, 0, v145, vcc
	v_add_co_u32_e32 v144, vcc, 0x7000000, v144
	global_store_dword v[146:147], v143, off
	s_nop 0
	v_addc_co_u32_e32 v145, vcc, 0, v145, vcc
	global_store_dword v[144:145], v141, off
; DI void phase_peer_select(const Args& a, int layer, LAS unsigned char* lds) {
;     ...
;             const int ci = 255 - (int)(mx & 0xFFu);
;             const int e = (int)(127u - (lt1[(ci >> 4) * 64 + lane] & 0x7Fu)) * 128 + (int)(127u - (lt2[(ci & 15) * 64 + lane] & 0x7Fu));
;             const float ek = __expf(unordf(mx & ~0xFFu) - scmax);
;             sum += ek;
;             if (hi == 0) { ip[k] = e; gp[k] = ek; }
;         }
.Lp_cand_8:
	s_or_b64 exec, exec, s[8:9]
	s_add_u32 s0, s0, 4
	s_addc_u32 s1, s1, 0
	v_add_f32_e32 v128, v128, v141
	s_movk_i32 s8, 0xff
	v_and_b32_e32 v141, 0x7fffff00, v182
	v_bitop3_b32 v143, v182, s8, v182 bitop3:0xcf
	v_cmp_gt_i32_e32 vcc, 0, v182
	s_nop 1
	v_cndmask_b32_e32 v141, v143, v141, vcc
	v_sub_f32_e32 v141, v141, v131
	v_mul_f32_e32 v141, 0x3fb8aa3b, v141
	v_exp_f32_e32 v141, v141
	s_and_saveexec_b64 s[8:9], s[38:39]
	s_cbranch_execz .Lp_cand_9
	v_not_b32_e32 v143, v182
	v_lshlrev_b32_e32 v144, 8, v143
	v_lshlrev_b32_e32 v143, 4, v143
	v_and_b32_e32 v144, 0xf00, v144
	v_and_b32_e32 v143, 0xf00, v143
	v_add_u32_e32 v144, v216, v144
	v_add_u32_e32 v143, v216, v143
	ds_read_b32 v146, v144 offset:4096
	ds_read_b32 v143, v143
	v_lshl_add_u64 v[144:145], v[124:125], 0, s[0:1]
	s_movk_i32 s16, 0x3fff
	s_waitcnt lgkmcnt(1)
	v_and_b32_e32 v146, 0x7f, v146
	s_waitcnt lgkmcnt(0)
	v_lshlrev_b32_e32 v143, 7, v143
	v_and_b32_e32 v143, 0x3f80, v143
	v_bitop3_b32 v143, v143, s16, v146 bitop3:0x36
	v_add_co_u32_e32 v146, vcc, 0x6000000, v144
	s_nop 1
	v_addc_co_u32_e32 v147, vcc, 0, v145, vcc
	v_add_co_u32_e32 v144, vcc, 0x7000000, v144
	global_store_dword v[146:147], v143, off
	s_nop 0
	v_addc_co_u32_e32 v145, vcc, 0, v145, vcc
	global_store_dword v[144:145], v141, off
.Lp_cand_9:
	s_or_b64 exec, exec, s[8:9]
	s_add_u32 s0, s0, 4
	s_addc_u32 s1, s1, 0
	v_add_f32_e32 v128, v128, v141
	s_movk_i32 s8, 0xff
	v_and_b32_e32 v141, 0x7fffff00, v2
	v_bitop3_b32 v143, v2, s8, v2 bitop3:0xcf
	v_cmp_gt_i32_e32 vcc, 0, v2
	s_nop 1
	v_cndmask_b32_e32 v141, v143, v141, vcc
	v_sub_f32_e32 v141, v141, v131
	v_mul_f32_e32 v141, 0x3fb8aa3b, v141
	v_exp_f32_e32 v141, v141
	s_and_saveexec_b64 s[8:9], s[38:39]
	s_cbranch_execz .Lp_cand_10
	v_not_b32_e32 v143, v2
	v_lshlrev_b32_e32 v144, 8, v143
	v_lshlrev_b32_e32 v143, 4, v143
	v_and_b32_e32 v144, 0xf00, v144
	v_and_b32_e32 v143, 0xf00, v143
	v_add_u32_e32 v144, v216, v144
	v_add_u32_e32 v143, v216, v143
	ds_read_b32 v146, v144 offset:4096
	ds_read_b32 v143, v143
	v_lshl_add_u64 v[144:145], v[124:125], 0, s[0:1]
	s_movk_i32 s16, 0x3fff
	s_waitcnt lgkmcnt(1)
	v_and_b32_e32 v146, 0x7f, v146
	s_waitcnt lgkmcnt(0)
	v_lshlrev_b32_e32 v143, 7, v143
	v_and_b32_e32 v143, 0x3f80, v143
	v_bitop3_b32 v143, v143, s16, v146 bitop3:0x36
	v_add_co_u32_e32 v146, vcc, 0x6000000, v144
	s_nop 1
	v_addc_co_u32_e32 v147, vcc, 0, v145, vcc
	v_add_co_u32_e32 v144, vcc, 0x7000000, v144
	global_store_dword v[146:147], v143, off
	s_nop 0
	v_addc_co_u32_e32 v145, vcc, 0, v145, vcc
	global_store_dword v[144:145], v141, off
.Lp_cand_10:
	s_or_b64 exec, exec, s[8:9]
	s_add_u32 s0, s0, 4
	s_addc_u32 s1, s1, 0
	v_add_f32_e32 v128, v128, v141
	s_movk_i32 s8, 0xff
	v_and_b32_e32 v141, 0x7fffff00, v17
	v_bitop3_b32 v143, v17, s8, v17 bitop3:0xcf
	v_cmp_gt_i32_e32 vcc, 0, v17
	s_nop 1
	v_cndmask_b32_e32 v141, v143, v141, vcc
	v_sub_f32_e32 v141, v141, v131
	v_mul_f32_e32 v141, 0x3fb8aa3b, v141
	v_exp_f32_e32 v141, v141
	s_and_saveexec_b64 s[8:9], s[38:39]
	s_cbranch_execz .Lp_cand_11
	v_not_b32_e32 v143, v17
	v_lshlrev_b32_e32 v144, 8, v143
	v_lshlrev_b32_e32 v143, 4, v143
	v_and_b32_e32 v144, 0xf00, v144
	v_and_b32_e32 v143, 0xf00, v143
	v_add_u32_e32 v144, v216, v144
	v_add_u32_e32 v143, v216, v143
	ds_read_b32 v146, v144 offset:4096
	ds_read_b32 v143, v143
	v_lshl_add_u64 v[144:145], v[124:125], 0, s[0:1]
	s_movk_i32 s16, 0x3fff
	s_waitcnt lgkmcnt(1)
	v_and_b32_e32 v146, 0x7f, v146
	s_waitcnt lgkmcnt(0)
	v_lshlrev_b32_e32 v143, 7, v143
	v_and_b32_e32 v143, 0x3f80, v143
	v_bitop3_b32 v143, v143, s16, v146 bitop3:0x36
	v_add_co_u32_e32 v146, vcc, 0x6000000, v144
	s_nop 1
	v_addc_co_u32_e32 v147, vcc, 0, v145, vcc
	v_add_co_u32_e32 v144, vcc, 0x7000000, v144
	global_store_dword v[146:147], v143, off
	s_nop 0
	v_addc_co_u32_e32 v145, vcc, 0, v145, vcc
	global_store_dword v[144:145], v141, off
.Lp_cand_11:
	s_or_b64 exec, exec, s[8:9]
	s_add_u32 s0, s0, 4
	s_addc_u32 s1, s1, 0
	v_add_f32_e32 v128, v128, v141
	s_movk_i32 s8, 0xff
	v_and_b32_e32 v141, 0x7fffff00, v119
	v_bitop3_b32 v143, v119, s8, v119 bitop3:0xcf
	v_cmp_gt_i32_e32 vcc, 0, v119
	s_nop 1
	v_cndmask_b32_e32 v141, v143, v141, vcc
	v_sub_f32_e32 v141, v141, v131
	v_mul_f32_e32 v141, 0x3fb8aa3b, v141
	v_exp_f32_e32 v141, v141
	s_and_saveexec_b64 s[8:9], s[38:39]
	s_cbranch_execz .Lp_cand_12
	v_not_b32_e32 v143, v119
	v_lshlrev_b32_e32 v144, 8, v143
	v_lshlrev_b32_e32 v143, 4, v143
	v_and_b32_e32 v144, 0xf00, v144
	v_and_b32_e32 v143, 0xf00, v143
	v_add_u32_e32 v144, v216, v144
	v_add_u32_e32 v143, v216, v143
	ds_read_b32 v146, v144 offset:4096
	ds_read_b32 v143, v143
	v_lshl_add_u64 v[144:145], v[124:125], 0, s[0:1]
	s_movk_i32 s16, 0x3fff
	s_waitcnt lgkmcnt(1)
	v_and_b32_e32 v146, 0x7f, v146
	s_waitcnt lgkmcnt(0)
	v_lshlrev_b32_e32 v143, 7, v143
	v_and_b32_e32 v143, 0x3f80, v143
	v_bitop3_b32 v143, v143, s16, v146 bitop3:0x36
	v_add_co_u32_e32 v146, vcc, 0x6000000, v144
	s_nop 1
	v_addc_co_u32_e32 v147, vcc, 0, v145, vcc
	v_add_co_u32_e32 v144, vcc, 0x7000000, v144
	global_store_dword v[146:147], v143, off
	s_nop 0
	v_addc_co_u32_e32 v145, vcc, 0, v145, vcc
	global_store_dword v[144:145], v141, off
; DI void phase_peer_select(const Args& a, int layer, LAS unsigned char* lds) {
;     ...
;             const int ci = 255 - (int)(mx & 0xFFu);
;             const int e = (int)(127u - (lt1[(ci >> 4) * 64 + lane] & 0x7Fu)) * 128 + (int)(127u - (lt2[(ci & 15) * 64 + lane] & 0x7Fu));
;             const float ek = __expf(unordf(mx & ~0xFFu) - scmax);
;             sum += ek;
;             if (hi == 0) { ip[k] = e; gp[k] = ek; }
;         }
;         if (hi == 0) ((float*)(ws + WS_GSUM))[m * 8 + h] = 1.f / sum;
.Lp_cand_12:
	s_or_b64 exec, exec, s[8:9]
	s_add_u32 s0, s0, 4
	s_addc_u32 s1, s1, 0
	v_add_f32_e32 v128, v128, v141
	s_movk_i32 s8, 0xff
	v_and_b32_e32 v141, 0x7fffff00, v7
	v_bitop3_b32 v143, v7, s8, v7 bitop3:0xcf
	v_cmp_gt_i32_e32 vcc, 0, v7
	s_nop 1
	v_cndmask_b32_e32 v141, v143, v141, vcc
	v_sub_f32_e32 v141, v141, v131
	v_mul_f32_e32 v141, 0x3fb8aa3b, v141
	v_exp_f32_e32 v141, v141
	s_and_saveexec_b64 s[8:9], s[38:39]
	s_cbranch_execz .Lp_cand_13
	v_not_b32_e32 v143, v7
	v_lshlrev_b32_e32 v144, 8, v143
	v_lshlrev_b32_e32 v143, 4, v143
	v_and_b32_e32 v144, 0xf00, v144
	v_and_b32_e32 v143, 0xf00, v143
	v_add_u32_e32 v144, v216, v144
	v_add_u32_e32 v143, v216, v143
	ds_read_b32 v146, v144 offset:4096
	ds_read_b32 v143, v143
	v_lshl_add_u64 v[144:145], v[124:125], 0, s[0:1]
	s_movk_i32 s16, 0x3fff
	s_waitcnt lgkmcnt(1)
	v_and_b32_e32 v146, 0x7f, v146
	s_waitcnt lgkmcnt(0)
	v_lshlrev_b32_e32 v143, 7, v143
	v_and_b32_e32 v143, 0x3f80, v143
	v_bitop3_b32 v143, v143, s16, v146 bitop3:0x36
	v_add_co_u32_e32 v146, vcc, 0x6000000, v144
	s_nop 1
	v_addc_co_u32_e32 v147, vcc, 0, v145, vcc
	v_add_co_u32_e32 v144, vcc, 0x7000000, v144
	global_store_dword v[146:147], v143, off
	s_nop 0
	v_addc_co_u32_e32 v145, vcc, 0, v145, vcc
	global_store_dword v[144:145], v141, off
.Lp_cand_13:
	s_or_b64 exec, exec, s[8:9]
	s_add_u32 s0, s0, 4
	s_addc_u32 s1, s1, 0
	v_add_f32_e32 v128, v128, v141
	s_movk_i32 s8, 0xff
	v_and_b32_e32 v141, 0x7fffff00, v3
	v_bitop3_b32 v143, v3, s8, v3 bitop3:0xcf
	v_cmp_gt_i32_e32 vcc, 0, v3
	s_nop 1
	v_cndmask_b32_e32 v141, v143, v141, vcc
	v_sub_f32_e32 v141, v141, v131
	v_mul_f32_e32 v141, 0x3fb8aa3b, v141
	v_exp_f32_e32 v141, v141
	s_and_saveexec_b64 s[8:9], s[38:39]
	s_cbranch_execz .Lp_cand_14
	v_not_b32_e32 v143, v3
	v_lshlrev_b32_e32 v144, 8, v143
	v_lshlrev_b32_e32 v143, 4, v143
	v_and_b32_e32 v144, 0xf00, v144
	v_and_b32_e32 v143, 0xf00, v143
	v_add_u32_e32 v144, v216, v144
	v_add_u32_e32 v143, v216, v143
	ds_read_b32 v146, v144 offset:4096
	ds_read_b32 v143, v143
	v_lshl_add_u64 v[144:145], v[124:125], 0, s[0:1]
	s_movk_i32 s16, 0x3fff
	s_waitcnt lgkmcnt(1)
	v_and_b32_e32 v146, 0x7f, v146
	s_waitcnt lgkmcnt(0)
	v_lshlrev_b32_e32 v143, 7, v143
	v_and_b32_e32 v143, 0x3f80, v143
	v_bitop3_b32 v143, v143, s16, v146 bitop3:0x36
	v_add_co_u32_e32 v146, vcc, 0x6000000, v144
	s_nop 1
	v_addc_co_u32_e32 v147, vcc, 0, v145, vcc
	v_add_co_u32_e32 v144, vcc, 0x7000000, v144
	global_store_dword v[146:147], v143, off
	s_nop 0
	v_addc_co_u32_e32 v145, vcc, 0, v145, vcc
	global_store_dword v[144:145], v141, off
.Lp_cand_14:
	s_or_b64 exec, exec, s[8:9]
	s_add_u32 s0, s0, 4
	s_addc_u32 s1, s1, 0
	v_add_f32_e32 v128, v128, v141
	s_movk_i32 s8, 0xff
	v_and_b32_e32 v141, 0x7fffff00, v30
	v_bitop3_b32 v143, v30, s8, v30 bitop3:0xcf
	v_cmp_gt_i32_e32 vcc, 0, v30
	s_nop 1
	v_cndmask_b32_e32 v141, v143, v141, vcc
	v_sub_f32_e32 v141, v141, v131
	v_mul_f32_e32 v141, 0x3fb8aa3b, v141
	v_exp_f32_e32 v141, v141
	s_and_saveexec_b64 s[8:9], s[38:39]
	s_cbranch_execz .Lp_cand_15
	v_not_b32_e32 v143, v30
	v_lshlrev_b32_e32 v144, 8, v143
	v_lshlrev_b32_e32 v143, 4, v143
	v_and_b32_e32 v144, 0xf00, v144
	v_and_b32_e32 v143, 0xf00, v143
	v_add_u32_e32 v144, v216, v144
	v_add_u32_e32 v143, v216, v143
	ds_read_b32 v146, v144 offset:4096
	ds_read_b32 v143, v143
	v_lshl_add_u64 v[144:145], v[124:125], 0, s[0:1]
	s_movk_i32 s16, 0x3fff
	s_waitcnt lgkmcnt(1)
	v_and_b32_e32 v146, 0x7f, v146
	s_waitcnt lgkmcnt(0)
	v_lshlrev_b32_e32 v143, 7, v143
	v_and_b32_e32 v143, 0x3f80, v143
	v_bitop3_b32 v143, v143, s16, v146 bitop3:0x36
	v_add_co_u32_e32 v146, vcc, 0x6000000, v144
	s_nop 1
	v_addc_co_u32_e32 v147, vcc, 0, v145, vcc
	v_add_co_u32_e32 v144, vcc, 0x7000000, v144
	global_store_dword v[146:147], v143, off
	s_nop 0
	v_addc_co_u32_e32 v145, vcc, 0, v145, vcc
	global_store_dword v[144:145], v141, off
.Lp_cand_15:
	s_or_b64 exec, exec, s[8:9]
	s_add_u32 s0, s0, 4
	s_addc_u32 s1, s1, 0
	v_add_f32_e32 v128, v128, v141

; DI unsigned pk2(float lo, float hi) { const f32x2 v = {lo, hi}; return __builtin_bit_cast(unsigned, __builtin_convertvector(v, bf16v2)); }
;     DI void operator()(const pg8::f32x4 (&acc)[2][2][4][2], const pg8::Unit& u, int wr, int wc, int fr, int fq) const {
;     ...
;                 if (rss) { const pg8::f32x4* rp = (const pg8::f32x4*)(rss + (size_t)row * 32); pg8::f32x4 t = rp[0];
; #pragma unroll
;                     for (int j = 1; j < 8; ++j) t += rp[j];
;                     sc = rsqrtf(((t[0] + t[1]) + (t[2] + t[3])) * (1.f / D) + 1e-6f); }
;                 bf16_t* rowp = O + (size_t)row * ldc + col0;
; #pragma unroll
;                 for (int bj = 0; bj < 2; ++bj) { const pg8::f32x4 v0 = acc[ai][bj][m][0] * sc, v1 = acc[ai][bj][m][1] * sc;
;                     u32x4 w; w.x = pk2(v0[0], v0[1]); w.y = pk2(v0[2], v0[3]); w.z = pk2(v1[0], v1[1]); w.w = pk2(v1[2], v1[3]);
;                     *(u32x4*)(rowp + bj * pg8::HALF) = w; }
.LBB0_70:
	v_lshl_add_u32 v152, s29, 8, v131
	v_ashrrev_i32_e32 v153, 31, v152
	v_mbcnt_lo_u32_b32 v151, -1, 0
	v_mbcnt_hi_u32_b32 v151, -1, v151
	v_lshrrev_b32_e32 v157, 4, v151
	v_lshlrev_b32_e32 v157, 2, v157
	v_lshl_add_u32 v157, v152, 7, v157
	s_mov_b64 s[22:23], s[24:25]
	v_lshl_or_b32 v150, s27, 8, v155
	v_lshlrev_b32_e32 v150, 1, v150
	v_lshl_add_u32 v150, v152, 12, v150
	v_readlane_b32 s8, v252, 25
	v_readlane_b32 s9, v252, 26
	v_readlane_b32 s62, v255, 17
	v_readlane_b32 s63, v255, 18
	s_mov_b32 s16, 0x800000
	global_load_dword v168, v157, s[22:23]
	global_load_dword v169, v157, s[22:23] offset:16
	global_load_dword v170, v157, s[22:23] offset:32
	global_load_dword v171, v157, s[22:23] offset:48
	global_load_dword v172, v157, s[22:23] offset:64
	global_load_dword v173, v157, s[22:23] offset:80
	global_load_dword v174, v157, s[22:23] offset:96
	global_load_dword v175, v157, s[22:23] offset:112
	global_load_dword v176, v157, s[22:23] offset:2048
	global_load_dword v177, v157, s[22:23] offset:2064
	global_load_dword v178, v157, s[22:23] offset:2080
	global_load_dword v179, v157, s[22:23] offset:2096
	s_waitcnt vmcnt(11)
	v_mov_b32_e32 v160, v168
	global_load_dword v168, v157, s[22:23] offset:2112
	s_waitcnt vmcnt(11)
	v_add_f32_e32 v160, v160, v169
	global_load_dword v169, v157, s[22:23] offset:2128
	s_waitcnt vmcnt(11)
	v_add_f32_e32 v160, v160, v170
	global_load_dword v170, v157, s[22:23] offset:2144
	s_waitcnt vmcnt(11)
	v_add_f32_e32 v160, v160, v171
	global_load_dword v171, v157, s[22:23] offset:2160
	s_waitcnt vmcnt(11)
	v_add_f32_e32 v160, v160, v172
	s_add_u32 s22, s22, 0x1000
	s_addc_u32 s23, s23, 0
	global_load_dword v172, v157, s[22:23]
	s_waitcnt vmcnt(11)
	v_add_f32_e32 v160, v160, v173
	global_load_dword v173, v157, s[22:23] offset:16
	s_waitcnt vmcnt(11)
	v_add_f32_e32 v160, v160, v174
	global_load_dword v174, v157, s[22:23] offset:32
	s_waitcnt vmcnt(11)
	v_add_f32_e32 v160, v160, v175
	global_load_dword v175, v157, s[22:23] offset:48
	s_waitcnt vmcnt(11)
	v_mov_b32_e32 v161, v176
	global_load_dword v176, v157, s[22:23] offset:64
	s_waitcnt vmcnt(11)
	v_add_f32_e32 v161, v161, v177
	global_load_dword v177, v157, s[22:23] offset:80
	s_waitcnt vmcnt(11)
	v_add_f32_e32 v161, v161, v178
	global_load_dword v178, v157, s[22:23] offset:96
	s_waitcnt vmcnt(11)
	v_add_f32_e32 v161, v161, v179
	global_load_dword v179, v157, s[22:23] offset:112
	s_waitcnt vmcnt(11)
	v_add_f32_e32 v161, v161, v168
	global_load_dword v168, v157, s[22:23] offset:2048
	s_waitcnt vmcnt(11)
	v_add_f32_e32 v161, v161, v169
	global_load_dword v169, v157, s[22:23] offset:2064
	s_waitcnt vmcnt(11)
	v_add_f32_e32 v161, v161, v170
	global_load_dword v170, v157, s[22:23] offset:2080
	s_waitcnt vmcnt(11)
	v_add_f32_e32 v161, v161, v171
	global_load_dword v171, v157, s[22:23] offset:2096
	s_waitcnt vmcnt(11)
	v_mov_b32_e32 v162, v172
	global_load_dword v172, v157, s[22:23] offset:2112
	s_waitcnt vmcnt(11)
	v_add_f32_e32 v162, v162, v173
	global_load_dword v173, v157, s[22:23] offset:2128
	s_waitcnt vmcnt(11)
	v_add_f32_e32 v162, v162, v174
	global_load_dword v174, v157, s[22:23] offset:2144
	s_waitcnt vmcnt(11)
	v_add_f32_e32 v162, v162, v175
	global_load_dword v175, v157, s[22:23] offset:2160
	s_waitcnt vmcnt(11)
	v_add_f32_e32 v162, v162, v176
	s_add_u32 s22, s22, 0x3000
	s_addc_u32 s23, s23, 0
	global_load_dword v176, v157, s[22:23]
	s_waitcnt vmcnt(11)
	v_add_f32_e32 v162, v162, v177
	global_load_dword v177, v157, s[22:23] offset:16
	s_waitcnt vmcnt(11)
	v_add_f32_e32 v162, v162, v178
	global_load_dword v178, v157, s[22:23] offset:32
	s_waitcnt vmcnt(11)
	v_add_f32_e32 v162, v162, v179
	global_load_dword v179, v157, s[22:23] offset:48
	s_waitcnt vmcnt(11)
	v_mov_b32_e32 v163, v168
	global_load_dword v168, v157, s[22:23] offset:64
	s_waitcnt vmcnt(11)
	v_add_f32_e32 v163, v163, v169
	global_load_dword v169, v157, s[22:23] offset:80
	s_waitcnt vmcnt(11)
	v_add_f32_e32 v163, v163, v170
	global_load_dword v170, v157, s[22:23] offset:96
	s_waitcnt vmcnt(11)
	v_add_f32_e32 v163, v163, v171
	global_load_dword v171, v157, s[22:23] offset:112
	s_waitcnt vmcnt(11)
	v_add_f32_e32 v163, v163, v172
	global_load_dword v172, v157, s[22:23] offset:2048
	s_waitcnt vmcnt(11)
	v_add_f32_e32 v163, v163, v173
	global_load_dword v173, v157, s[22:23] offset:2064
	s_waitcnt vmcnt(11)
	v_add_f32_e32 v163, v163, v174
	global_load_dword v174, v157, s[22:23] offset:2080
	s_waitcnt vmcnt(11)
	v_add_f32_e32 v163, v163, v175
	global_load_dword v175, v157, s[22:23] offset:2096
	s_waitcnt vmcnt(11)
	v_mov_b32_e32 v164, v176
	global_load_dword v176, v157, s[22:23] offset:2112
	s_waitcnt vmcnt(11)
	v_add_f32_e32 v164, v164, v177
	global_load_dword v177, v157, s[22:23] offset:2128
	s_waitcnt vmcnt(11)
	v_add_f32_e32 v164, v164, v178
	global_load_dword v178, v157, s[22:23] offset:2144
	s_waitcnt vmcnt(11)
	v_add_f32_e32 v164, v164, v179
	global_load_dword v179, v157, s[22:23] offset:2160
	s_waitcnt vmcnt(11)
	v_add_f32_e32 v164, v164, v168
	s_add_u32 s22, s22, 0x1000
	s_addc_u32 s23, s23, 0
	global_load_dword v168, v157, s[22:23]
	s_waitcnt vmcnt(11)
	v_add_f32_e32 v164, v164, v169
	global_load_dword v169, v157, s[22:23] offset:16
	s_waitcnt vmcnt(11)
	v_add_f32_e32 v164, v164, v170
	global_load_dword v170, v157, s[22:23] offset:32
	s_waitcnt vmcnt(11)
	v_add_f32_e32 v164, v164, v171
	global_load_dword v171, v157, s[22:23] offset:48
	s_waitcnt vmcnt(11)
	v_mov_b32_e32 v165, v172
	global_load_dword v172, v157, s[22:23] offset:64
	s_waitcnt vmcnt(11)
	v_add_f32_e32 v165, v165, v173
	global_load_dword v173, v157, s[22:23] offset:80
	s_waitcnt vmcnt(11)
; DI unsigned pk2(float lo, float hi) { const f32x2 v = {lo, hi}; return __builtin_bit_cast(unsigned, __builtin_convertvector(v, bf16v2)); }
;     DI void operator()(const pg8::f32x4 (&acc)[2][2][4][2], const pg8::Unit& u, int wr, int wc, int fr, int fq) const {
;     ...
;                 if (rss) { const pg8::f32x4* rp = (const pg8::f32x4*)(rss + (size_t)row * 32); pg8::f32x4 t = rp[0];
; #pragma unroll
;                     for (int j = 1; j < 8; ++j) t += rp[j];
;                     sc = rsqrtf(((t[0] + t[1]) + (t[2] + t[3])) * (1.f / D) + 1e-6f); }
;                 bf16_t* rowp = O + (size_t)row * ldc + col0;
; #pragma unroll
;                 for (int bj = 0; bj < 2; ++bj) { const pg8::f32x4 v0 = acc[ai][bj][m][0] * sc, v1 = acc[ai][bj][m][1] * sc;
;                     u32x4 w; w.x = pk2(v0[0], v0[1]); w.y = pk2(v0[2], v0[3]); w.z = pk2(v1[0], v1[1]); w.w = pk2(v1[2], v1[3]);
;                     *(u32x4*)(rowp + bj * pg8::HALF) = w; }
	v_add_f32_e32 v165, v165, v174
	global_load_dword v174, v157, s[22:23] offset:96
	s_waitcnt vmcnt(11)
	v_add_f32_e32 v165, v165, v175
	global_load_dword v175, v157, s[22:23] offset:112
	s_waitcnt vmcnt(11)
	v_add_f32_e32 v165, v165, v176
	global_load_dword v176, v157, s[22:23] offset:2048
	s_waitcnt vmcnt(11)
	v_add_f32_e32 v165, v165, v177
	global_load_dword v177, v157, s[22:23] offset:2064
	s_waitcnt vmcnt(11)
	v_add_f32_e32 v165, v165, v178
	global_load_dword v178, v157, s[22:23] offset:2080
	s_waitcnt vmcnt(11)
	v_add_f32_e32 v165, v165, v179
	global_load_dword v179, v157, s[22:23] offset:2096
	s_waitcnt vmcnt(11)
	v_mov_b32_e32 v166, v168
	global_load_dword v168, v157, s[22:23] offset:2112
	s_waitcnt vmcnt(11)
	v_add_f32_e32 v166, v166, v169
	global_load_dword v169, v157, s[22:23] offset:2128
	s_waitcnt vmcnt(11)
	v_add_f32_e32 v166, v166, v170
	global_load_dword v170, v157, s[22:23] offset:2144
	s_waitcnt vmcnt(11)
	v_add_f32_e32 v166, v166, v171
	global_load_dword v171, v157, s[22:23] offset:2160
	s_waitcnt vmcnt(11)
	v_add_f32_e32 v166, v166, v172
	s_waitcnt vmcnt(10)
	v_add_f32_e32 v166, v166, v173
	s_waitcnt vmcnt(9)
	v_add_f32_e32 v166, v166, v174
	s_waitcnt vmcnt(8)
	v_add_f32_e32 v166, v166, v175
	s_waitcnt vmcnt(7)
	v_mov_b32_e32 v167, v176
	s_waitcnt vmcnt(6)
	v_add_f32_e32 v167, v167, v177
	s_waitcnt vmcnt(5)
	v_add_f32_e32 v167, v167, v178
	s_waitcnt vmcnt(4)
	v_add_f32_e32 v167, v167, v179
	s_waitcnt vmcnt(3)
	v_add_f32_e32 v167, v167, v168
	s_waitcnt vmcnt(2)
	v_add_f32_e32 v167, v167, v169
	s_waitcnt vmcnt(1)
	v_add_f32_e32 v167, v167, v170
	s_waitcnt vmcnt(0)
	v_add_f32_e32 v167, v167, v171
	v_xor_b32_e32 v168, 16, v151
	v_xor_b32_e32 v169, 32, v151
	v_lshlrev_b32_e32 v168, 2, v168
	v_lshlrev_b32_e32 v169, 2, v169
	ds_bpermute_b32 v170, v168, v160
	ds_bpermute_b32 v171, v168, v161
	ds_bpermute_b32 v172, v168, v162
	ds_bpermute_b32 v173, v168, v163
	ds_bpermute_b32 v174, v168, v164
	ds_bpermute_b32 v175, v168, v165
	ds_bpermute_b32 v176, v168, v166
	ds_bpermute_b32 v177, v168, v167
	s_waitcnt lgkmcnt(7)
	v_add_f32_e32 v160, v160, v170
	s_waitcnt lgkmcnt(6)
	v_add_f32_e32 v161, v161, v171
	s_waitcnt lgkmcnt(5)
	v_add_f32_e32 v162, v162, v172
	s_waitcnt lgkmcnt(4)
	v_add_f32_e32 v163, v163, v173
	s_waitcnt lgkmcnt(3)
	v_add_f32_e32 v164, v164, v174
	s_waitcnt lgkmcnt(2)
	v_add_f32_e32 v165, v165, v175
	s_waitcnt lgkmcnt(1)
	v_add_f32_e32 v166, v166, v176
	s_waitcnt lgkmcnt(0)
	v_add_f32_e32 v167, v167, v177
	s_nop 0
	ds_bpermute_b32 v170, v169, v160
	ds_bpermute_b32 v171, v169, v161
	ds_bpermute_b32 v172, v169, v162
	ds_bpermute_b32 v173, v169, v163
	ds_bpermute_b32 v174, v169, v164
	ds_bpermute_b32 v175, v169, v165
	ds_bpermute_b32 v176, v169, v166
	ds_bpermute_b32 v177, v169, v167
	s_waitcnt lgkmcnt(7)
	v_add_f32_e32 v160, v160, v170
	s_waitcnt lgkmcnt(6)
	v_add_f32_e32 v161, v161, v171
	s_waitcnt lgkmcnt(5)
	v_add_f32_e32 v162, v162, v172
	s_waitcnt lgkmcnt(4)
	v_add_f32_e32 v163, v163, v173
	s_waitcnt lgkmcnt(3)
	v_add_f32_e32 v164, v164, v174
	s_waitcnt lgkmcnt(2)
	v_add_f32_e32 v165, v165, v175
	s_waitcnt lgkmcnt(1)
	v_add_f32_e32 v166, v166, v176
	s_waitcnt lgkmcnt(0)
	v_add_f32_e32 v167, v167, v177
	v_fmamk_f32 v160, v160, 0x3a000000, v190
	v_fmamk_f32 v161, v161, 0x3a000000, v190
	v_fmamk_f32 v162, v162, 0x3a000000, v190
	v_fmamk_f32 v163, v163, 0x3a000000, v190
	v_fmamk_f32 v164, v164, 0x3a000000, v190
	v_fmamk_f32 v165, v165, 0x3a000000, v190
	v_fmamk_f32 v166, v166, 0x3a000000, v190
	v_fmamk_f32 v167, v167, 0x3a000000, v190
	v_rsq_f32_e32 v160, v160
	v_rsq_f32_e32 v161, v161
	v_rsq_f32_e32 v162, v162
	v_rsq_f32_e32 v163, v163
	v_rsq_f32_e32 v164, v164
	v_rsq_f32_e32 v165, v165
	v_rsq_f32_e32 v166, v166
	v_rsq_f32_e32 v167, v167
	s_nop 0
	v_mov_b32_e32 v158, v160
	v_pk_mul_f32 v[120:121], v[120:121], v[158:159] op_sel_hi:[1,0]
	v_pk_mul_f32 v[122:123], v[122:123], v[158:159] op_sel_hi:[1,0]
	v_pk_mul_f32 v[124:125], v[124:125], v[158:159] op_sel_hi:[1,0]
	v_pk_mul_f32 v[126:127], v[126:127], v[158:159] op_sel_hi:[1,0]
	v_cvt_pk_bf16_f32 v124, v124, v125
	v_cvt_pk_bf16_f32 v125, v126, v127
	v_cvt_pk_bf16_f32 v126, v120, v121
	v_cvt_pk_bf16_f32 v127, v122, v123
	global_store_dwordx4 v150, v[124:127], s[8:9]
	v_pk_mul_f32 v[112:113], v[112:113], v[158:159] op_sel_hi:[1,0]
	v_pk_mul_f32 v[114:115], v[114:115], v[158:159] op_sel_hi:[1,0]
	v_pk_mul_f32 v[116:117], v[116:117], v[158:159] op_sel_hi:[1,0]
	v_pk_mul_f32 v[118:119], v[118:119], v[158:159] op_sel_hi:[1,0]
	v_cvt_pk_bf16_f32 v116, v116, v117
	v_cvt_pk_bf16_f32 v117, v118, v119
	v_cvt_pk_bf16_f32 v118, v112, v113
	v_cvt_pk_bf16_f32 v119, v114, v115
	global_store_dwordx4 v150, v[116:119], s[8:9] offset:256
	s_add_u32 s8, s8, 0x10000
	s_addc_u32 s9, s9, 0
	v_mov_b32_e32 v158, v161
	v_pk_mul_f32 v[104:105], v[104:105], v[158:159] op_sel_hi:[1,0]
	v_pk_mul_f32 v[106:107], v[106:107], v[158:159] op_sel_hi:[1,0]
	v_pk_mul_f32 v[108:109], v[108:109], v[158:159] op_sel_hi:[1,0]
	v_pk_mul_f32 v[110:111], v[110:111], v[158:159] op_sel_hi:[1,0]
	v_cvt_pk_bf16_f32 v108, v108, v109
	v_cvt_pk_bf16_f32 v109, v110, v111
	v_cvt_pk_bf16_f32 v110, v104, v105
	v_cvt_pk_bf16_f32 v111, v106, v107
	global_store_dwordx4 v150, v[108:111], s[8:9]
	v_pk_mul_f32 v[96:97], v[96:97], v[158:159] op_sel_hi:[1,0]
	v_pk_mul_f32 v[98:99], v[98:99], v[158:159] op_sel_hi:[1,0]
	v_pk_mul_f32 v[100:101], v[100:101], v[158:159] op_sel_hi:[1,0]
	v_pk_mul_f32 v[102:103], v[102:103], v[158:159] op_sel_hi:[1,0]
	v_cvt_pk_bf16_f32 v100, v100, v101
	v_cvt_pk_bf16_f32 v101, v102, v103
	v_cvt_pk_bf16_f32 v102, v96, v97
	v_cvt_pk_bf16_f32 v103, v98, v99
	global_store_dwordx4 v150, v[100:103], s[8:9] offset:256
; #define PG8_BAR __builtin_amdgcn_s_barrier()
; DI unsigned pk2(float lo, float hi) { const f32x2 v = {lo, hi}; return __builtin_bit_cast(unsigned, __builtin_convertvector(v, bf16v2)); }
; template <class Epi, class Sched, bool ALIGN_EPI = false, bool SP2 = false>
; __device__ __forceinline__ void gemm_phase(PG8_LAS unsigned char* lds, const Gemm g, const Sched& S, const Epi& E) {
;     ...
;         if constexpr (ALIGN_EPI) { if (wr == 0) PG8_BAR; }
;         if constexpr (!Epi::AFTER_DRAIN) { E(acc, cur, wr, wc, fr, fq); S.done(cur); }
;         if (!has_next) break;
; #pragma unroll
;         for (int a = 0; a < 2; ++a)
; #pragma unroll
;             for (int b = 0; b < 2; ++b)
; #pragma unroll
;                 for (int m = 0; m < 4; ++m)
; #pragma unroll
;                     for (int n = 0; n < 2; ++n) acc[a][b][m][n] = (f32x4){0.f, 0.f, 0.f, 0.f};
;         cur = nxt; cA = nA; cB = nB; ++ui;
;         if constexpr (ALIGN_EPI) { if (wr == 1) PG8_BAR; }
;     }
;     DI void operator()(const pg8::f32x4 (&acc)[2][2][4][2], const pg8::Unit& u, int wr, int wc, int fr, int fq) const {
;         const int row0 = u.pm * pg8::BM + wr * 64 + fr, col0 = u.pn * pg8::BM + wc * 32 + 8 * fq;
; #pragma unroll
;         for (int ai = 0; ai < 2; ++ai)
; #pragma unroll
;             for (int m = 0; m < 4; ++m) {
;                 const int row = row0 + ai * pg8::HALF + m * 16;
;                 float sc = 1.f;
;                 if (rss) { const pg8::f32x4* rp = (const pg8::f32x4*)(rss + (size_t)row * 32); pg8::f32x4 t = rp[0];
; #pragma unroll
;                     for (int j = 1; j < 8; ++j) t += rp[j];
;                     sc = rsqrtf(((t[0] + t[1]) + (t[2] + t[3])) * (1.f / D) + 1e-6f); }
;                 bf16_t* rowp = O + (size_t)row * ldc + col0;
; #pragma unroll
;                 for (int bj = 0; bj < 2; ++bj) { const pg8::f32x4 v0 = acc[ai][bj][m][0] * sc, v1 = acc[ai][bj][m][1] * sc;
;                     u32x4 w; w.x = pk2(v0[0], v0[1]); w.y = pk2(v0[2], v0[3]); w.z = pk2(v1[0], v1[1]); w.w = pk2(v1[2], v1[3]);
;                     *(u32x4*)(rowp + bj * pg8::HALF) = w; }
;             }
	s_add_u32 s8, s8, 0x10000
	s_addc_u32 s9, s9, 0
	v_mov_b32_e32 v158, v162
	v_pk_mul_f32 v[88:89], v[88:89], v[158:159] op_sel_hi:[1,0]
	v_pk_mul_f32 v[90:91], v[90:91], v[158:159] op_sel_hi:[1,0]
	v_pk_mul_f32 v[92:93], v[92:93], v[158:159] op_sel_hi:[1,0]
	v_pk_mul_f32 v[94:95], v[94:95], v[158:159] op_sel_hi:[1,0]
	v_cvt_pk_bf16_f32 v92, v92, v93
	v_cvt_pk_bf16_f32 v93, v94, v95
	v_cvt_pk_bf16_f32 v94, v88, v89
	v_cvt_pk_bf16_f32 v95, v90, v91
	global_store_dwordx4 v150, v[92:95], s[8:9]
	v_pk_mul_f32 v[80:81], v[80:81], v[158:159] op_sel_hi:[1,0]
	v_pk_mul_f32 v[82:83], v[82:83], v[158:159] op_sel_hi:[1,0]
	v_pk_mul_f32 v[84:85], v[84:85], v[158:159] op_sel_hi:[1,0]
	v_pk_mul_f32 v[86:87], v[86:87], v[158:159] op_sel_hi:[1,0]
	v_cvt_pk_bf16_f32 v84, v84, v85
	v_cvt_pk_bf16_f32 v85, v86, v87
	v_cvt_pk_bf16_f32 v86, v80, v81
	v_cvt_pk_bf16_f32 v87, v82, v83
	global_store_dwordx4 v150, v[84:87], s[8:9] offset:256
	s_add_u32 s8, s8, 0x10000
	s_addc_u32 s9, s9, 0
	v_mov_b32_e32 v158, v163
	v_pk_mul_f32 v[72:73], v[72:73], v[158:159] op_sel_hi:[1,0]
	v_pk_mul_f32 v[74:75], v[74:75], v[158:159] op_sel_hi:[1,0]
	v_pk_mul_f32 v[76:77], v[76:77], v[158:159] op_sel_hi:[1,0]
	v_pk_mul_f32 v[78:79], v[78:79], v[158:159] op_sel_hi:[1,0]
	v_cvt_pk_bf16_f32 v76, v76, v77
	v_cvt_pk_bf16_f32 v77, v78, v79
	v_cvt_pk_bf16_f32 v78, v72, v73
	v_cvt_pk_bf16_f32 v79, v74, v75
	global_store_dwordx4 v150, v[76:79], s[8:9]
	v_pk_mul_f32 v[64:65], v[64:65], v[158:159] op_sel_hi:[1,0]
	v_pk_mul_f32 v[66:67], v[66:67], v[158:159] op_sel_hi:[1,0]
	v_pk_mul_f32 v[68:69], v[68:69], v[158:159] op_sel_hi:[1,0]
	v_pk_mul_f32 v[70:71], v[70:71], v[158:159] op_sel_hi:[1,0]
	v_cvt_pk_bf16_f32 v68, v68, v69
	v_cvt_pk_bf16_f32 v69, v70, v71
	v_cvt_pk_bf16_f32 v70, v64, v65
	v_cvt_pk_bf16_f32 v71, v66, v67
	global_store_dwordx4 v150, v[68:71], s[8:9] offset:256
	s_add_u32 s8, s8, 0x50000
	s_addc_u32 s9, s9, 0
	v_mov_b32_e32 v158, v164
	v_pk_mul_f32 v[56:57], v[56:57], v[158:159] op_sel_hi:[1,0]
	v_pk_mul_f32 v[58:59], v[58:59], v[158:159] op_sel_hi:[1,0]
	v_pk_mul_f32 v[60:61], v[60:61], v[158:159] op_sel_hi:[1,0]
	v_pk_mul_f32 v[62:63], v[62:63], v[158:159] op_sel_hi:[1,0]
	v_cvt_pk_bf16_f32 v60, v60, v61
	v_cvt_pk_bf16_f32 v61, v62, v63
	v_cvt_pk_bf16_f32 v62, v56, v57
	v_cvt_pk_bf16_f32 v63, v58, v59
	global_store_dwordx4 v150, v[60:63], s[8:9]
	v_pk_mul_f32 v[48:49], v[48:49], v[158:159] op_sel_hi:[1,0]
	v_pk_mul_f32 v[50:51], v[50:51], v[158:159] op_sel_hi:[1,0]
	v_pk_mul_f32 v[52:53], v[52:53], v[158:159] op_sel_hi:[1,0]
	v_pk_mul_f32 v[54:55], v[54:55], v[158:159] op_sel_hi:[1,0]
	v_cvt_pk_bf16_f32 v52, v52, v53
	v_cvt_pk_bf16_f32 v53, v54, v55
	v_cvt_pk_bf16_f32 v54, v48, v49
	v_cvt_pk_bf16_f32 v55, v50, v51
	global_store_dwordx4 v150, v[52:55], s[8:9] offset:256
	s_add_u32 s8, s8, 0x10000
	s_addc_u32 s9, s9, 0
	v_mov_b32_e32 v158, v165
	v_pk_mul_f32 v[40:41], v[40:41], v[158:159] op_sel_hi:[1,0]
	v_pk_mul_f32 v[42:43], v[42:43], v[158:159] op_sel_hi:[1,0]
	v_pk_mul_f32 v[44:45], v[44:45], v[158:159] op_sel_hi:[1,0]
	v_pk_mul_f32 v[46:47], v[46:47], v[158:159] op_sel_hi:[1,0]
	v_cvt_pk_bf16_f32 v44, v44, v45
	v_cvt_pk_bf16_f32 v45, v46, v47
	v_cvt_pk_bf16_f32 v46, v40, v41
	v_cvt_pk_bf16_f32 v47, v42, v43
	global_store_dwordx4 v150, v[44:47], s[8:9]
	v_pk_mul_f32 v[32:33], v[32:33], v[158:159] op_sel_hi:[1,0]
	v_pk_mul_f32 v[34:35], v[34:35], v[158:159] op_sel_hi:[1,0]
	v_pk_mul_f32 v[36:37], v[36:37], v[158:159] op_sel_hi:[1,0]
	v_pk_mul_f32 v[38:39], v[38:39], v[158:159] op_sel_hi:[1,0]
	v_cvt_pk_bf16_f32 v36, v36, v37
	v_cvt_pk_bf16_f32 v37, v38, v39
	v_cvt_pk_bf16_f32 v38, v32, v33
	v_cvt_pk_bf16_f32 v39, v34, v35
	global_store_dwordx4 v150, v[36:39], s[8:9] offset:256
	s_add_u32 s8, s8, 0x10000
	s_addc_u32 s9, s9, 0
	v_mov_b32_e32 v158, v166
	v_pk_mul_f32 v[24:25], v[24:25], v[158:159] op_sel_hi:[1,0]
	v_pk_mul_f32 v[26:27], v[26:27], v[158:159] op_sel_hi:[1,0]
	v_pk_mul_f32 v[28:29], v[28:29], v[158:159] op_sel_hi:[1,0]
	v_pk_mul_f32 v[30:31], v[30:31], v[158:159] op_sel_hi:[1,0]
	v_cvt_pk_bf16_f32 v28, v28, v29
	v_cvt_pk_bf16_f32 v29, v30, v31
	v_cvt_pk_bf16_f32 v30, v24, v25
	v_cvt_pk_bf16_f32 v31, v26, v27
	global_store_dwordx4 v150, v[28:31], s[8:9]
	v_pk_mul_f32 v[16:17], v[16:17], v[158:159] op_sel_hi:[1,0]
	v_pk_mul_f32 v[18:19], v[18:19], v[158:159] op_sel_hi:[1,0]
	v_pk_mul_f32 v[20:21], v[20:21], v[158:159] op_sel_hi:[1,0]
	v_pk_mul_f32 v[22:23], v[22:23], v[158:159] op_sel_hi:[1,0]
	v_cvt_pk_bf16_f32 v20, v20, v21
	v_cvt_pk_bf16_f32 v21, v22, v23
	v_cvt_pk_bf16_f32 v22, v16, v17
	v_cvt_pk_bf16_f32 v23, v18, v19
	global_store_dwordx4 v150, v[20:23], s[8:9] offset:256
	s_add_u32 s8, s8, 0x10000
	s_addc_u32 s9, s9, 0
	v_mov_b32_e32 v158, v167
	v_pk_mul_f32 v[8:9], v[8:9], v[158:159] op_sel_hi:[1,0]
	v_pk_mul_f32 v[10:11], v[10:11], v[158:159] op_sel_hi:[1,0]
	v_pk_mul_f32 v[12:13], v[12:13], v[158:159] op_sel_hi:[1,0]
	v_pk_mul_f32 v[14:15], v[14:15], v[158:159] op_sel_hi:[1,0]
	v_cvt_pk_bf16_f32 v12, v12, v13
	v_cvt_pk_bf16_f32 v13, v14, v15
	v_cvt_pk_bf16_f32 v14, v8, v9
	v_cvt_pk_bf16_f32 v15, v10, v11
	global_store_dwordx4 v150, v[12:15], s[8:9]
	v_pk_mul_f32 v[0:1], v[0:1], v[158:159] op_sel_hi:[1,0]
	v_pk_mul_f32 v[2:3], v[2:3], v[158:159] op_sel_hi:[1,0]
	v_pk_mul_f32 v[4:5], v[4:5], v[158:159] op_sel_hi:[1,0]
	v_pk_mul_f32 v[6:7], v[6:7], v[158:159] op_sel_hi:[1,0]
	v_cvt_pk_bf16_f32 v4, v4, v5
	v_cvt_pk_bf16_f32 v5, v6, v7
	v_cvt_pk_bf16_f32 v6, v0, v1
	v_cvt_pk_bf16_f32 v7, v2, v3
	global_store_dwordx4 v150, v[4:7], s[8:9] offset:256
	s_mov_b64 s[8:9], -1
	s_andn2_b64 vcc, exec, s[38:39]
	s_cbranch_vccnz .LBB0_59
	v_readlane_b32 s8, v255, 21
	v_readlane_b32 s9, v255, 22
	s_andn2_b64 vcc, exec, s[8:9]
	s_cbranch_vccnz .LBB0_58
	s_barrier
	s_branch .LBB0_58
